# GEMM k-loop first trip peeled with C=0 MFMAs, per-tile accumulator zeroing removed (8 GEMM sites)
# baseline (speedup 1.0000x reference)
; #define PG8_STAGE(bufoff, gbase, voff) do { _Pragma("unroll") for (int _i = 0; _i < 2; ++_i) \
;         __builtin_amdgcn_global_load_lds((const unsigned*)((const char*)(gbase) + (voff)[_i]), (LAS unsigned*)(lds + (bufoff) + ldsw + _i * 8192), 16, 0, 0); } while (0)
; #define PG8_LDA(dst, b, h) do { _Pragma("unroll") for (int m = 0; m < 4; ++m) _Pragma("unroll") for (int k = 0; k < 2; ++k) dst[m][k] = *(const LAS bf16x8*)(lds + PG8_SA(b, h) + aoff + m * 2048 + k * 1024); } while (0)
; #define PG8_LDB(dst, b, h) do { _Pragma("unroll") for (int n = 0; n < 2; ++n) _Pragma("unroll") for (int k = 0; k < 2; ++k) dst[n][k] = *(const LAS bf16x8*)(lds + PG8_SB(b, h) + boff + n * 2048 + k * 1024); } while (0)
; #define PG8_MMA(ai, bj, At, Bt) do { __builtin_amdgcn_s_setprio(1); _Pragma("unroll") for (int m = 0; m < 4; ++m) _Pragma("unroll") for (int n = 0; n < 2; ++n) _Pragma("unroll") for (int k = 0; k < 2; ++k) \
;         acc[ai][bj][m][n] = __builtin_amdgcn_mfma_f32_16x16x32_bf16(Bt[n][k], At[m][k], acc[ai][bj][m][n], 0, 0, 0); __builtin_amdgcn_s_setprio(0); } while (0)
; #define PG8_WAIT_V(n) asm volatile("s_waitcnt vmcnt(" #n ")" ::: "memory")
; #define PG8_WAIT_L(n) asm volatile("s_waitcnt lgkmcnt(" #n ")" ::: "memory")
; #define PG8_BAR __builtin_amdgcn_s_barrier()
; #define PG8_SCHED __builtin_amdgcn_sched_barrier(0)
; template <class EpiT>
; __device__ __forceinline__ void gemm_phase(LAS unsigned char* lds, const Gemm g, const StaticOrder& S, const EpiT& E) {
;     ...
;         for (int t = 0; t < nt; t += 2) {
;             const bool last = (t == nt - 2);
;             const char* a1 = cA + (size_t)(t + 1) * kstep;
;             const char* a2 = last ? nA : cA + (size_t)(t + 2) * kstep; const char* b2 = last ? nB : cB + (size_t)(t + 2) * kstep;
;             const char* a3 = a2 + kstep; const char* b3 = b2 + kstep;
;             PG8_LDB(B0, 0, 0); PG8_LDB(B1, 0, 1); PG8_SCHED; PG8_LDA(At, 0, 0); PG8_STAGE(PG8_SA(1, 1), a1 + hstepA, voffA);
;             PG8_WAIT_V(8); PG8_WAIT_L(0); PG8_BAR; PG8_MMA(0, 0, At, B0); PG8_MMA(0, 1, At, B1); PG8_BAR; PG8_SCHED;
;             PG8_LDA(At, 0, 1); PG8_STAGE(PG8_SB(0, 0), b2, voffB); PG8_STAGE(PG8_SB(0, 1), b2 + hstepB, voffB); PG8_STAGE(PG8_SA(0, 0), a2, voffA);
;             PG8_WAIT_V(8); PG8_WAIT_L(0); PG8_BAR; PG8_MMA(1, 0, At, B0); PG8_MMA(1, 1, At, B1); PG8_BAR; PG8_SCHED;
.LBB0_99:
	s_add_u32 s16, s16, 0x84080
	s_addc_u32 s17, s17, 0
	s_add_u32 s51, s18, 0x100
	s_addc_u32 s52, s19, 0
	s_mov_b32 s53, -2
	ds_read_b128 v[128:131], v160
	ds_read_b128 v[170:173], v160 offset:1024
	ds_read_b128 v[174:177], v160 offset:2048
	ds_read_b128 v[178:181], v160 offset:3072
	ds_read_b128 v[182:185], v161
	ds_read_b128 v[186:189], v161 offset:1024
	ds_read_b128 v[190:193], v161 offset:2048
	ds_read_b128 v[194:197], v161 offset:3072
	s_add_u32 s18, s16, 0xfff7c080
	s_addc_u32 s19, s17, -1
	s_cmp_eq_u32 s53, 28
	s_cselect_b32 s21, s3, s19
	s_cselect_b32 s20, s2, s18
	s_cselect_b32 s19, s15, s52
	s_cselect_b32 s18, s14, s51
	v_lshl_add_u64 v[158:159], s[16:17], 0, v[150:151]
	s_add_i32 m0, s35, 0xc000
	ds_read_b128 v[198:201], v162
	ds_read_b128 v[202:205], v162 offset:1024
	ds_read_b128 v[206:209], v162 offset:2048
	ds_read_b128 v[210:213], v162 offset:3072
	ds_read_b128 v[214:217], v162 offset:4096
	ds_read_b128 v[218:221], v162 offset:5120
	ds_read_b128 v[222:225], v162 offset:6144
	ds_read_b128 v[226:229], v162 offset:7168
	global_load_lds_dwordx4 v[158:159], off
	v_lshl_add_u64 v[158:159], s[16:17], 0, v[152:153]
	s_add_i32 m0, s35, 0xe000
	s_nop 0
	global_load_lds_dwordx4 v[158:159], off
	s_waitcnt vmcnt(8)
	s_waitcnt lgkmcnt(0)
	s_barrier
	s_setprio 1
	s_waitcnt lgkmcnt(0)
	v_mfma_f32_16x16x32_bf16 v[124:127], v[128:131], v[198:201], 0
	v_mfma_f32_16x16x32_bf16 v[120:123], v[174:177], v[198:201], 0
	v_mfma_f32_16x16x32_bf16 v[108:111], v[128:131], v[206:209], 0
	v_mfma_f32_16x16x32_bf16 v[104:107], v[174:177], v[206:209], 0
	v_mfma_f32_16x16x32_bf16 v[92:95], v[128:131], v[214:217], 0
	v_mfma_f32_16x16x32_bf16 v[88:91], v[174:177], v[214:217], 0
	v_mfma_f32_16x16x32_bf16 v[76:79], v[128:131], v[222:225], 0
	v_mfma_f32_16x16x32_bf16 v[72:75], v[174:177], v[222:225], 0
	v_mfma_f32_16x16x32_bf16 v[124:127], v[170:173], v[202:205], v[124:127]
	v_mfma_f32_16x16x32_bf16 v[120:123], v[178:181], v[202:205], v[120:123]
	v_mfma_f32_16x16x32_bf16 v[108:111], v[170:173], v[210:213], v[108:111]
	v_mfma_f32_16x16x32_bf16 v[104:107], v[178:181], v[210:213], v[104:107]
	v_mfma_f32_16x16x32_bf16 v[92:95], v[170:173], v[218:221], v[92:95]
	v_mfma_f32_16x16x32_bf16 v[88:91], v[178:181], v[218:221], v[88:91]
	v_mfma_f32_16x16x32_bf16 v[76:79], v[170:173], v[226:229], v[76:79]
	v_mfma_f32_16x16x32_bf16 v[72:75], v[178:181], v[226:229], v[72:75]
	s_setprio 0
	s_setprio 1
	v_mfma_f32_16x16x32_bf16 v[116:119], v[182:185], v[198:201], 0
	v_mfma_f32_16x16x32_bf16 v[112:115], v[190:193], v[198:201], 0
	v_mfma_f32_16x16x32_bf16 v[100:103], v[182:185], v[206:209], 0
	v_mfma_f32_16x16x32_bf16 v[96:99], v[190:193], v[206:209], 0
	v_mfma_f32_16x16x32_bf16 v[84:87], v[182:185], v[214:217], 0
	v_mfma_f32_16x16x32_bf16 v[80:83], v[190:193], v[214:217], 0
	v_mfma_f32_16x16x32_bf16 v[68:71], v[182:185], v[222:225], 0
	v_mfma_f32_16x16x32_bf16 v[64:67], v[190:193], v[222:225], 0
	v_mfma_f32_16x16x32_bf16 v[116:119], v[186:189], v[202:205], v[116:119]
	v_mfma_f32_16x16x32_bf16 v[112:115], v[194:197], v[202:205], v[112:115]
	v_mfma_f32_16x16x32_bf16 v[100:103], v[186:189], v[210:213], v[100:103]
	v_mfma_f32_16x16x32_bf16 v[96:99], v[194:197], v[210:213], v[96:99]
	v_mfma_f32_16x16x32_bf16 v[84:87], v[186:189], v[218:221], v[84:87]
	v_mfma_f32_16x16x32_bf16 v[80:83], v[194:197], v[218:221], v[80:83]
	v_mfma_f32_16x16x32_bf16 v[68:71], v[186:189], v[226:229], v[68:71]
	v_mfma_f32_16x16x32_bf16 v[64:67], v[194:197], v[226:229], v[64:67]
	s_setprio 0
	s_barrier
	s_add_i32 s54, s43, s25
	v_lshl_add_u64 v[158:159], s[18:19], 0, v[136:137]
	s_mov_b32 m0, s54
	ds_read_b128 v[198:201], v162 offset:16384
	ds_read_b128 v[202:205], v162 offset:17408
	ds_read_b128 v[206:209], v162 offset:18432
	ds_read_b128 v[210:213], v162 offset:19456
	ds_read_b128 v[214:217], v162 offset:20480
	ds_read_b128 v[218:221], v162 offset:21504
	ds_read_b128 v[222:225], v162 offset:22528
	ds_read_b128 v[226:229], v162 offset:23552
	global_load_lds_dwordx4 v[158:159], off
	s_add_i32 m0, s54, 0x2000
	s_add_u32 s54, s18, 0x84000
	v_lshl_add_u64 v[166:167], s[18:19], 0, v[132:133]
	s_addc_u32 s55, s19, 0
	s_add_i32 s56, s44, s25
	global_load_lds_dwordx4 v[166:167], off
	v_lshl_add_u64 v[230:231], s[54:55], 0, v[136:137]
	s_mov_b32 m0, s56
	v_lshl_add_u64 v[232:233], s[20:21], 0, v[134:135]
	global_load_lds_dwordx4 v[230:231], off
	v_lshl_add_u64 v[230:231], s[54:55], 0, v[132:133]
	s_add_i32 m0, s56, 0x2000
	s_nop 0
	global_load_lds_dwordx4 v[230:231], off
	v_lshl_add_u64 v[230:231], s[20:21], 0, v[138:139]
	s_mov_b32 m0, s35
	s_nop 0
	global_load_lds_dwordx4 v[230:231], off
	s_mov_b32 m0, s36
	s_nop 0
	global_load_lds_dwordx4 v[232:233], off
	s_waitcnt vmcnt(8)
	s_waitcnt lgkmcnt(0)
	s_barrier
; #define PG8_STAGE(bufoff, gbase, voff) do { _Pragma("unroll") for (int _i = 0; _i < 2; ++_i) \
;         __builtin_amdgcn_global_load_lds((const unsigned*)((const char*)(gbase) + (voff)[_i]), (LAS unsigned*)(lds + (bufoff) + ldsw + _i * 8192), 16, 0, 0); } while (0)
; #define PG8_LDA(dst, b, h) do { _Pragma("unroll") for (int m = 0; m < 4; ++m) _Pragma("unroll") for (int k = 0; k < 2; ++k) dst[m][k] = *(const LAS bf16x8*)(lds + PG8_SA(b, h) + aoff + m * 2048 + k * 1024); } while (0)
; #define PG8_LDB(dst, b, h) do { _Pragma("unroll") for (int n = 0; n < 2; ++n) _Pragma("unroll") for (int k = 0; k < 2; ++k) dst[n][k] = *(const LAS bf16x8*)(lds + PG8_SB(b, h) + boff + n * 2048 + k * 1024); } while (0)
; #define PG8_MMA(ai, bj, At, Bt) do { __builtin_amdgcn_s_setprio(1); _Pragma("unroll") for (int m = 0; m < 4; ++m) _Pragma("unroll") for (int n = 0; n < 2; ++n) _Pragma("unroll") for (int k = 0; k < 2; ++k) \
;         acc[ai][bj][m][n] = __builtin_amdgcn_mfma_f32_16x16x32_bf16(Bt[n][k], At[m][k], acc[ai][bj][m][n], 0, 0, 0); __builtin_amdgcn_s_setprio(0); } while (0)
; #define PG8_WAIT_V(n) asm volatile("s_waitcnt vmcnt(" #n ")" ::: "memory")
; #define PG8_WAIT_L(n) asm volatile("s_waitcnt lgkmcnt(" #n ")" ::: "memory")
; #define PG8_BAR __builtin_amdgcn_s_barrier()
; #define PG8_SCHED __builtin_amdgcn_sched_barrier(0)
; template <class EpiT>
; __device__ __forceinline__ void gemm_phase(LAS unsigned char* lds, const Gemm g, const StaticOrder& S, const EpiT& E) {
;     ...
;             PG8_WAIT_V(8); PG8_WAIT_L(0); PG8_BAR; PG8_MMA(1, 0, At, B0); PG8_MMA(1, 1, At, B1); PG8_BAR; PG8_SCHED;
;             PG8_LDB(B0, 1, 0); PG8_LDB(B1, 1, 1); PG8_SCHED; PG8_LDA(At, 1, 0); PG8_STAGE(PG8_SA(0, 1), a2 + hstepA, voffA);
;             PG8_WAIT_V(8); PG8_WAIT_L(0); PG8_BAR; PG8_MMA(0, 0, At, B0); PG8_MMA(0, 1, At, B1); PG8_BAR; PG8_SCHED;
	s_setprio 1
	s_waitcnt lgkmcnt(0)
	v_mfma_f32_16x16x32_bf16 v[60:63], v[128:131], v[198:201], 0
	v_mfma_f32_16x16x32_bf16 v[56:59], v[174:177], v[198:201], 0
	v_mfma_f32_16x16x32_bf16 v[44:47], v[128:131], v[206:209], 0
	v_mfma_f32_16x16x32_bf16 v[40:43], v[174:177], v[206:209], 0
	v_mfma_f32_16x16x32_bf16 v[28:31], v[128:131], v[214:217], 0
	v_mfma_f32_16x16x32_bf16 v[24:27], v[174:177], v[214:217], 0
	v_mfma_f32_16x16x32_bf16 v[12:15], v[128:131], v[222:225], 0
	v_mfma_f32_16x16x32_bf16 v[8:11], v[174:177], v[222:225], 0
	v_mfma_f32_16x16x32_bf16 v[60:63], v[170:173], v[202:205], v[60:63]
	v_mfma_f32_16x16x32_bf16 v[56:59], v[178:181], v[202:205], v[56:59]
	v_mfma_f32_16x16x32_bf16 v[44:47], v[170:173], v[210:213], v[44:47]
	v_mfma_f32_16x16x32_bf16 v[40:43], v[178:181], v[210:213], v[40:43]
	v_mfma_f32_16x16x32_bf16 v[28:31], v[170:173], v[218:221], v[28:31]
	v_mfma_f32_16x16x32_bf16 v[24:27], v[178:181], v[218:221], v[24:27]
	v_mfma_f32_16x16x32_bf16 v[12:15], v[170:173], v[226:229], v[12:15]
	v_mfma_f32_16x16x32_bf16 v[8:11], v[178:181], v[226:229], v[8:11]
	s_setprio 0
	s_setprio 1
	v_mfma_f32_16x16x32_bf16 v[52:55], v[182:185], v[198:201], 0
	v_mfma_f32_16x16x32_bf16 v[48:51], v[190:193], v[198:201], 0
	v_mfma_f32_16x16x32_bf16 v[36:39], v[182:185], v[206:209], 0
	v_mfma_f32_16x16x32_bf16 v[32:35], v[190:193], v[206:209], 0
	v_mfma_f32_16x16x32_bf16 v[20:23], v[182:185], v[214:217], 0
	v_mfma_f32_16x16x32_bf16 v[16:19], v[190:193], v[214:217], 0
	v_mfma_f32_16x16x32_bf16 v[4:7], v[182:185], v[222:225], 0
	v_mfma_f32_16x16x32_bf16 v[0:3], v[190:193], v[222:225], 0
	v_mfma_f32_16x16x32_bf16 v[52:55], v[186:189], v[202:205], v[52:55]
	v_mfma_f32_16x16x32_bf16 v[48:51], v[194:197], v[202:205], v[48:51]
	v_mfma_f32_16x16x32_bf16 v[36:39], v[186:189], v[210:213], v[36:39]
	v_mfma_f32_16x16x32_bf16 v[32:35], v[194:197], v[210:213], v[32:35]
	v_mfma_f32_16x16x32_bf16 v[20:23], v[186:189], v[218:221], v[20:23]
	v_mfma_f32_16x16x32_bf16 v[16:19], v[194:197], v[218:221], v[16:19]
	v_mfma_f32_16x16x32_bf16 v[4:7], v[186:189], v[226:229], v[4:7]
	v_mfma_f32_16x16x32_bf16 v[0:3], v[194:197], v[226:229], v[0:3]
	s_setprio 0
	s_barrier
	s_add_i32 s54, 0, 0x18000
	v_add_u32_e32 v140, s54, v145
	s_add_i32 s55, 0, 0x1c000
	ds_read_b128 v[128:131], v140
	ds_read_b128 v[170:173], v140 offset:1024
	ds_read_b128 v[174:177], v140 offset:2048
	ds_read_b128 v[178:181], v140 offset:3072
	v_add_u32_e32 v140, s55, v145
	ds_read_b128 v[182:185], v140
	ds_read_b128 v[186:189], v140 offset:1024
	ds_read_b128 v[190:193], v140 offset:2048
	ds_read_b128 v[194:197], v140 offset:3072
	s_add_u32 s20, s20, 0x84000
	s_addc_u32 s21, s21, 0
	s_mov_b32 m0, s37
	v_lshl_add_u64 v[234:235], s[20:21], 0, v[138:139]
	ds_read_b128 v[198:201], v162 offset:32768
	ds_read_b128 v[202:205], v162 offset:33792
	ds_read_b128 v[206:209], v162 offset:34816
	ds_read_b128 v[210:213], v162 offset:35840
	ds_read_b128 v[214:217], v162 offset:36864
	ds_read_b128 v[218:221], v162 offset:37888
	ds_read_b128 v[222:225], v162 offset:38912
	ds_read_b128 v[226:229], v162 offset:39936
	global_load_lds_dwordx4 v[234:235], off
	v_lshl_add_u64 v[234:235], s[20:21], 0, v[134:135]
	s_mov_b32 m0, s38
	s_nop 0
	global_load_lds_dwordx4 v[234:235], off
	s_waitcnt vmcnt(8)
	s_waitcnt lgkmcnt(0)
	s_barrier
	s_setprio 1
	s_waitcnt lgkmcnt(0)
	v_mfma_f32_16x16x32_bf16 v[124:127], v[128:131], v[198:201], v[124:127]
	v_mfma_f32_16x16x32_bf16 v[120:123], v[174:177], v[198:201], v[120:123]
	v_mfma_f32_16x16x32_bf16 v[108:111], v[128:131], v[206:209], v[108:111]
	v_mfma_f32_16x16x32_bf16 v[104:107], v[174:177], v[206:209], v[104:107]
	v_mfma_f32_16x16x32_bf16 v[92:95], v[128:131], v[214:217], v[92:95]
	v_mfma_f32_16x16x32_bf16 v[88:91], v[174:177], v[214:217], v[88:91]
	v_mfma_f32_16x16x32_bf16 v[76:79], v[128:131], v[222:225], v[76:79]
	v_mfma_f32_16x16x32_bf16 v[72:75], v[174:177], v[222:225], v[72:75]
	v_mfma_f32_16x16x32_bf16 v[124:127], v[170:173], v[202:205], v[124:127]
	v_mfma_f32_16x16x32_bf16 v[120:123], v[178:181], v[202:205], v[120:123]
	v_mfma_f32_16x16x32_bf16 v[108:111], v[170:173], v[210:213], v[108:111]
	v_mfma_f32_16x16x32_bf16 v[104:107], v[178:181], v[210:213], v[104:107]
	v_mfma_f32_16x16x32_bf16 v[92:95], v[170:173], v[218:221], v[92:95]
	v_mfma_f32_16x16x32_bf16 v[88:91], v[178:181], v[218:221], v[88:91]
	v_mfma_f32_16x16x32_bf16 v[76:79], v[170:173], v[226:229], v[76:79]
	v_mfma_f32_16x16x32_bf16 v[72:75], v[178:181], v[226:229], v[72:75]
	s_setprio 0
	s_setprio 1
	v_mfma_f32_16x16x32_bf16 v[116:119], v[182:185], v[198:201], v[116:119]
	v_mfma_f32_16x16x32_bf16 v[112:115], v[190:193], v[198:201], v[112:115]
	v_mfma_f32_16x16x32_bf16 v[100:103], v[182:185], v[206:209], v[100:103]
	v_mfma_f32_16x16x32_bf16 v[96:99], v[190:193], v[206:209], v[96:99]
	v_mfma_f32_16x16x32_bf16 v[84:87], v[182:185], v[214:217], v[84:87]
	v_mfma_f32_16x16x32_bf16 v[80:83], v[190:193], v[214:217], v[80:83]
	v_mfma_f32_16x16x32_bf16 v[68:71], v[182:185], v[222:225], v[68:71]
	v_mfma_f32_16x16x32_bf16 v[64:67], v[190:193], v[222:225], v[64:67]
	v_mfma_f32_16x16x32_bf16 v[116:119], v[186:189], v[202:205], v[116:119]
	v_mfma_f32_16x16x32_bf16 v[112:115], v[194:197], v[202:205], v[112:115]
	v_mfma_f32_16x16x32_bf16 v[100:103], v[186:189], v[210:213], v[100:103]
	v_mfma_f32_16x16x32_bf16 v[96:99], v[194:197], v[210:213], v[96:99]
	v_mfma_f32_16x16x32_bf16 v[84:87], v[186:189], v[218:221], v[84:87]
	v_mfma_f32_16x16x32_bf16 v[80:83], v[194:197], v[218:221], v[80:83]
	v_mfma_f32_16x16x32_bf16 v[68:71], v[186:189], v[226:229], v[68:71]
	v_mfma_f32_16x16x32_bf16 v[64:67], v[194:197], v[226:229], v[64:67]
	s_setprio 0
	s_barrier
; #define PG8_STAGE(bufoff, gbase, voff) do { _Pragma("unroll") for (int _i = 0; _i < 2; ++_i) \
;         __builtin_amdgcn_global_load_lds((const unsigned*)((const char*)(gbase) + (voff)[_i]), (LAS unsigned*)(lds + (bufoff) + ldsw + _i * 8192), 16, 0, 0); } while (0)
; #define PG8_LDA(dst, b, h) do { _Pragma("unroll") for (int m = 0; m < 4; ++m) _Pragma("unroll") for (int k = 0; k < 2; ++k) dst[m][k] = *(const LAS bf16x8*)(lds + PG8_SA(b, h) + aoff + m * 2048 + k * 1024); } while (0)
; #define PG8_MMA(ai, bj, At, Bt) do { __builtin_amdgcn_s_setprio(1); _Pragma("unroll") for (int m = 0; m < 4; ++m) _Pragma("unroll") for (int n = 0; n < 2; ++n) _Pragma("unroll") for (int k = 0; k < 2; ++k) \
;         acc[ai][bj][m][n] = __builtin_amdgcn_mfma_f32_16x16x32_bf16(Bt[n][k], At[m][k], acc[ai][bj][m][n], 0, 0, 0); __builtin_amdgcn_s_setprio(0); } while (0)
; #define PG8_WAIT_V(n) asm volatile("s_waitcnt vmcnt(" #n ")" ::: "memory")
; #define PG8_WAIT_L(n) asm volatile("s_waitcnt lgkmcnt(" #n ")" ::: "memory")
; #define PG8_BAR __builtin_amdgcn_s_barrier()
; #define PG8_SCHED __builtin_amdgcn_sched_barrier(0)
; template <class EpiT>
; __device__ __forceinline__ void gemm_phase(LAS unsigned char* lds, const Gemm g, const StaticOrder& S, const EpiT& E) {
;     ...
;         for (int t = 0; t < nt; t += 2) {
;             const bool last = (t == nt - 2);
;     ...
;             PG8_LDA(At, 1, 1); PG8_STAGE(PG8_SB(1, 0), b3, voffB); PG8_STAGE(PG8_SB(1, 1), b3 + hstepB, voffB); PG8_STAGE(PG8_SA(1, 0), a3, voffA);
;             PG8_WAIT_V(8); PG8_WAIT_L(0); PG8_BAR; PG8_MMA(1, 0, At, B0); PG8_MMA(1, 1, At, B1); PG8_BAR; PG8_SCHED;
	s_add_i32 s20, s54, s25
	v_lshl_add_u64 v[158:159], v[158:159], 0, s[10:11]
	s_mov_b32 m0, s20
	ds_read_b128 v[198:201], v162 offset:49152
	ds_read_b128 v[202:205], v162 offset:50176
	ds_read_b128 v[206:209], v162 offset:51200
	ds_read_b128 v[210:213], v162 offset:52224
	ds_read_b128 v[214:217], v162 offset:53248
	ds_read_b128 v[218:221], v162 offset:54272
	ds_read_b128 v[222:225], v162 offset:55296
	ds_read_b128 v[226:229], v162 offset:56320
	global_load_lds_dwordx4 v[158:159], off
	s_add_i32 m0, s20, 0x2000
	s_add_u32 s18, s18, 0x84080
	v_lshl_add_u64 v[158:159], v[166:167], 0, s[10:11]
	s_addc_u32 s19, s19, 0
	s_add_i32 s20, s55, s25
	global_load_lds_dwordx4 v[158:159], off
	v_lshl_add_u64 v[158:159], s[18:19], 0, v[136:137]
	s_mov_b32 m0, s20
	s_nop 0
	global_load_lds_dwordx4 v[158:159], off
	v_lshl_add_u64 v[158:159], s[18:19], 0, v[132:133]
	s_add_i32 m0, s20, 0x2000
	s_nop 0
	global_load_lds_dwordx4 v[158:159], off
	v_lshl_add_u64 v[158:159], v[230:231], 0, s[10:11]
	s_mov_b32 m0, s40
	s_nop 0
	global_load_lds_dwordx4 v[158:159], off
	v_lshl_add_u64 v[158:159], v[232:233], 0, s[10:11]
	s_mov_b32 m0, s41
	s_nop 0
	global_load_lds_dwordx4 v[158:159], off
	s_waitcnt vmcnt(8)
	s_waitcnt lgkmcnt(0)
	s_barrier
	s_setprio 1
	s_waitcnt lgkmcnt(0)
	v_mfma_f32_16x16x32_bf16 v[60:63], v[128:131], v[198:201], v[60:63]
	v_mfma_f32_16x16x32_bf16 v[56:59], v[174:177], v[198:201], v[56:59]
	v_mfma_f32_16x16x32_bf16 v[44:47], v[128:131], v[206:209], v[44:47]
	v_mfma_f32_16x16x32_bf16 v[40:43], v[174:177], v[206:209], v[40:43]
	v_mfma_f32_16x16x32_bf16 v[28:31], v[128:131], v[214:217], v[28:31]
	v_mfma_f32_16x16x32_bf16 v[24:27], v[174:177], v[214:217], v[24:27]
	v_mfma_f32_16x16x32_bf16 v[12:15], v[128:131], v[222:225], v[12:15]
	v_mfma_f32_16x16x32_bf16 v[8:11], v[174:177], v[222:225], v[8:11]
	v_mfma_f32_16x16x32_bf16 v[60:63], v[170:173], v[202:205], v[60:63]
	v_mfma_f32_16x16x32_bf16 v[56:59], v[178:181], v[202:205], v[56:59]
	v_mfma_f32_16x16x32_bf16 v[44:47], v[170:173], v[210:213], v[44:47]
	v_mfma_f32_16x16x32_bf16 v[40:43], v[178:181], v[210:213], v[40:43]
	v_mfma_f32_16x16x32_bf16 v[28:31], v[170:173], v[218:221], v[28:31]
	v_mfma_f32_16x16x32_bf16 v[24:27], v[178:181], v[218:221], v[24:27]
	v_mfma_f32_16x16x32_bf16 v[12:15], v[170:173], v[226:229], v[12:15]
	v_mfma_f32_16x16x32_bf16 v[8:11], v[178:181], v[226:229], v[8:11]
	s_setprio 0
	s_setprio 1
	v_mfma_f32_16x16x32_bf16 v[52:55], v[182:185], v[198:201], v[52:55]
	v_mfma_f32_16x16x32_bf16 v[48:51], v[190:193], v[198:201], v[48:51]
	v_mfma_f32_16x16x32_bf16 v[36:39], v[182:185], v[206:209], v[36:39]
	v_mfma_f32_16x16x32_bf16 v[32:35], v[190:193], v[206:209], v[32:35]
	v_mfma_f32_16x16x32_bf16 v[20:23], v[182:185], v[214:217], v[20:23]
	v_mfma_f32_16x16x32_bf16 v[16:19], v[190:193], v[214:217], v[16:19]
	v_mfma_f32_16x16x32_bf16 v[4:7], v[182:185], v[222:225], v[4:7]
	v_mfma_f32_16x16x32_bf16 v[0:3], v[190:193], v[222:225], v[0:3]
	v_mfma_f32_16x16x32_bf16 v[52:55], v[186:189], v[202:205], v[52:55]
	v_mfma_f32_16x16x32_bf16 v[48:51], v[194:197], v[202:205], v[48:51]
	v_mfma_f32_16x16x32_bf16 v[36:39], v[186:189], v[210:213], v[36:39]
	v_mfma_f32_16x16x32_bf16 v[32:35], v[194:197], v[210:213], v[32:35]
	v_mfma_f32_16x16x32_bf16 v[20:23], v[186:189], v[218:221], v[20:23]
	v_mfma_f32_16x16x32_bf16 v[16:19], v[194:197], v[218:221], v[16:19]
	v_mfma_f32_16x16x32_bf16 v[4:7], v[186:189], v[226:229], v[4:7]
	v_mfma_f32_16x16x32_bf16 v[0:3], v[194:197], v[226:229], v[0:3]
	s_setprio 0
	s_barrier
	s_add_i32 s53, s53, 2
	s_add_u32 s16, s16, 0x100
	s_addc_u32 s17, s17, 0
	s_add_u32 s51, s51, 0x100
	s_addc_u32 s52, s52, 0
	s_cmp_gt_u32 s53, 29
	s_cbranch_scc1 .Lpeel_done_100
	.p2alignl 6, 3212836864
	s_nop 0
	s_nop 0
	s_nop 0
	s_nop 0
	s_nop 0
	s_nop 0
	s_nop 0
	s_nop 0
	s_nop 0
	s_nop 0
	s_nop 0

; #define PG8_BAR __builtin_amdgcn_s_barrier()
; template <class EpiT>
; __device__ __forceinline__ void gemm_phase(LAS unsigned char* lds, const Gemm g, const StaticOrder& S, const EpiT& E) {
;     ...
;         if (wr == 0) PG8_BAR;
;         E(acc, cur, wr, wc, fr, fq);
.Lpeel_done_100:
	s_and_b64 vcc, exec, s[12:13]
	s_cbranch_vccz .LBB0_103
	s_barrier

; #define PG8_STAGE(bufoff, gbase, voff) do { _Pragma("unroll") for (int _i = 0; _i < 2; ++_i) \
;         __builtin_amdgcn_global_load_lds((const unsigned*)((const char*)(gbase) + (voff)[_i]), (LAS unsigned*)(lds + (bufoff) + ldsw + _i * 8192), 16, 0, 0); } while (0)
; #define PG8_LDA(dst, b, h) do { _Pragma("unroll") for (int m = 0; m < 4; ++m) _Pragma("unroll") for (int k = 0; k < 2; ++k) dst[m][k] = *(const LAS bf16x8*)(lds + PG8_SA(b, h) + aoff + m * 2048 + k * 1024); } while (0)
; #define PG8_LDB(dst, b, h) do { _Pragma("unroll") for (int n = 0; n < 2; ++n) _Pragma("unroll") for (int k = 0; k < 2; ++k) dst[n][k] = *(const LAS bf16x8*)(lds + PG8_SB(b, h) + boff + n * 2048 + k * 1024); } while (0)
; #define PG8_WAIT_V(n) asm volatile("s_waitcnt vmcnt(" #n ")" ::: "memory")
; #define PG8_WAIT_L(n) asm volatile("s_waitcnt lgkmcnt(" #n ")" ::: "memory")
; template <class EpiT>
; __device__ __forceinline__ void gemm_phase(LAS unsigned char* lds, const Gemm g, const StaticOrder& S, const EpiT& E) {
;     ...
;         const char* nA = has_next ? (const char*)g.A + (size_t)nxt.pm * tstepA + (size_t)nxt.pn * g.a_koff * 2 : cA; const char* nB = has_next ? (const char*)g.Bt + (size_t)nxt.pn * tstepB : cB;
;         for (int t = 0; t < nt; t += 2) {
;             const bool last = (t == nt - 2);
;             const char* a1 = cA + (size_t)(t + 1) * kstep;
;             const char* a2 = last ? nA : cA + (size_t)(t + 2) * kstep; const char* b2 = last ? nB : cB + (size_t)(t + 2) * kstep;
;             const char* a3 = a2 + kstep; const char* b3 = b2 + kstep;
;             PG8_LDB(B0, 0, 0); PG8_LDB(B1, 0, 1); PG8_SCHED; PG8_LDA(At, 0, 0); PG8_STAGE(PG8_SA(1, 1), a1 + hstepA, voffA);
;             PG8_WAIT_V(8); PG8_WAIT_L(0); PG8_BAR; PG8_MMA(0, 0, At, B0); PG8_MMA(0, 1, At, B1); PG8_BAR; PG8_SCHED;
;             PG8_LDA(At, 0, 1); PG8_STAGE(PG8_SB(0, 0), b2, voffB); PG8_STAGE(PG8_SB(0, 1), b2 + hstepB, voffB); PG8_STAGE(PG8_SA(0, 0), a2, voffA);
;             PG8_WAIT_V(8); PG8_WAIT_L(0); PG8_BAR; PG8_MMA(1, 0, At, B0); PG8_MMA(1, 1, At, B1); PG8_BAR; PG8_SCHED;
;     ...
; #pragma unroll
;         for (int a = 0; a < 2; ++a)
; #pragma unroll
;             for (int b = 0; b < 2; ++b)
; #pragma unroll
;                 for (int m = 0; m < 4; ++m)
; #pragma unroll
;                     for (int n = 0; n < 2; ++n) acc[a][b][m][n] = (f32x4){0.f, 0.f, 0.f, 0.f};
.LBB0_391:
	s_add_u32 s18, s18, 0x84080
	s_addc_u32 s19, s19, 0
	s_add_u32 s51, s20, 0x100
	s_addc_u32 s52, s21, 0
	s_mov_b32 s53, -2
	ds_read_b128 v[154:157], v149
	ds_read_b128 v[158:161], v149 offset:1024
	ds_read_b128 v[170:173], v149 offset:2048
	ds_read_b128 v[174:177], v149 offset:3072
	ds_read_b128 v[178:181], v150
	ds_read_b128 v[182:185], v150 offset:1024
	ds_read_b128 v[186:189], v150 offset:2048
	ds_read_b128 v[190:193], v150 offset:3072
	s_add_u32 s20, s18, 0xfff7c080
	s_addc_u32 s21, s19, -1
	s_cmp_eq_u32 s53, 28
	s_cselect_b32 s23, s5, s21
	s_cselect_b32 s22, s4, s20
	s_cselect_b32 s21, s17, s52
	s_cselect_b32 s20, s16, s51
	v_lshl_add_u64 v[162:163], s[18:19], 0, v[138:139]
	s_add_i32 m0, s35, 0xc000
	ds_read_b128 v[194:197], v151
	ds_read_b128 v[198:201], v151 offset:1024
	ds_read_b128 v[202:205], v151 offset:2048
	ds_read_b128 v[206:209], v151 offset:3072
	ds_read_b128 v[210:213], v151 offset:4096
	ds_read_b128 v[214:217], v151 offset:5120
	ds_read_b128 v[218:221], v151 offset:6144
	ds_read_b128 v[222:225], v151 offset:7168
	global_load_lds_dwordx4 v[162:163], off
	v_lshl_add_u64 v[162:163], s[18:19], 0, v[140:141]
	s_add_i32 m0, s35, 0xe000
	s_nop 0
	global_load_lds_dwordx4 v[162:163], off
	s_waitcnt vmcnt(8)
	s_waitcnt lgkmcnt(0)
	s_barrier
	s_setprio 1
	s_waitcnt lgkmcnt(0)
	v_mfma_f32_16x16x32_bf16 v[124:127], v[154:157], v[194:197], 0
	v_mfma_f32_16x16x32_bf16 v[120:123], v[170:173], v[194:197], 0
	v_mfma_f32_16x16x32_bf16 v[108:111], v[154:157], v[202:205], 0
	v_mfma_f32_16x16x32_bf16 v[104:107], v[170:173], v[202:205], 0
	v_mfma_f32_16x16x32_bf16 v[92:95], v[154:157], v[210:213], 0
	v_mfma_f32_16x16x32_bf16 v[88:91], v[170:173], v[210:213], 0
	v_mfma_f32_16x16x32_bf16 v[76:79], v[154:157], v[218:221], 0
	v_mfma_f32_16x16x32_bf16 v[72:75], v[170:173], v[218:221], 0
	v_mfma_f32_16x16x32_bf16 v[124:127], v[158:161], v[198:201], v[124:127]
	v_mfma_f32_16x16x32_bf16 v[120:123], v[174:177], v[198:201], v[120:123]
	v_mfma_f32_16x16x32_bf16 v[108:111], v[158:161], v[206:209], v[108:111]
	v_mfma_f32_16x16x32_bf16 v[104:107], v[174:177], v[206:209], v[104:107]
	v_mfma_f32_16x16x32_bf16 v[92:95], v[158:161], v[214:217], v[92:95]
	v_mfma_f32_16x16x32_bf16 v[88:91], v[174:177], v[214:217], v[88:91]
	v_mfma_f32_16x16x32_bf16 v[76:79], v[158:161], v[222:225], v[76:79]
	v_mfma_f32_16x16x32_bf16 v[72:75], v[174:177], v[222:225], v[72:75]
	s_setprio 0
	s_setprio 1
	v_mfma_f32_16x16x32_bf16 v[116:119], v[178:181], v[194:197], 0
	v_mfma_f32_16x16x32_bf16 v[112:115], v[186:189], v[194:197], 0
	v_mfma_f32_16x16x32_bf16 v[100:103], v[178:181], v[202:205], 0
	v_mfma_f32_16x16x32_bf16 v[96:99], v[186:189], v[202:205], 0
	v_mfma_f32_16x16x32_bf16 v[84:87], v[178:181], v[210:213], 0
	v_mfma_f32_16x16x32_bf16 v[80:83], v[186:189], v[210:213], 0
	v_mfma_f32_16x16x32_bf16 v[68:71], v[178:181], v[218:221], 0
	v_mfma_f32_16x16x32_bf16 v[64:67], v[186:189], v[218:221], 0
	v_mfma_f32_16x16x32_bf16 v[116:119], v[182:185], v[198:201], v[116:119]
	v_mfma_f32_16x16x32_bf16 v[112:115], v[190:193], v[198:201], v[112:115]
	v_mfma_f32_16x16x32_bf16 v[100:103], v[182:185], v[206:209], v[100:103]
	v_mfma_f32_16x16x32_bf16 v[96:99], v[190:193], v[206:209], v[96:99]
	v_mfma_f32_16x16x32_bf16 v[84:87], v[182:185], v[214:217], v[84:87]
	v_mfma_f32_16x16x32_bf16 v[80:83], v[190:193], v[214:217], v[80:83]
	v_mfma_f32_16x16x32_bf16 v[68:71], v[182:185], v[222:225], v[68:71]
	v_mfma_f32_16x16x32_bf16 v[64:67], v[190:193], v[222:225], v[64:67]
	s_setprio 0
	s_barrier
	s_add_i32 s54, s44, s33
	v_lshl_add_u64 v[162:163], s[20:21], 0, v[130:131]
	s_mov_b32 m0, s54
	ds_read_b128 v[194:197], v151 offset:16384
	ds_read_b128 v[198:201], v151 offset:17408
	ds_read_b128 v[202:205], v151 offset:18432
	ds_read_b128 v[206:209], v151 offset:19456
	ds_read_b128 v[210:213], v151 offset:20480
	ds_read_b128 v[214:217], v151 offset:21504
	ds_read_b128 v[218:221], v151 offset:22528
	ds_read_b128 v[222:225], v151 offset:23552
	global_load_lds_dwordx4 v[162:163], off
	s_add_i32 m0, s54, 0x2000
	s_add_u32 s54, s20, 0x84000
	v_lshl_add_u64 v[166:167], s[20:21], 0, v[134:135]
	s_addc_u32 s55, s21, 0
	s_add_i32 s56, s45, s33
	global_load_lds_dwordx4 v[166:167], off
	v_lshl_add_u64 v[226:227], s[54:55], 0, v[130:131]
	s_mov_b32 m0, s56
	v_lshl_add_u64 v[228:229], s[22:23], 0, v[132:133]
	global_load_lds_dwordx4 v[226:227], off
	v_lshl_add_u64 v[226:227], s[54:55], 0, v[134:135]
	s_add_i32 m0, s56, 0x2000
	s_nop 0
	global_load_lds_dwordx4 v[226:227], off
	v_lshl_add_u64 v[226:227], s[22:23], 0, v[128:129]
	s_mov_b32 m0, s35
	s_nop 0
	global_load_lds_dwordx4 v[226:227], off
	s_mov_b32 m0, s36
	s_nop 0
	global_load_lds_dwordx4 v[228:229], off
	s_waitcnt vmcnt(8)
	s_waitcnt lgkmcnt(0)
	s_barrier
; #define PG8_STAGE(bufoff, gbase, voff) do { _Pragma("unroll") for (int _i = 0; _i < 2; ++_i) \
;         __builtin_amdgcn_global_load_lds((const unsigned*)((const char*)(gbase) + (voff)[_i]), (LAS unsigned*)(lds + (bufoff) + ldsw + _i * 8192), 16, 0, 0); } while (0)
; #define PG8_LDA(dst, b, h) do { _Pragma("unroll") for (int m = 0; m < 4; ++m) _Pragma("unroll") for (int k = 0; k < 2; ++k) dst[m][k] = *(const LAS bf16x8*)(lds + PG8_SA(b, h) + aoff + m * 2048 + k * 1024); } while (0)
; #define PG8_LDB(dst, b, h) do { _Pragma("unroll") for (int n = 0; n < 2; ++n) _Pragma("unroll") for (int k = 0; k < 2; ++k) dst[n][k] = *(const LAS bf16x8*)(lds + PG8_SB(b, h) + boff + n * 2048 + k * 1024); } while (0)
; #define PG8_MMA(ai, bj, At, Bt) do { __builtin_amdgcn_s_setprio(1); _Pragma("unroll") for (int m = 0; m < 4; ++m) _Pragma("unroll") for (int n = 0; n < 2; ++n) _Pragma("unroll") for (int k = 0; k < 2; ++k) \
;         acc[ai][bj][m][n] = __builtin_amdgcn_mfma_f32_16x16x32_bf16(Bt[n][k], At[m][k], acc[ai][bj][m][n], 0, 0, 0); __builtin_amdgcn_s_setprio(0); } while (0)
; #define PG8_WAIT_V(n) asm volatile("s_waitcnt vmcnt(" #n ")" ::: "memory")
; #define PG8_WAIT_L(n) asm volatile("s_waitcnt lgkmcnt(" #n ")" ::: "memory")
; #define PG8_BAR __builtin_amdgcn_s_barrier()
; #define PG8_SCHED __builtin_amdgcn_sched_barrier(0)
; template <class EpiT>
; __device__ __forceinline__ void gemm_phase(LAS unsigned char* lds, const Gemm g, const StaticOrder& S, const EpiT& E) {
;     ...
;             PG8_WAIT_V(8); PG8_WAIT_L(0); PG8_BAR; PG8_MMA(1, 0, At, B0); PG8_MMA(1, 1, At, B1); PG8_BAR; PG8_SCHED;
;             PG8_LDB(B0, 1, 0); PG8_LDB(B1, 1, 1); PG8_SCHED; PG8_LDA(At, 1, 0); PG8_STAGE(PG8_SA(0, 1), a2 + hstepA, voffA);
;             PG8_WAIT_V(8); PG8_WAIT_L(0); PG8_BAR; PG8_MMA(0, 0, At, B0); PG8_MMA(0, 1, At, B1); PG8_BAR; PG8_SCHED;
	s_setprio 1
	s_waitcnt lgkmcnt(0)
	v_mfma_f32_16x16x32_bf16 v[60:63], v[154:157], v[194:197], 0
	v_mfma_f32_16x16x32_bf16 v[56:59], v[170:173], v[194:197], 0
	v_mfma_f32_16x16x32_bf16 v[44:47], v[154:157], v[202:205], 0
	v_mfma_f32_16x16x32_bf16 v[40:43], v[170:173], v[202:205], 0
	v_mfma_f32_16x16x32_bf16 v[28:31], v[154:157], v[210:213], 0
	v_mfma_f32_16x16x32_bf16 v[24:27], v[170:173], v[210:213], 0
	v_mfma_f32_16x16x32_bf16 v[12:15], v[154:157], v[218:221], 0
	v_mfma_f32_16x16x32_bf16 v[8:11], v[170:173], v[218:221], 0
	v_mfma_f32_16x16x32_bf16 v[60:63], v[158:161], v[198:201], v[60:63]
	v_mfma_f32_16x16x32_bf16 v[56:59], v[174:177], v[198:201], v[56:59]
	v_mfma_f32_16x16x32_bf16 v[44:47], v[158:161], v[206:209], v[44:47]
	v_mfma_f32_16x16x32_bf16 v[40:43], v[174:177], v[206:209], v[40:43]
	v_mfma_f32_16x16x32_bf16 v[28:31], v[158:161], v[214:217], v[28:31]
	v_mfma_f32_16x16x32_bf16 v[24:27], v[174:177], v[214:217], v[24:27]
	v_mfma_f32_16x16x32_bf16 v[12:15], v[158:161], v[222:225], v[12:15]
	v_mfma_f32_16x16x32_bf16 v[8:11], v[174:177], v[222:225], v[8:11]
	s_setprio 0
	s_setprio 1
	v_mfma_f32_16x16x32_bf16 v[52:55], v[178:181], v[194:197], 0
	v_mfma_f32_16x16x32_bf16 v[48:51], v[186:189], v[194:197], 0
	v_mfma_f32_16x16x32_bf16 v[36:39], v[178:181], v[202:205], 0
	v_mfma_f32_16x16x32_bf16 v[32:35], v[186:189], v[202:205], 0
	v_mfma_f32_16x16x32_bf16 v[20:23], v[178:181], v[210:213], 0
	v_mfma_f32_16x16x32_bf16 v[16:19], v[186:189], v[210:213], 0
	v_mfma_f32_16x16x32_bf16 v[4:7], v[178:181], v[218:221], 0
	v_mfma_f32_16x16x32_bf16 v[0:3], v[186:189], v[218:221], 0
	v_mfma_f32_16x16x32_bf16 v[52:55], v[182:185], v[198:201], v[52:55]
	v_mfma_f32_16x16x32_bf16 v[48:51], v[190:193], v[198:201], v[48:51]
	v_mfma_f32_16x16x32_bf16 v[36:39], v[182:185], v[206:209], v[36:39]
	v_mfma_f32_16x16x32_bf16 v[32:35], v[190:193], v[206:209], v[32:35]
	v_mfma_f32_16x16x32_bf16 v[20:23], v[182:185], v[214:217], v[20:23]
	v_mfma_f32_16x16x32_bf16 v[16:19], v[190:193], v[214:217], v[16:19]
	v_mfma_f32_16x16x32_bf16 v[4:7], v[182:185], v[222:225], v[4:7]
	v_mfma_f32_16x16x32_bf16 v[0:3], v[190:193], v[222:225], v[0:3]
	s_setprio 0
	s_barrier
	s_add_i32 s54, 0, 0x18000
	v_add_u32_e32 v153, s54, v146
	s_add_i32 s55, 0, 0x1c000
	ds_read_b128 v[154:157], v153
	ds_read_b128 v[158:161], v153 offset:1024
	ds_read_b128 v[170:173], v153 offset:2048
	ds_read_b128 v[174:177], v153 offset:3072
	v_add_u32_e32 v153, s55, v146
	ds_read_b128 v[178:181], v153
	ds_read_b128 v[182:185], v153 offset:1024
	ds_read_b128 v[186:189], v153 offset:2048
	ds_read_b128 v[190:193], v153 offset:3072
	s_add_u32 s22, s22, 0x84000
	s_addc_u32 s23, s23, 0
	s_mov_b32 m0, s37
	v_lshl_add_u64 v[230:231], s[22:23], 0, v[128:129]
	ds_read_b128 v[194:197], v151 offset:32768
	ds_read_b128 v[198:201], v151 offset:33792
	ds_read_b128 v[202:205], v151 offset:34816
	ds_read_b128 v[206:209], v151 offset:35840
	ds_read_b128 v[210:213], v151 offset:36864
	ds_read_b128 v[214:217], v151 offset:37888
	ds_read_b128 v[218:221], v151 offset:38912
	ds_read_b128 v[222:225], v151 offset:39936
	global_load_lds_dwordx4 v[230:231], off
	v_lshl_add_u64 v[230:231], s[22:23], 0, v[132:133]
	s_mov_b32 m0, s38
	s_nop 0
	global_load_lds_dwordx4 v[230:231], off
	s_waitcnt vmcnt(8)
	s_waitcnt lgkmcnt(0)
	s_barrier
	s_setprio 1
	s_waitcnt lgkmcnt(0)
	v_mfma_f32_16x16x32_bf16 v[124:127], v[154:157], v[194:197], v[124:127]
	v_mfma_f32_16x16x32_bf16 v[120:123], v[170:173], v[194:197], v[120:123]
	v_mfma_f32_16x16x32_bf16 v[108:111], v[154:157], v[202:205], v[108:111]
	v_mfma_f32_16x16x32_bf16 v[104:107], v[170:173], v[202:205], v[104:107]
	v_mfma_f32_16x16x32_bf16 v[92:95], v[154:157], v[210:213], v[92:95]
	v_mfma_f32_16x16x32_bf16 v[88:91], v[170:173], v[210:213], v[88:91]
	v_mfma_f32_16x16x32_bf16 v[76:79], v[154:157], v[218:221], v[76:79]
	v_mfma_f32_16x16x32_bf16 v[72:75], v[170:173], v[218:221], v[72:75]
	v_mfma_f32_16x16x32_bf16 v[124:127], v[158:161], v[198:201], v[124:127]
	v_mfma_f32_16x16x32_bf16 v[120:123], v[174:177], v[198:201], v[120:123]
	v_mfma_f32_16x16x32_bf16 v[108:111], v[158:161], v[206:209], v[108:111]
	v_mfma_f32_16x16x32_bf16 v[104:107], v[174:177], v[206:209], v[104:107]
	v_mfma_f32_16x16x32_bf16 v[92:95], v[158:161], v[214:217], v[92:95]
	v_mfma_f32_16x16x32_bf16 v[88:91], v[174:177], v[214:217], v[88:91]
	v_mfma_f32_16x16x32_bf16 v[76:79], v[158:161], v[222:225], v[76:79]
	v_mfma_f32_16x16x32_bf16 v[72:75], v[174:177], v[222:225], v[72:75]
	s_setprio 0
	s_setprio 1
	v_mfma_f32_16x16x32_bf16 v[116:119], v[178:181], v[194:197], v[116:119]
	v_mfma_f32_16x16x32_bf16 v[112:115], v[186:189], v[194:197], v[112:115]
	v_mfma_f32_16x16x32_bf16 v[100:103], v[178:181], v[202:205], v[100:103]
	v_mfma_f32_16x16x32_bf16 v[96:99], v[186:189], v[202:205], v[96:99]
	v_mfma_f32_16x16x32_bf16 v[84:87], v[178:181], v[210:213], v[84:87]
	v_mfma_f32_16x16x32_bf16 v[80:83], v[186:189], v[210:213], v[80:83]
	v_mfma_f32_16x16x32_bf16 v[68:71], v[178:181], v[218:221], v[68:71]
	v_mfma_f32_16x16x32_bf16 v[64:67], v[186:189], v[218:221], v[64:67]
	v_mfma_f32_16x16x32_bf16 v[116:119], v[182:185], v[198:201], v[116:119]
	v_mfma_f32_16x16x32_bf16 v[112:115], v[190:193], v[198:201], v[112:115]
	v_mfma_f32_16x16x32_bf16 v[100:103], v[182:185], v[206:209], v[100:103]
	v_mfma_f32_16x16x32_bf16 v[96:99], v[190:193], v[206:209], v[96:99]
	v_mfma_f32_16x16x32_bf16 v[84:87], v[182:185], v[214:217], v[84:87]
	v_mfma_f32_16x16x32_bf16 v[80:83], v[190:193], v[214:217], v[80:83]
	v_mfma_f32_16x16x32_bf16 v[68:71], v[182:185], v[222:225], v[68:71]
	v_mfma_f32_16x16x32_bf16 v[64:67], v[190:193], v[222:225], v[64:67]
	s_setprio 0
	s_barrier
; #define PG8_STAGE(bufoff, gbase, voff) do { _Pragma("unroll") for (int _i = 0; _i < 2; ++_i) \
;         __builtin_amdgcn_global_load_lds((const unsigned*)((const char*)(gbase) + (voff)[_i]), (LAS unsigned*)(lds + (bufoff) + ldsw + _i * 8192), 16, 0, 0); } while (0)
; #define PG8_LDA(dst, b, h) do { _Pragma("unroll") for (int m = 0; m < 4; ++m) _Pragma("unroll") for (int k = 0; k < 2; ++k) dst[m][k] = *(const LAS bf16x8*)(lds + PG8_SA(b, h) + aoff + m * 2048 + k * 1024); } while (0)
; #define PG8_MMA(ai, bj, At, Bt) do { __builtin_amdgcn_s_setprio(1); _Pragma("unroll") for (int m = 0; m < 4; ++m) _Pragma("unroll") for (int n = 0; n < 2; ++n) _Pragma("unroll") for (int k = 0; k < 2; ++k) \
;         acc[ai][bj][m][n] = __builtin_amdgcn_mfma_f32_16x16x32_bf16(Bt[n][k], At[m][k], acc[ai][bj][m][n], 0, 0, 0); __builtin_amdgcn_s_setprio(0); } while (0)
; #define PG8_WAIT_V(n) asm volatile("s_waitcnt vmcnt(" #n ")" ::: "memory")
; #define PG8_WAIT_L(n) asm volatile("s_waitcnt lgkmcnt(" #n ")" ::: "memory")
; #define PG8_BAR __builtin_amdgcn_s_barrier()
; #define PG8_SCHED __builtin_amdgcn_sched_barrier(0)
; template <class EpiT>
; __device__ __forceinline__ void gemm_phase(LAS unsigned char* lds, const Gemm g, const StaticOrder& S, const EpiT& E) {
;     ...
;         for (int t = 0; t < nt; t += 2) {
;             const bool last = (t == nt - 2);
;     ...
;             PG8_LDA(At, 1, 1); PG8_STAGE(PG8_SB(1, 0), b3, voffB); PG8_STAGE(PG8_SB(1, 1), b3 + hstepB, voffB); PG8_STAGE(PG8_SA(1, 0), a3, voffA);
;             PG8_WAIT_V(8); PG8_WAIT_L(0); PG8_BAR; PG8_MMA(1, 0, At, B0); PG8_MMA(1, 1, At, B1); PG8_BAR; PG8_SCHED;
	s_add_i32 s22, s54, s33
	v_lshl_add_u64 v[162:163], v[162:163], 0, s[12:13]
	s_mov_b32 m0, s22
	ds_read_b128 v[194:197], v151 offset:49152
	ds_read_b128 v[198:201], v151 offset:50176
	ds_read_b128 v[202:205], v151 offset:51200
	ds_read_b128 v[206:209], v151 offset:52224
	ds_read_b128 v[210:213], v151 offset:53248
	ds_read_b128 v[214:217], v151 offset:54272
	ds_read_b128 v[218:221], v151 offset:55296
	ds_read_b128 v[222:225], v151 offset:56320
	global_load_lds_dwordx4 v[162:163], off
	s_add_i32 m0, s22, 0x2000
	s_add_u32 s20, s20, 0x84080
	v_lshl_add_u64 v[162:163], v[166:167], 0, s[12:13]
	s_addc_u32 s21, s21, 0
	s_add_i32 s22, s55, s33
	global_load_lds_dwordx4 v[162:163], off
	v_lshl_add_u64 v[162:163], s[20:21], 0, v[130:131]
	s_mov_b32 m0, s22
	s_nop 0
	global_load_lds_dwordx4 v[162:163], off
	v_lshl_add_u64 v[162:163], s[20:21], 0, v[134:135]
	s_add_i32 m0, s22, 0x2000
	s_nop 0
	global_load_lds_dwordx4 v[162:163], off
	v_lshl_add_u64 v[162:163], v[226:227], 0, s[12:13]
	s_mov_b32 m0, s40
	s_nop 0
	global_load_lds_dwordx4 v[162:163], off
	v_lshl_add_u64 v[162:163], v[228:229], 0, s[12:13]
	s_mov_b32 m0, s41
	s_nop 0
	global_load_lds_dwordx4 v[162:163], off
	s_waitcnt vmcnt(8)
	s_waitcnt lgkmcnt(0)
	s_barrier
	s_setprio 1
	s_waitcnt lgkmcnt(0)
	v_mfma_f32_16x16x32_bf16 v[60:63], v[154:157], v[194:197], v[60:63]
	v_mfma_f32_16x16x32_bf16 v[56:59], v[170:173], v[194:197], v[56:59]
	v_mfma_f32_16x16x32_bf16 v[44:47], v[154:157], v[202:205], v[44:47]
	v_mfma_f32_16x16x32_bf16 v[40:43], v[170:173], v[202:205], v[40:43]
	v_mfma_f32_16x16x32_bf16 v[28:31], v[154:157], v[210:213], v[28:31]
	v_mfma_f32_16x16x32_bf16 v[24:27], v[170:173], v[210:213], v[24:27]
	v_mfma_f32_16x16x32_bf16 v[12:15], v[154:157], v[218:221], v[12:15]
	v_mfma_f32_16x16x32_bf16 v[8:11], v[170:173], v[218:221], v[8:11]
	v_mfma_f32_16x16x32_bf16 v[60:63], v[158:161], v[198:201], v[60:63]
	v_mfma_f32_16x16x32_bf16 v[56:59], v[174:177], v[198:201], v[56:59]
	v_mfma_f32_16x16x32_bf16 v[44:47], v[158:161], v[206:209], v[44:47]
	v_mfma_f32_16x16x32_bf16 v[40:43], v[174:177], v[206:209], v[40:43]
	v_mfma_f32_16x16x32_bf16 v[28:31], v[158:161], v[214:217], v[28:31]
	v_mfma_f32_16x16x32_bf16 v[24:27], v[174:177], v[214:217], v[24:27]
	v_mfma_f32_16x16x32_bf16 v[12:15], v[158:161], v[222:225], v[12:15]
	v_mfma_f32_16x16x32_bf16 v[8:11], v[174:177], v[222:225], v[8:11]
	s_setprio 0
	s_setprio 1
	v_mfma_f32_16x16x32_bf16 v[52:55], v[178:181], v[194:197], v[52:55]
	v_mfma_f32_16x16x32_bf16 v[48:51], v[186:189], v[194:197], v[48:51]
	v_mfma_f32_16x16x32_bf16 v[36:39], v[178:181], v[202:205], v[36:39]
	v_mfma_f32_16x16x32_bf16 v[32:35], v[186:189], v[202:205], v[32:35]
	v_mfma_f32_16x16x32_bf16 v[20:23], v[178:181], v[210:213], v[20:23]
	v_mfma_f32_16x16x32_bf16 v[16:19], v[186:189], v[210:213], v[16:19]
	v_mfma_f32_16x16x32_bf16 v[4:7], v[178:181], v[218:221], v[4:7]
	v_mfma_f32_16x16x32_bf16 v[0:3], v[186:189], v[218:221], v[0:3]
	v_mfma_f32_16x16x32_bf16 v[52:55], v[182:185], v[198:201], v[52:55]
	v_mfma_f32_16x16x32_bf16 v[48:51], v[190:193], v[198:201], v[48:51]
	v_mfma_f32_16x16x32_bf16 v[36:39], v[182:185], v[206:209], v[36:39]
	v_mfma_f32_16x16x32_bf16 v[32:35], v[190:193], v[206:209], v[32:35]
	v_mfma_f32_16x16x32_bf16 v[20:23], v[182:185], v[214:217], v[20:23]
	v_mfma_f32_16x16x32_bf16 v[16:19], v[190:193], v[214:217], v[16:19]
	v_mfma_f32_16x16x32_bf16 v[4:7], v[182:185], v[222:225], v[4:7]
	v_mfma_f32_16x16x32_bf16 v[0:3], v[190:193], v[222:225], v[0:3]
	s_setprio 0
	s_barrier
	s_add_i32 s53, s53, 2
	s_add_u32 s18, s18, 0x100
	s_addc_u32 s19, s19, 0
	s_add_u32 s51, s51, 0x100
	s_addc_u32 s52, s52, 0
	s_cmp_gt_u32 s53, 29
	s_cbranch_scc1 .Lpeel_done_392
	.p2alignl 6, 3212836864
	s_nop 0
	s_nop 0
	s_nop 0
	s_nop 0
	s_nop 0
	s_nop 0
	s_nop 0
	s_nop 0
	s_nop 0
	s_nop 0
	s_nop 0
	s_nop 0
	s_nop 0
	s_nop 0

; #define PG8_BAR __builtin_amdgcn_s_barrier()
; template <class EpiT>
; __device__ __forceinline__ void gemm_phase(LAS unsigned char* lds, const Gemm g, const StaticOrder& S, const EpiT& E) {
;     ...
;         if (wr == 0) PG8_BAR;
;         E(acc, cur, wr, wc, fr, fq);
.Lpeel_done_392:
	s_and_b64 vcc, exec, s[14:15]
	s_cbranch_vccz .LBB0_395
	s_barrier

; #define PG8_STAGE(bufoff, gbase, voff) do { _Pragma("unroll") for (int _i = 0; _i < 2; ++_i) \
;         __builtin_amdgcn_global_load_lds((const unsigned*)((const char*)(gbase) + (voff)[_i]), (LAS unsigned*)(lds + (bufoff) + ldsw + _i * 8192), 16, 0, 0); } while (0)
; #define PG8_LDA(dst, b, h) do { _Pragma("unroll") for (int m = 0; m < 4; ++m) _Pragma("unroll") for (int k = 0; k < 2; ++k) dst[m][k] = *(const LAS bf16x8*)(lds + PG8_SA(b, h) + aoff + m * 2048 + k * 1024); } while (0)
; #define PG8_LDB(dst, b, h) do { _Pragma("unroll") for (int n = 0; n < 2; ++n) _Pragma("unroll") for (int k = 0; k < 2; ++k) dst[n][k] = *(const LAS bf16x8*)(lds + PG8_SB(b, h) + boff + n * 2048 + k * 1024); } while (0)
; #define PG8_WAIT_V(n) asm volatile("s_waitcnt vmcnt(" #n ")" ::: "memory")
; #define PG8_WAIT_L(n) asm volatile("s_waitcnt lgkmcnt(" #n ")" ::: "memory")
; template <class EpiT>
; __device__ __forceinline__ void gemm_phase(LAS unsigned char* lds, const Gemm g, const StaticOrder& S, const EpiT& E) {
;     ...
;         const char* nA = has_next ? (const char*)g.A + (size_t)nxt.pm * tstepA + (size_t)nxt.pn * g.a_koff * 2 : cA; const char* nB = has_next ? (const char*)g.Bt + (size_t)nxt.pn * tstepB : cB;
;         for (int t = 0; t < nt; t += 2) {
;             const bool last = (t == nt - 2);
;             const char* a1 = cA + (size_t)(t + 1) * kstep;
;             const char* a2 = last ? nA : cA + (size_t)(t + 2) * kstep; const char* b2 = last ? nB : cB + (size_t)(t + 2) * kstep;
;             const char* a3 = a2 + kstep; const char* b3 = b2 + kstep;
;             PG8_LDB(B0, 0, 0); PG8_LDB(B1, 0, 1); PG8_SCHED; PG8_LDA(At, 0, 0); PG8_STAGE(PG8_SA(1, 1), a1 + hstepA, voffA);
;             PG8_WAIT_V(8); PG8_WAIT_L(0); PG8_BAR; PG8_MMA(0, 0, At, B0); PG8_MMA(0, 1, At, B1); PG8_BAR; PG8_SCHED;
;             PG8_LDA(At, 0, 1); PG8_STAGE(PG8_SB(0, 0), b2, voffB); PG8_STAGE(PG8_SB(0, 1), b2 + hstepB, voffB); PG8_STAGE(PG8_SA(0, 0), a2, voffA);
;             PG8_WAIT_V(8); PG8_WAIT_L(0); PG8_BAR; PG8_MMA(1, 0, At, B0); PG8_MMA(1, 1, At, B1); PG8_BAR; PG8_SCHED;
;     ...
; #pragma unroll
;         for (int a = 0; a < 2; ++a)
; #pragma unroll
;             for (int b = 0; b < 2; ++b)
; #pragma unroll
;                 for (int m = 0; m < 4; ++m)
; #pragma unroll
;                     for (int n = 0; n < 2; ++n) acc[a][b][m][n] = (f32x4){0.f, 0.f, 0.f, 0.f};
.LBB0_515:
	s_add_u32 s16, s16, 0x84080
	s_addc_u32 s17, s17, 0
	s_add_u32 s51, s18, 0x100
	s_addc_u32 s52, s19, 0
	s_mov_b32 s53, -2
	ds_read_b128 v[154:157], v150
	ds_read_b128 v[158:161], v150 offset:1024
	ds_read_b128 v[170:173], v150 offset:2048
	ds_read_b128 v[174:177], v150 offset:3072
	ds_read_b128 v[178:181], v151
	ds_read_b128 v[182:185], v151 offset:1024
	ds_read_b128 v[186:189], v151 offset:2048
	ds_read_b128 v[190:193], v151 offset:3072
	s_add_u32 s18, s16, 0xfff7c080
	s_addc_u32 s19, s17, -1
	s_cmp_eq_u32 s53, 28
	s_cselect_b32 s21, s3, s19
	s_cselect_b32 s20, s2, s18
	s_cselect_b32 s19, s15, s52
	s_cselect_b32 s18, s14, s51
	v_lshl_add_u64 v[144:145], s[16:17], 0, v[136:137]
	s_add_i32 m0, s36, 0xc000
	ds_read_b128 v[194:197], v152
	ds_read_b128 v[198:201], v152 offset:1024
	ds_read_b128 v[202:205], v152 offset:2048
	ds_read_b128 v[206:209], v152 offset:3072
	ds_read_b128 v[210:213], v152 offset:4096
	ds_read_b128 v[214:217], v152 offset:5120
	ds_read_b128 v[218:221], v152 offset:6144
	ds_read_b128 v[222:225], v152 offset:7168
	global_load_lds_dwordx4 v[144:145], off
	v_lshl_add_u64 v[144:145], s[16:17], 0, v[138:139]
	s_add_i32 m0, s36, 0xe000
	s_nop 0
	global_load_lds_dwordx4 v[144:145], off
	s_waitcnt vmcnt(8)
	s_waitcnt lgkmcnt(0)
	s_barrier
	s_setprio 1
	s_waitcnt lgkmcnt(0)
	v_mfma_f32_16x16x32_bf16 v[124:127], v[154:157], v[194:197], 0
	v_mfma_f32_16x16x32_bf16 v[120:123], v[170:173], v[194:197], 0
	v_mfma_f32_16x16x32_bf16 v[108:111], v[154:157], v[202:205], 0
	v_mfma_f32_16x16x32_bf16 v[104:107], v[170:173], v[202:205], 0
	v_mfma_f32_16x16x32_bf16 v[92:95], v[154:157], v[210:213], 0
	v_mfma_f32_16x16x32_bf16 v[88:91], v[170:173], v[210:213], 0
	v_mfma_f32_16x16x32_bf16 v[76:79], v[154:157], v[218:221], 0
	v_mfma_f32_16x16x32_bf16 v[72:75], v[170:173], v[218:221], 0
	v_mfma_f32_16x16x32_bf16 v[124:127], v[158:161], v[198:201], v[124:127]
	v_mfma_f32_16x16x32_bf16 v[120:123], v[174:177], v[198:201], v[120:123]
	v_mfma_f32_16x16x32_bf16 v[108:111], v[158:161], v[206:209], v[108:111]
	v_mfma_f32_16x16x32_bf16 v[104:107], v[174:177], v[206:209], v[104:107]
	v_mfma_f32_16x16x32_bf16 v[92:95], v[158:161], v[214:217], v[92:95]
	v_mfma_f32_16x16x32_bf16 v[88:91], v[174:177], v[214:217], v[88:91]
	v_mfma_f32_16x16x32_bf16 v[76:79], v[158:161], v[222:225], v[76:79]
	v_mfma_f32_16x16x32_bf16 v[72:75], v[174:177], v[222:225], v[72:75]
	s_setprio 0
	s_setprio 1
	v_mfma_f32_16x16x32_bf16 v[116:119], v[178:181], v[194:197], 0
	v_mfma_f32_16x16x32_bf16 v[112:115], v[186:189], v[194:197], 0
	v_mfma_f32_16x16x32_bf16 v[100:103], v[178:181], v[202:205], 0
	v_mfma_f32_16x16x32_bf16 v[96:99], v[186:189], v[202:205], 0
	v_mfma_f32_16x16x32_bf16 v[84:87], v[178:181], v[210:213], 0
	v_mfma_f32_16x16x32_bf16 v[80:83], v[186:189], v[210:213], 0
	v_mfma_f32_16x16x32_bf16 v[68:71], v[178:181], v[218:221], 0
	v_mfma_f32_16x16x32_bf16 v[64:67], v[186:189], v[218:221], 0
	v_mfma_f32_16x16x32_bf16 v[116:119], v[182:185], v[198:201], v[116:119]
	v_mfma_f32_16x16x32_bf16 v[112:115], v[190:193], v[198:201], v[112:115]
	v_mfma_f32_16x16x32_bf16 v[100:103], v[182:185], v[206:209], v[100:103]
	v_mfma_f32_16x16x32_bf16 v[96:99], v[190:193], v[206:209], v[96:99]
	v_mfma_f32_16x16x32_bf16 v[84:87], v[182:185], v[214:217], v[84:87]
	v_mfma_f32_16x16x32_bf16 v[80:83], v[190:193], v[214:217], v[80:83]
	v_mfma_f32_16x16x32_bf16 v[68:71], v[182:185], v[222:225], v[68:71]
	v_mfma_f32_16x16x32_bf16 v[64:67], v[190:193], v[222:225], v[64:67]
	s_setprio 0
	s_barrier
	s_add_i32 s54, s44, s27
	v_lshl_add_u64 v[144:145], s[18:19], 0, v[132:133]
	s_mov_b32 m0, s54
	ds_read_b128 v[194:197], v152 offset:16384
	ds_read_b128 v[198:201], v152 offset:17408
	ds_read_b128 v[202:205], v152 offset:18432
	ds_read_b128 v[206:209], v152 offset:19456
	ds_read_b128 v[210:213], v152 offset:20480
	ds_read_b128 v[214:217], v152 offset:21504
	ds_read_b128 v[218:221], v152 offset:22528
	ds_read_b128 v[222:225], v152 offset:23552
	global_load_lds_dwordx4 v[144:145], off
	s_add_i32 m0, s54, 0x2000
	s_add_u32 s54, s18, 0x84000
	v_lshl_add_u64 v[162:163], s[18:19], 0, v[128:129]
	s_addc_u32 s55, s19, 0
	s_add_i32 s56, s45, s27
	global_load_lds_dwordx4 v[162:163], off
	v_lshl_add_u64 v[166:167], s[54:55], 0, v[132:133]
	s_mov_b32 m0, s56
	v_lshl_add_u64 v[226:227], s[20:21], 0, v[130:131]
	global_load_lds_dwordx4 v[166:167], off
	v_lshl_add_u64 v[166:167], s[54:55], 0, v[128:129]
	s_add_i32 m0, s56, 0x2000
	s_nop 0
	global_load_lds_dwordx4 v[166:167], off
	v_lshl_add_u64 v[166:167], s[20:21], 0, v[134:135]
	s_mov_b32 m0, s36
	s_nop 0
	global_load_lds_dwordx4 v[166:167], off
	s_mov_b32 m0, s37
	s_nop 0
	global_load_lds_dwordx4 v[226:227], off
	s_waitcnt vmcnt(8)
	s_waitcnt lgkmcnt(0)
	s_barrier
; #define PG8_STAGE(bufoff, gbase, voff) do { _Pragma("unroll") for (int _i = 0; _i < 2; ++_i) \
;         __builtin_amdgcn_global_load_lds((const unsigned*)((const char*)(gbase) + (voff)[_i]), (LAS unsigned*)(lds + (bufoff) + ldsw + _i * 8192), 16, 0, 0); } while (0)
; #define PG8_LDA(dst, b, h) do { _Pragma("unroll") for (int m = 0; m < 4; ++m) _Pragma("unroll") for (int k = 0; k < 2; ++k) dst[m][k] = *(const LAS bf16x8*)(lds + PG8_SA(b, h) + aoff + m * 2048 + k * 1024); } while (0)
; #define PG8_LDB(dst, b, h) do { _Pragma("unroll") for (int n = 0; n < 2; ++n) _Pragma("unroll") for (int k = 0; k < 2; ++k) dst[n][k] = *(const LAS bf16x8*)(lds + PG8_SB(b, h) + boff + n * 2048 + k * 1024); } while (0)
; #define PG8_MMA(ai, bj, At, Bt) do { __builtin_amdgcn_s_setprio(1); _Pragma("unroll") for (int m = 0; m < 4; ++m) _Pragma("unroll") for (int n = 0; n < 2; ++n) _Pragma("unroll") for (int k = 0; k < 2; ++k) \
;         acc[ai][bj][m][n] = __builtin_amdgcn_mfma_f32_16x16x32_bf16(Bt[n][k], At[m][k], acc[ai][bj][m][n], 0, 0, 0); __builtin_amdgcn_s_setprio(0); } while (0)
; #define PG8_WAIT_V(n) asm volatile("s_waitcnt vmcnt(" #n ")" ::: "memory")
; #define PG8_WAIT_L(n) asm volatile("s_waitcnt lgkmcnt(" #n ")" ::: "memory")
; #define PG8_BAR __builtin_amdgcn_s_barrier()
; #define PG8_SCHED __builtin_amdgcn_sched_barrier(0)
; template <class EpiT>
; __device__ __forceinline__ void gemm_phase(LAS unsigned char* lds, const Gemm g, const StaticOrder& S, const EpiT& E) {
;     ...
;             PG8_WAIT_V(8); PG8_WAIT_L(0); PG8_BAR; PG8_MMA(1, 0, At, B0); PG8_MMA(1, 1, At, B1); PG8_BAR; PG8_SCHED;
;             PG8_LDB(B0, 1, 0); PG8_LDB(B1, 1, 1); PG8_SCHED; PG8_LDA(At, 1, 0); PG8_STAGE(PG8_SA(0, 1), a2 + hstepA, voffA);
;             PG8_WAIT_V(8); PG8_WAIT_L(0); PG8_BAR; PG8_MMA(0, 0, At, B0); PG8_MMA(0, 1, At, B1); PG8_BAR; PG8_SCHED;
	s_setprio 1
	s_waitcnt lgkmcnt(0)
	v_mfma_f32_16x16x32_bf16 v[60:63], v[154:157], v[194:197], 0
	v_mfma_f32_16x16x32_bf16 v[56:59], v[170:173], v[194:197], 0
	v_mfma_f32_16x16x32_bf16 v[44:47], v[154:157], v[202:205], 0
	v_mfma_f32_16x16x32_bf16 v[40:43], v[170:173], v[202:205], 0
	v_mfma_f32_16x16x32_bf16 v[28:31], v[154:157], v[210:213], 0
	v_mfma_f32_16x16x32_bf16 v[24:27], v[170:173], v[210:213], 0
	v_mfma_f32_16x16x32_bf16 v[12:15], v[154:157], v[218:221], 0
	v_mfma_f32_16x16x32_bf16 v[8:11], v[170:173], v[218:221], 0
	v_mfma_f32_16x16x32_bf16 v[60:63], v[158:161], v[198:201], v[60:63]
	v_mfma_f32_16x16x32_bf16 v[56:59], v[174:177], v[198:201], v[56:59]
	v_mfma_f32_16x16x32_bf16 v[44:47], v[158:161], v[206:209], v[44:47]
	v_mfma_f32_16x16x32_bf16 v[40:43], v[174:177], v[206:209], v[40:43]
	v_mfma_f32_16x16x32_bf16 v[28:31], v[158:161], v[214:217], v[28:31]
	v_mfma_f32_16x16x32_bf16 v[24:27], v[174:177], v[214:217], v[24:27]
	v_mfma_f32_16x16x32_bf16 v[12:15], v[158:161], v[222:225], v[12:15]
	v_mfma_f32_16x16x32_bf16 v[8:11], v[174:177], v[222:225], v[8:11]
	s_setprio 0
	s_setprio 1
	v_mfma_f32_16x16x32_bf16 v[52:55], v[178:181], v[194:197], 0
	v_mfma_f32_16x16x32_bf16 v[48:51], v[186:189], v[194:197], 0
	v_mfma_f32_16x16x32_bf16 v[36:39], v[178:181], v[202:205], 0
	v_mfma_f32_16x16x32_bf16 v[32:35], v[186:189], v[202:205], 0
	v_mfma_f32_16x16x32_bf16 v[20:23], v[178:181], v[210:213], 0
	v_mfma_f32_16x16x32_bf16 v[16:19], v[186:189], v[210:213], 0
	v_mfma_f32_16x16x32_bf16 v[4:7], v[178:181], v[218:221], 0
	v_mfma_f32_16x16x32_bf16 v[0:3], v[186:189], v[218:221], 0
	v_mfma_f32_16x16x32_bf16 v[52:55], v[182:185], v[198:201], v[52:55]
	v_mfma_f32_16x16x32_bf16 v[48:51], v[190:193], v[198:201], v[48:51]
	v_mfma_f32_16x16x32_bf16 v[36:39], v[182:185], v[206:209], v[36:39]
	v_mfma_f32_16x16x32_bf16 v[32:35], v[190:193], v[206:209], v[32:35]
	v_mfma_f32_16x16x32_bf16 v[20:23], v[182:185], v[214:217], v[20:23]
	v_mfma_f32_16x16x32_bf16 v[16:19], v[190:193], v[214:217], v[16:19]
	v_mfma_f32_16x16x32_bf16 v[4:7], v[182:185], v[222:225], v[4:7]
	v_mfma_f32_16x16x32_bf16 v[0:3], v[190:193], v[222:225], v[0:3]
	s_setprio 0
	s_barrier
	s_add_i32 s54, 0, 0x18000
	v_add_u32_e32 v153, s54, v147
	s_add_i32 s55, 0, 0x1c000
	ds_read_b128 v[154:157], v153
	ds_read_b128 v[158:161], v153 offset:1024
	ds_read_b128 v[170:173], v153 offset:2048
	ds_read_b128 v[174:177], v153 offset:3072
	v_add_u32_e32 v153, s55, v147
	ds_read_b128 v[178:181], v153
	ds_read_b128 v[182:185], v153 offset:1024
	ds_read_b128 v[186:189], v153 offset:2048
	ds_read_b128 v[190:193], v153 offset:3072
	s_add_u32 s20, s20, 0x84000
	s_addc_u32 s21, s21, 0
	s_mov_b32 m0, s38
	v_lshl_add_u64 v[228:229], s[20:21], 0, v[134:135]
	ds_read_b128 v[194:197], v152 offset:32768
	ds_read_b128 v[198:201], v152 offset:33792
	ds_read_b128 v[202:205], v152 offset:34816
	ds_read_b128 v[206:209], v152 offset:35840
	ds_read_b128 v[210:213], v152 offset:36864
	ds_read_b128 v[214:217], v152 offset:37888
	ds_read_b128 v[218:221], v152 offset:38912
	ds_read_b128 v[222:225], v152 offset:39936
	global_load_lds_dwordx4 v[228:229], off
	v_lshl_add_u64 v[228:229], s[20:21], 0, v[130:131]
	s_mov_b32 m0, s39
	s_nop 0
	global_load_lds_dwordx4 v[228:229], off
	s_waitcnt vmcnt(8)
	s_waitcnt lgkmcnt(0)
	s_barrier
	s_setprio 1
	s_waitcnt lgkmcnt(0)
	v_mfma_f32_16x16x32_bf16 v[124:127], v[154:157], v[194:197], v[124:127]
	v_mfma_f32_16x16x32_bf16 v[120:123], v[170:173], v[194:197], v[120:123]
	v_mfma_f32_16x16x32_bf16 v[108:111], v[154:157], v[202:205], v[108:111]
	v_mfma_f32_16x16x32_bf16 v[104:107], v[170:173], v[202:205], v[104:107]
	v_mfma_f32_16x16x32_bf16 v[92:95], v[154:157], v[210:213], v[92:95]
	v_mfma_f32_16x16x32_bf16 v[88:91], v[170:173], v[210:213], v[88:91]
	v_mfma_f32_16x16x32_bf16 v[76:79], v[154:157], v[218:221], v[76:79]
	v_mfma_f32_16x16x32_bf16 v[72:75], v[170:173], v[218:221], v[72:75]
	v_mfma_f32_16x16x32_bf16 v[124:127], v[158:161], v[198:201], v[124:127]
	v_mfma_f32_16x16x32_bf16 v[120:123], v[174:177], v[198:201], v[120:123]
	v_mfma_f32_16x16x32_bf16 v[108:111], v[158:161], v[206:209], v[108:111]
	v_mfma_f32_16x16x32_bf16 v[104:107], v[174:177], v[206:209], v[104:107]
	v_mfma_f32_16x16x32_bf16 v[92:95], v[158:161], v[214:217], v[92:95]
	v_mfma_f32_16x16x32_bf16 v[88:91], v[174:177], v[214:217], v[88:91]
	v_mfma_f32_16x16x32_bf16 v[76:79], v[158:161], v[222:225], v[76:79]
	v_mfma_f32_16x16x32_bf16 v[72:75], v[174:177], v[222:225], v[72:75]
	s_setprio 0
	s_setprio 1
	v_mfma_f32_16x16x32_bf16 v[116:119], v[178:181], v[194:197], v[116:119]
	v_mfma_f32_16x16x32_bf16 v[112:115], v[186:189], v[194:197], v[112:115]
	v_mfma_f32_16x16x32_bf16 v[100:103], v[178:181], v[202:205], v[100:103]
	v_mfma_f32_16x16x32_bf16 v[96:99], v[186:189], v[202:205], v[96:99]
	v_mfma_f32_16x16x32_bf16 v[84:87], v[178:181], v[210:213], v[84:87]
	v_mfma_f32_16x16x32_bf16 v[80:83], v[186:189], v[210:213], v[80:83]
	v_mfma_f32_16x16x32_bf16 v[68:71], v[178:181], v[218:221], v[68:71]
	v_mfma_f32_16x16x32_bf16 v[64:67], v[186:189], v[218:221], v[64:67]
	v_mfma_f32_16x16x32_bf16 v[116:119], v[182:185], v[198:201], v[116:119]
	v_mfma_f32_16x16x32_bf16 v[112:115], v[190:193], v[198:201], v[112:115]
	v_mfma_f32_16x16x32_bf16 v[100:103], v[182:185], v[206:209], v[100:103]
	v_mfma_f32_16x16x32_bf16 v[96:99], v[190:193], v[206:209], v[96:99]
	v_mfma_f32_16x16x32_bf16 v[84:87], v[182:185], v[214:217], v[84:87]
	v_mfma_f32_16x16x32_bf16 v[80:83], v[190:193], v[214:217], v[80:83]
	v_mfma_f32_16x16x32_bf16 v[68:71], v[182:185], v[222:225], v[68:71]
	v_mfma_f32_16x16x32_bf16 v[64:67], v[190:193], v[222:225], v[64:67]
	s_setprio 0
	s_barrier
; #define PG8_STAGE(bufoff, gbase, voff) do { _Pragma("unroll") for (int _i = 0; _i < 2; ++_i) \
;         __builtin_amdgcn_global_load_lds((const unsigned*)((const char*)(gbase) + (voff)[_i]), (LAS unsigned*)(lds + (bufoff) + ldsw + _i * 8192), 16, 0, 0); } while (0)
; #define PG8_LDA(dst, b, h) do { _Pragma("unroll") for (int m = 0; m < 4; ++m) _Pragma("unroll") for (int k = 0; k < 2; ++k) dst[m][k] = *(const LAS bf16x8*)(lds + PG8_SA(b, h) + aoff + m * 2048 + k * 1024); } while (0)
; #define PG8_MMA(ai, bj, At, Bt) do { __builtin_amdgcn_s_setprio(1); _Pragma("unroll") for (int m = 0; m < 4; ++m) _Pragma("unroll") for (int n = 0; n < 2; ++n) _Pragma("unroll") for (int k = 0; k < 2; ++k) \
;         acc[ai][bj][m][n] = __builtin_amdgcn_mfma_f32_16x16x32_bf16(Bt[n][k], At[m][k], acc[ai][bj][m][n], 0, 0, 0); __builtin_amdgcn_s_setprio(0); } while (0)
; #define PG8_WAIT_V(n) asm volatile("s_waitcnt vmcnt(" #n ")" ::: "memory")
; #define PG8_WAIT_L(n) asm volatile("s_waitcnt lgkmcnt(" #n ")" ::: "memory")
; #define PG8_BAR __builtin_amdgcn_s_barrier()
; #define PG8_SCHED __builtin_amdgcn_sched_barrier(0)
; template <class EpiT>
; __device__ __forceinline__ void gemm_phase(LAS unsigned char* lds, const Gemm g, const StaticOrder& S, const EpiT& E) {
;     ...
;         for (int t = 0; t < nt; t += 2) {
;             const bool last = (t == nt - 2);
;     ...
;             PG8_LDA(At, 1, 1); PG8_STAGE(PG8_SB(1, 0), b3, voffB); PG8_STAGE(PG8_SB(1, 1), b3 + hstepB, voffB); PG8_STAGE(PG8_SA(1, 0), a3, voffA);
;             PG8_WAIT_V(8); PG8_WAIT_L(0); PG8_BAR; PG8_MMA(1, 0, At, B0); PG8_MMA(1, 1, At, B1); PG8_BAR; PG8_SCHED;
	s_add_i32 s20, s54, s27
	v_lshl_add_u64 v[144:145], v[144:145], 0, s[10:11]
	s_mov_b32 m0, s20
	ds_read_b128 v[194:197], v152 offset:49152
	ds_read_b128 v[198:201], v152 offset:50176
	ds_read_b128 v[202:205], v152 offset:51200
	ds_read_b128 v[206:209], v152 offset:52224
	ds_read_b128 v[210:213], v152 offset:53248
	ds_read_b128 v[214:217], v152 offset:54272
	ds_read_b128 v[218:221], v152 offset:55296
	ds_read_b128 v[222:225], v152 offset:56320
	global_load_lds_dwordx4 v[144:145], off
	s_add_i32 m0, s20, 0x2000
	s_add_u32 s18, s18, 0x84080
	v_lshl_add_u64 v[144:145], v[162:163], 0, s[10:11]
	s_addc_u32 s19, s19, 0
	s_add_i32 s20, s55, s27
	global_load_lds_dwordx4 v[144:145], off
	v_lshl_add_u64 v[144:145], s[18:19], 0, v[132:133]
	s_mov_b32 m0, s20
	s_nop 0
	global_load_lds_dwordx4 v[144:145], off
	v_lshl_add_u64 v[144:145], s[18:19], 0, v[128:129]
	s_add_i32 m0, s20, 0x2000
	s_nop 0
	global_load_lds_dwordx4 v[144:145], off
	v_lshl_add_u64 v[144:145], v[166:167], 0, s[10:11]
	s_mov_b32 m0, s41
	s_nop 0
	global_load_lds_dwordx4 v[144:145], off
	v_lshl_add_u64 v[144:145], v[226:227], 0, s[10:11]
	s_mov_b32 m0, s42
	s_nop 0
	global_load_lds_dwordx4 v[144:145], off
	s_waitcnt vmcnt(8)
	s_waitcnt lgkmcnt(0)
	s_barrier
	s_setprio 1
	s_waitcnt lgkmcnt(0)
	v_mfma_f32_16x16x32_bf16 v[60:63], v[154:157], v[194:197], v[60:63]
	v_mfma_f32_16x16x32_bf16 v[56:59], v[170:173], v[194:197], v[56:59]
	v_mfma_f32_16x16x32_bf16 v[44:47], v[154:157], v[202:205], v[44:47]
	v_mfma_f32_16x16x32_bf16 v[40:43], v[170:173], v[202:205], v[40:43]
	v_mfma_f32_16x16x32_bf16 v[28:31], v[154:157], v[210:213], v[28:31]
	v_mfma_f32_16x16x32_bf16 v[24:27], v[170:173], v[210:213], v[24:27]
	v_mfma_f32_16x16x32_bf16 v[12:15], v[154:157], v[218:221], v[12:15]
	v_mfma_f32_16x16x32_bf16 v[8:11], v[170:173], v[218:221], v[8:11]
	v_mfma_f32_16x16x32_bf16 v[60:63], v[158:161], v[198:201], v[60:63]
	v_mfma_f32_16x16x32_bf16 v[56:59], v[174:177], v[198:201], v[56:59]
	v_mfma_f32_16x16x32_bf16 v[44:47], v[158:161], v[206:209], v[44:47]
	v_mfma_f32_16x16x32_bf16 v[40:43], v[174:177], v[206:209], v[40:43]
	v_mfma_f32_16x16x32_bf16 v[28:31], v[158:161], v[214:217], v[28:31]
	v_mfma_f32_16x16x32_bf16 v[24:27], v[174:177], v[214:217], v[24:27]
	v_mfma_f32_16x16x32_bf16 v[12:15], v[158:161], v[222:225], v[12:15]
	v_mfma_f32_16x16x32_bf16 v[8:11], v[174:177], v[222:225], v[8:11]
	s_setprio 0
	s_setprio 1
	v_mfma_f32_16x16x32_bf16 v[52:55], v[178:181], v[194:197], v[52:55]
	v_mfma_f32_16x16x32_bf16 v[48:51], v[186:189], v[194:197], v[48:51]
	v_mfma_f32_16x16x32_bf16 v[36:39], v[178:181], v[202:205], v[36:39]
	v_mfma_f32_16x16x32_bf16 v[32:35], v[186:189], v[202:205], v[32:35]
	v_mfma_f32_16x16x32_bf16 v[20:23], v[178:181], v[210:213], v[20:23]
	v_mfma_f32_16x16x32_bf16 v[16:19], v[186:189], v[210:213], v[16:19]
	v_mfma_f32_16x16x32_bf16 v[4:7], v[178:181], v[218:221], v[4:7]
	v_mfma_f32_16x16x32_bf16 v[0:3], v[186:189], v[218:221], v[0:3]
	v_mfma_f32_16x16x32_bf16 v[52:55], v[182:185], v[198:201], v[52:55]
	v_mfma_f32_16x16x32_bf16 v[48:51], v[190:193], v[198:201], v[48:51]
	v_mfma_f32_16x16x32_bf16 v[36:39], v[182:185], v[206:209], v[36:39]
	v_mfma_f32_16x16x32_bf16 v[32:35], v[190:193], v[206:209], v[32:35]
	v_mfma_f32_16x16x32_bf16 v[20:23], v[182:185], v[214:217], v[20:23]
	v_mfma_f32_16x16x32_bf16 v[16:19], v[190:193], v[214:217], v[16:19]
	v_mfma_f32_16x16x32_bf16 v[4:7], v[182:185], v[222:225], v[4:7]
	v_mfma_f32_16x16x32_bf16 v[0:3], v[190:193], v[222:225], v[0:3]
	s_setprio 0
	s_barrier
	s_add_i32 s53, s53, 2
	s_add_u32 s16, s16, 0x100
	s_addc_u32 s17, s17, 0
	s_add_u32 s51, s51, 0x100
	s_addc_u32 s52, s52, 0
	s_cmp_gt_u32 s53, 29
	s_cbranch_scc1 .Lpeel_done_516
	.p2alignl 6, 3212836864
	s_nop 0
	s_nop 0
	s_nop 0
	s_nop 0
	s_nop 0
	s_nop 0
	s_nop 0
	s_nop 0
	s_nop 0
	s_nop 0

; #define PG8_STAGE(bufoff, gbase, voff) do { _Pragma("unroll") for (int _i = 0; _i < 2; ++_i) \
;         __builtin_amdgcn_global_load_lds((const unsigned*)((const char*)(gbase) + (voff)[_i]), (LAS unsigned*)(lds + (bufoff) + ldsw + _i * 8192), 16, 0, 0); } while (0)
; #define PG8_LDA(dst, b, h) do { _Pragma("unroll") for (int m = 0; m < 4; ++m) _Pragma("unroll") for (int k = 0; k < 2; ++k) dst[m][k] = *(const LAS bf16x8*)(lds + PG8_SA(b, h) + aoff + m * 2048 + k * 1024); } while (0)
; #define PG8_LDB(dst, b, h) do { _Pragma("unroll") for (int n = 0; n < 2; ++n) _Pragma("unroll") for (int k = 0; k < 2; ++k) dst[n][k] = *(const LAS bf16x8*)(lds + PG8_SB(b, h) + boff + n * 2048 + k * 1024); } while (0)
; #define PG8_WAIT_V(n) asm volatile("s_waitcnt vmcnt(" #n ")" ::: "memory")
; #define PG8_WAIT_L(n) asm volatile("s_waitcnt lgkmcnt(" #n ")" ::: "memory")
; template <class EpiT>
; __device__ __forceinline__ void gemm_phase(LAS unsigned char* lds, const Gemm g, const StaticOrder& S, const EpiT& E) {
;     ...
;         const char* nA = has_next ? (const char*)g.A + (size_t)nxt.pm * tstepA + (size_t)nxt.pn * g.a_koff * 2 : cA; const char* nB = has_next ? (const char*)g.Bt + (size_t)nxt.pn * tstepB : cB;
;         for (int t = 0; t < nt; t += 2) {
;             const bool last = (t == nt - 2);
;             const char* a1 = cA + (size_t)(t + 1) * kstep;
;             const char* a2 = last ? nA : cA + (size_t)(t + 2) * kstep; const char* b2 = last ? nB : cB + (size_t)(t + 2) * kstep;
;             const char* a3 = a2 + kstep; const char* b3 = b2 + kstep;
;             PG8_LDB(B0, 0, 0); PG8_LDB(B1, 0, 1); PG8_SCHED; PG8_LDA(At, 0, 0); PG8_STAGE(PG8_SA(1, 1), a1 + hstepA, voffA);
;             PG8_WAIT_V(8); PG8_WAIT_L(0); PG8_BAR; PG8_MMA(0, 0, At, B0); PG8_MMA(0, 1, At, B1); PG8_BAR; PG8_SCHED;
;             PG8_LDA(At, 0, 1); PG8_STAGE(PG8_SB(0, 0), b2, voffB); PG8_STAGE(PG8_SB(0, 1), b2 + hstepB, voffB); PG8_STAGE(PG8_SA(0, 0), a2, voffA);
;             PG8_WAIT_V(8); PG8_WAIT_L(0); PG8_BAR; PG8_MMA(1, 0, At, B0); PG8_MMA(1, 1, At, B1); PG8_BAR; PG8_SCHED;
;     ...
; #pragma unroll
;         for (int a = 0; a < 2; ++a)
; #pragma unroll
;             for (int b = 0; b < 2; ++b)
; #pragma unroll
;                 for (int m = 0; m < 4; ++m)
; #pragma unroll
;                     for (int n = 0; n < 2; ++n) acc[a][b][m][n] = (f32x4){0.f, 0.f, 0.f, 0.f};
.LBB0_594:
	s_add_u32 s18, s18, 0x164080
	s_addc_u32 s19, s19, 0
	s_add_u32 s53, s20, 0x100
	s_addc_u32 s54, s21, 0
	s_mov_b32 s55, -2
	ds_read_b128 v[154:157], v150
	ds_read_b128 v[158:161], v150 offset:1024
	ds_read_b128 v[170:173], v150 offset:2048
	ds_read_b128 v[174:177], v150 offset:3072
	ds_read_b128 v[178:181], v151
	ds_read_b128 v[182:185], v151 offset:1024
	ds_read_b128 v[186:189], v151 offset:2048
	ds_read_b128 v[190:193], v151 offset:3072
	s_add_u32 s20, s18, 0xffe9c080
	s_addc_u32 s21, s19, -1
	s_cmpk_eq_i32 s55, 0x54
	s_cselect_b32 s23, s5, s21
	s_cselect_b32 s22, s4, s20
	s_cselect_b32 s21, s17, s54
	s_cselect_b32 s20, s16, s53
	v_lshl_add_u64 v[162:163], s[18:19], 0, v[138:139]
	s_add_i32 m0, s37, 0xc000
	ds_read_b128 v[194:197], v152
	ds_read_b128 v[198:201], v152 offset:1024
	ds_read_b128 v[202:205], v152 offset:2048
	ds_read_b128 v[206:209], v152 offset:3072
	ds_read_b128 v[210:213], v152 offset:4096
	ds_read_b128 v[214:217], v152 offset:5120
	ds_read_b128 v[218:221], v152 offset:6144
	ds_read_b128 v[222:225], v152 offset:7168
	global_load_lds_dwordx4 v[162:163], off
	v_lshl_add_u64 v[162:163], s[18:19], 0, v[140:141]
	s_add_i32 m0, s37, 0xe000
	s_nop 0
	global_load_lds_dwordx4 v[162:163], off
	s_waitcnt vmcnt(8)
	s_waitcnt lgkmcnt(0)
	s_barrier
	s_setprio 1
	s_waitcnt lgkmcnt(0)
	v_mfma_f32_16x16x32_bf16 v[124:127], v[154:157], v[194:197], 0
	v_mfma_f32_16x16x32_bf16 v[120:123], v[170:173], v[194:197], 0
	v_mfma_f32_16x16x32_bf16 v[108:111], v[154:157], v[202:205], 0
	v_mfma_f32_16x16x32_bf16 v[104:107], v[170:173], v[202:205], 0
	v_mfma_f32_16x16x32_bf16 v[92:95], v[154:157], v[210:213], 0
	v_mfma_f32_16x16x32_bf16 v[88:91], v[170:173], v[210:213], 0
	v_mfma_f32_16x16x32_bf16 v[76:79], v[154:157], v[218:221], 0
	v_mfma_f32_16x16x32_bf16 v[72:75], v[170:173], v[218:221], 0
	v_mfma_f32_16x16x32_bf16 v[124:127], v[158:161], v[198:201], v[124:127]
	v_mfma_f32_16x16x32_bf16 v[120:123], v[174:177], v[198:201], v[120:123]
	v_mfma_f32_16x16x32_bf16 v[108:111], v[158:161], v[206:209], v[108:111]
	v_mfma_f32_16x16x32_bf16 v[104:107], v[174:177], v[206:209], v[104:107]
	v_mfma_f32_16x16x32_bf16 v[92:95], v[158:161], v[214:217], v[92:95]
	v_mfma_f32_16x16x32_bf16 v[88:91], v[174:177], v[214:217], v[88:91]
	v_mfma_f32_16x16x32_bf16 v[76:79], v[158:161], v[222:225], v[76:79]
	v_mfma_f32_16x16x32_bf16 v[72:75], v[174:177], v[222:225], v[72:75]
	s_setprio 0
	s_setprio 1
	v_mfma_f32_16x16x32_bf16 v[116:119], v[178:181], v[194:197], 0
	v_mfma_f32_16x16x32_bf16 v[112:115], v[186:189], v[194:197], 0
	v_mfma_f32_16x16x32_bf16 v[100:103], v[178:181], v[202:205], 0
	v_mfma_f32_16x16x32_bf16 v[96:99], v[186:189], v[202:205], 0
	v_mfma_f32_16x16x32_bf16 v[84:87], v[178:181], v[210:213], 0
	v_mfma_f32_16x16x32_bf16 v[80:83], v[186:189], v[210:213], 0
	v_mfma_f32_16x16x32_bf16 v[68:71], v[178:181], v[218:221], 0
	v_mfma_f32_16x16x32_bf16 v[64:67], v[186:189], v[218:221], 0
	v_mfma_f32_16x16x32_bf16 v[116:119], v[182:185], v[198:201], v[116:119]
	v_mfma_f32_16x16x32_bf16 v[112:115], v[190:193], v[198:201], v[112:115]
	v_mfma_f32_16x16x32_bf16 v[100:103], v[182:185], v[206:209], v[100:103]
	v_mfma_f32_16x16x32_bf16 v[96:99], v[190:193], v[206:209], v[96:99]
	v_mfma_f32_16x16x32_bf16 v[84:87], v[182:185], v[214:217], v[84:87]
	v_mfma_f32_16x16x32_bf16 v[80:83], v[190:193], v[214:217], v[80:83]
	v_mfma_f32_16x16x32_bf16 v[68:71], v[182:185], v[222:225], v[68:71]
	v_mfma_f32_16x16x32_bf16 v[64:67], v[190:193], v[222:225], v[64:67]
	s_setprio 0
	s_barrier
	s_add_i32 s56, s46, s36
	v_lshl_add_u64 v[162:163], s[20:21], 0, v[130:131]
	s_mov_b32 m0, s56
	ds_read_b128 v[194:197], v152 offset:16384
	ds_read_b128 v[198:201], v152 offset:17408
	ds_read_b128 v[202:205], v152 offset:18432
	ds_read_b128 v[206:209], v152 offset:19456
	ds_read_b128 v[210:213], v152 offset:20480
	ds_read_b128 v[214:217], v152 offset:21504
	ds_read_b128 v[218:221], v152 offset:22528
	ds_read_b128 v[222:225], v152 offset:23552
	global_load_lds_dwordx4 v[162:163], off
	s_add_i32 m0, s56, 0x2000
	s_add_u32 s56, s20, 0x164000
	v_lshl_add_u64 v[166:167], s[20:21], 0, v[134:135]
	s_addc_u32 s57, s21, 0
	s_add_i32 s58, s47, s36
	global_load_lds_dwordx4 v[166:167], off
	v_lshl_add_u64 v[226:227], s[56:57], 0, v[130:131]
	s_mov_b32 m0, s58
	v_lshl_add_u64 v[228:229], s[22:23], 0, v[132:133]
	global_load_lds_dwordx4 v[226:227], off
	v_lshl_add_u64 v[226:227], s[56:57], 0, v[134:135]
	s_add_i32 m0, s58, 0x2000
	s_nop 0
	global_load_lds_dwordx4 v[226:227], off
	v_lshl_add_u64 v[226:227], s[22:23], 0, v[128:129]
	s_mov_b32 m0, s37
	s_nop 0
	global_load_lds_dwordx4 v[226:227], off
	s_mov_b32 m0, s38
	s_nop 0
	global_load_lds_dwordx4 v[228:229], off
	s_waitcnt vmcnt(8)
	s_waitcnt lgkmcnt(0)
	s_barrier
; #define PG8_STAGE(bufoff, gbase, voff) do { _Pragma("unroll") for (int _i = 0; _i < 2; ++_i) \
;         __builtin_amdgcn_global_load_lds((const unsigned*)((const char*)(gbase) + (voff)[_i]), (LAS unsigned*)(lds + (bufoff) + ldsw + _i * 8192), 16, 0, 0); } while (0)
; #define PG8_LDA(dst, b, h) do { _Pragma("unroll") for (int m = 0; m < 4; ++m) _Pragma("unroll") for (int k = 0; k < 2; ++k) dst[m][k] = *(const LAS bf16x8*)(lds + PG8_SA(b, h) + aoff + m * 2048 + k * 1024); } while (0)
; #define PG8_LDB(dst, b, h) do { _Pragma("unroll") for (int n = 0; n < 2; ++n) _Pragma("unroll") for (int k = 0; k < 2; ++k) dst[n][k] = *(const LAS bf16x8*)(lds + PG8_SB(b, h) + boff + n * 2048 + k * 1024); } while (0)
; #define PG8_MMA(ai, bj, At, Bt) do { __builtin_amdgcn_s_setprio(1); _Pragma("unroll") for (int m = 0; m < 4; ++m) _Pragma("unroll") for (int n = 0; n < 2; ++n) _Pragma("unroll") for (int k = 0; k < 2; ++k) \
;         acc[ai][bj][m][n] = __builtin_amdgcn_mfma_f32_16x16x32_bf16(Bt[n][k], At[m][k], acc[ai][bj][m][n], 0, 0, 0); __builtin_amdgcn_s_setprio(0); } while (0)
; #define PG8_WAIT_V(n) asm volatile("s_waitcnt vmcnt(" #n ")" ::: "memory")
; #define PG8_WAIT_L(n) asm volatile("s_waitcnt lgkmcnt(" #n ")" ::: "memory")
; #define PG8_BAR __builtin_amdgcn_s_barrier()
; #define PG8_SCHED __builtin_amdgcn_sched_barrier(0)
; template <class EpiT>
; __device__ __forceinline__ void gemm_phase(LAS unsigned char* lds, const Gemm g, const StaticOrder& S, const EpiT& E) {
;     ...
;             PG8_WAIT_V(8); PG8_WAIT_L(0); PG8_BAR; PG8_MMA(1, 0, At, B0); PG8_MMA(1, 1, At, B1); PG8_BAR; PG8_SCHED;
;             PG8_LDB(B0, 1, 0); PG8_LDB(B1, 1, 1); PG8_SCHED; PG8_LDA(At, 1, 0); PG8_STAGE(PG8_SA(0, 1), a2 + hstepA, voffA);
;             PG8_WAIT_V(8); PG8_WAIT_L(0); PG8_BAR; PG8_MMA(0, 0, At, B0); PG8_MMA(0, 1, At, B1); PG8_BAR; PG8_SCHED;
	s_setprio 1
	s_waitcnt lgkmcnt(0)
	v_mfma_f32_16x16x32_bf16 v[60:63], v[154:157], v[194:197], 0
	v_mfma_f32_16x16x32_bf16 v[56:59], v[170:173], v[194:197], 0
	v_mfma_f32_16x16x32_bf16 v[44:47], v[154:157], v[202:205], 0
	v_mfma_f32_16x16x32_bf16 v[40:43], v[170:173], v[202:205], 0
	v_mfma_f32_16x16x32_bf16 v[28:31], v[154:157], v[210:213], 0
	v_mfma_f32_16x16x32_bf16 v[24:27], v[170:173], v[210:213], 0
	v_mfma_f32_16x16x32_bf16 v[12:15], v[154:157], v[218:221], 0
	v_mfma_f32_16x16x32_bf16 v[8:11], v[170:173], v[218:221], 0
	v_mfma_f32_16x16x32_bf16 v[60:63], v[158:161], v[198:201], v[60:63]
	v_mfma_f32_16x16x32_bf16 v[56:59], v[174:177], v[198:201], v[56:59]
	v_mfma_f32_16x16x32_bf16 v[44:47], v[158:161], v[206:209], v[44:47]
	v_mfma_f32_16x16x32_bf16 v[40:43], v[174:177], v[206:209], v[40:43]
	v_mfma_f32_16x16x32_bf16 v[28:31], v[158:161], v[214:217], v[28:31]
	v_mfma_f32_16x16x32_bf16 v[24:27], v[174:177], v[214:217], v[24:27]
	v_mfma_f32_16x16x32_bf16 v[12:15], v[158:161], v[222:225], v[12:15]
	v_mfma_f32_16x16x32_bf16 v[8:11], v[174:177], v[222:225], v[8:11]
	s_setprio 0
	s_setprio 1
	v_mfma_f32_16x16x32_bf16 v[52:55], v[178:181], v[194:197], 0
	v_mfma_f32_16x16x32_bf16 v[48:51], v[186:189], v[194:197], 0
	v_mfma_f32_16x16x32_bf16 v[36:39], v[178:181], v[202:205], 0
	v_mfma_f32_16x16x32_bf16 v[32:35], v[186:189], v[202:205], 0
	v_mfma_f32_16x16x32_bf16 v[20:23], v[178:181], v[210:213], 0
	v_mfma_f32_16x16x32_bf16 v[16:19], v[186:189], v[210:213], 0
	v_mfma_f32_16x16x32_bf16 v[4:7], v[178:181], v[218:221], 0
	v_mfma_f32_16x16x32_bf16 v[0:3], v[186:189], v[218:221], 0
	v_mfma_f32_16x16x32_bf16 v[52:55], v[182:185], v[198:201], v[52:55]
	v_mfma_f32_16x16x32_bf16 v[48:51], v[190:193], v[198:201], v[48:51]
	v_mfma_f32_16x16x32_bf16 v[36:39], v[182:185], v[206:209], v[36:39]
	v_mfma_f32_16x16x32_bf16 v[32:35], v[190:193], v[206:209], v[32:35]
	v_mfma_f32_16x16x32_bf16 v[20:23], v[182:185], v[214:217], v[20:23]
	v_mfma_f32_16x16x32_bf16 v[16:19], v[190:193], v[214:217], v[16:19]
	v_mfma_f32_16x16x32_bf16 v[4:7], v[182:185], v[222:225], v[4:7]
	v_mfma_f32_16x16x32_bf16 v[0:3], v[190:193], v[222:225], v[0:3]
	s_setprio 0
	s_barrier
	s_add_i32 s56, 0, 0x18000
	v_add_u32_e32 v165, s56, v146
	s_add_i32 s57, 0, 0x1c000
	ds_read_b128 v[154:157], v165
	ds_read_b128 v[158:161], v165 offset:1024
	ds_read_b128 v[170:173], v165 offset:2048
	ds_read_b128 v[174:177], v165 offset:3072
	v_add_u32_e32 v165, s57, v146
	ds_read_b128 v[178:181], v165
	ds_read_b128 v[182:185], v165 offset:1024
	ds_read_b128 v[186:189], v165 offset:2048
	ds_read_b128 v[190:193], v165 offset:3072
	s_add_u32 s22, s22, 0x164000
	s_addc_u32 s23, s23, 0
	s_mov_b32 m0, s39
	v_lshl_add_u64 v[230:231], s[22:23], 0, v[128:129]
	ds_read_b128 v[194:197], v152 offset:32768
	ds_read_b128 v[198:201], v152 offset:33792
	ds_read_b128 v[202:205], v152 offset:34816
	ds_read_b128 v[206:209], v152 offset:35840
	ds_read_b128 v[210:213], v152 offset:36864
	ds_read_b128 v[214:217], v152 offset:37888
	ds_read_b128 v[218:221], v152 offset:38912
	ds_read_b128 v[222:225], v152 offset:39936
	global_load_lds_dwordx4 v[230:231], off
	v_lshl_add_u64 v[230:231], s[22:23], 0, v[132:133]
	s_mov_b32 m0, s40
	s_nop 0
	global_load_lds_dwordx4 v[230:231], off
	s_waitcnt vmcnt(8)
	s_waitcnt lgkmcnt(0)
	s_barrier
	s_setprio 1
	s_waitcnt lgkmcnt(0)
	v_mfma_f32_16x16x32_bf16 v[124:127], v[154:157], v[194:197], v[124:127]
	v_mfma_f32_16x16x32_bf16 v[120:123], v[170:173], v[194:197], v[120:123]
	v_mfma_f32_16x16x32_bf16 v[108:111], v[154:157], v[202:205], v[108:111]
	v_mfma_f32_16x16x32_bf16 v[104:107], v[170:173], v[202:205], v[104:107]
	v_mfma_f32_16x16x32_bf16 v[92:95], v[154:157], v[210:213], v[92:95]
	v_mfma_f32_16x16x32_bf16 v[88:91], v[170:173], v[210:213], v[88:91]
	v_mfma_f32_16x16x32_bf16 v[76:79], v[154:157], v[218:221], v[76:79]
	v_mfma_f32_16x16x32_bf16 v[72:75], v[170:173], v[218:221], v[72:75]
	v_mfma_f32_16x16x32_bf16 v[124:127], v[158:161], v[198:201], v[124:127]
	v_mfma_f32_16x16x32_bf16 v[120:123], v[174:177], v[198:201], v[120:123]
	v_mfma_f32_16x16x32_bf16 v[108:111], v[158:161], v[206:209], v[108:111]
	v_mfma_f32_16x16x32_bf16 v[104:107], v[174:177], v[206:209], v[104:107]
	v_mfma_f32_16x16x32_bf16 v[92:95], v[158:161], v[214:217], v[92:95]
	v_mfma_f32_16x16x32_bf16 v[88:91], v[174:177], v[214:217], v[88:91]
	v_mfma_f32_16x16x32_bf16 v[76:79], v[158:161], v[222:225], v[76:79]
	v_mfma_f32_16x16x32_bf16 v[72:75], v[174:177], v[222:225], v[72:75]
	s_setprio 0
	s_setprio 1
	v_mfma_f32_16x16x32_bf16 v[116:119], v[178:181], v[194:197], v[116:119]
	v_mfma_f32_16x16x32_bf16 v[112:115], v[186:189], v[194:197], v[112:115]
	v_mfma_f32_16x16x32_bf16 v[100:103], v[178:181], v[202:205], v[100:103]
	v_mfma_f32_16x16x32_bf16 v[96:99], v[186:189], v[202:205], v[96:99]
	v_mfma_f32_16x16x32_bf16 v[84:87], v[178:181], v[210:213], v[84:87]
	v_mfma_f32_16x16x32_bf16 v[80:83], v[186:189], v[210:213], v[80:83]
	v_mfma_f32_16x16x32_bf16 v[68:71], v[178:181], v[218:221], v[68:71]
	v_mfma_f32_16x16x32_bf16 v[64:67], v[186:189], v[218:221], v[64:67]
	v_mfma_f32_16x16x32_bf16 v[116:119], v[182:185], v[198:201], v[116:119]
	v_mfma_f32_16x16x32_bf16 v[112:115], v[190:193], v[198:201], v[112:115]
	v_mfma_f32_16x16x32_bf16 v[100:103], v[182:185], v[206:209], v[100:103]
	v_mfma_f32_16x16x32_bf16 v[96:99], v[190:193], v[206:209], v[96:99]
	v_mfma_f32_16x16x32_bf16 v[84:87], v[182:185], v[214:217], v[84:87]
	v_mfma_f32_16x16x32_bf16 v[80:83], v[190:193], v[214:217], v[80:83]
	v_mfma_f32_16x16x32_bf16 v[68:71], v[182:185], v[222:225], v[68:71]
	v_mfma_f32_16x16x32_bf16 v[64:67], v[190:193], v[222:225], v[64:67]
	s_setprio 0
	s_barrier
; #define PG8_STAGE(bufoff, gbase, voff) do { _Pragma("unroll") for (int _i = 0; _i < 2; ++_i) \
;         __builtin_amdgcn_global_load_lds((const unsigned*)((const char*)(gbase) + (voff)[_i]), (LAS unsigned*)(lds + (bufoff) + ldsw + _i * 8192), 16, 0, 0); } while (0)
; #define PG8_LDA(dst, b, h) do { _Pragma("unroll") for (int m = 0; m < 4; ++m) _Pragma("unroll") for (int k = 0; k < 2; ++k) dst[m][k] = *(const LAS bf16x8*)(lds + PG8_SA(b, h) + aoff + m * 2048 + k * 1024); } while (0)
; #define PG8_MMA(ai, bj, At, Bt) do { __builtin_amdgcn_s_setprio(1); _Pragma("unroll") for (int m = 0; m < 4; ++m) _Pragma("unroll") for (int n = 0; n < 2; ++n) _Pragma("unroll") for (int k = 0; k < 2; ++k) \
;         acc[ai][bj][m][n] = __builtin_amdgcn_mfma_f32_16x16x32_bf16(Bt[n][k], At[m][k], acc[ai][bj][m][n], 0, 0, 0); __builtin_amdgcn_s_setprio(0); } while (0)
; #define PG8_WAIT_V(n) asm volatile("s_waitcnt vmcnt(" #n ")" ::: "memory")
; #define PG8_WAIT_L(n) asm volatile("s_waitcnt lgkmcnt(" #n ")" ::: "memory")
; #define PG8_BAR __builtin_amdgcn_s_barrier()
; #define PG8_SCHED __builtin_amdgcn_sched_barrier(0)
; template <class EpiT>
; __device__ __forceinline__ void gemm_phase(LAS unsigned char* lds, const Gemm g, const StaticOrder& S, const EpiT& E) {
;     ...
;         for (int t = 0; t < nt; t += 2) {
;             const bool last = (t == nt - 2);
;     ...
;             PG8_LDA(At, 1, 1); PG8_STAGE(PG8_SB(1, 0), b3, voffB); PG8_STAGE(PG8_SB(1, 1), b3 + hstepB, voffB); PG8_STAGE(PG8_SA(1, 0), a3, voffA);
;             PG8_WAIT_V(8); PG8_WAIT_L(0); PG8_BAR; PG8_MMA(1, 0, At, B0); PG8_MMA(1, 1, At, B1); PG8_BAR; PG8_SCHED;
	s_add_i32 s22, s56, s36
	v_lshl_add_u64 v[162:163], v[162:163], 0, s[12:13]
	s_mov_b32 m0, s22
	ds_read_b128 v[194:197], v152 offset:49152
	ds_read_b128 v[198:201], v152 offset:50176
	ds_read_b128 v[202:205], v152 offset:51200
	ds_read_b128 v[206:209], v152 offset:52224
	ds_read_b128 v[210:213], v152 offset:53248
	ds_read_b128 v[214:217], v152 offset:54272
	ds_read_b128 v[218:221], v152 offset:55296
	ds_read_b128 v[222:225], v152 offset:56320
	global_load_lds_dwordx4 v[162:163], off
	s_add_i32 m0, s22, 0x2000
	s_add_u32 s20, s20, 0x164080
	v_lshl_add_u64 v[162:163], v[166:167], 0, s[12:13]
	s_addc_u32 s21, s21, 0
	s_add_i32 s22, s57, s36
	global_load_lds_dwordx4 v[162:163], off
	v_lshl_add_u64 v[162:163], s[20:21], 0, v[130:131]
	s_mov_b32 m0, s22
	s_nop 0
	global_load_lds_dwordx4 v[162:163], off
	v_lshl_add_u64 v[162:163], s[20:21], 0, v[134:135]
	s_add_i32 m0, s22, 0x2000
	s_nop 0
	global_load_lds_dwordx4 v[162:163], off
	v_lshl_add_u64 v[162:163], v[226:227], 0, s[12:13]
	s_mov_b32 m0, s42
	s_nop 0
	global_load_lds_dwordx4 v[162:163], off
	v_lshl_add_u64 v[162:163], v[228:229], 0, s[12:13]
	s_mov_b32 m0, s43
	s_nop 0
	global_load_lds_dwordx4 v[162:163], off
	s_waitcnt vmcnt(8)
	s_waitcnt lgkmcnt(0)
	s_barrier
	s_setprio 1
	s_waitcnt lgkmcnt(0)
	v_mfma_f32_16x16x32_bf16 v[60:63], v[154:157], v[194:197], v[60:63]
	v_mfma_f32_16x16x32_bf16 v[56:59], v[170:173], v[194:197], v[56:59]
	v_mfma_f32_16x16x32_bf16 v[44:47], v[154:157], v[202:205], v[44:47]
	v_mfma_f32_16x16x32_bf16 v[40:43], v[170:173], v[202:205], v[40:43]
	v_mfma_f32_16x16x32_bf16 v[28:31], v[154:157], v[210:213], v[28:31]
	v_mfma_f32_16x16x32_bf16 v[24:27], v[170:173], v[210:213], v[24:27]
	v_mfma_f32_16x16x32_bf16 v[12:15], v[154:157], v[218:221], v[12:15]
	v_mfma_f32_16x16x32_bf16 v[8:11], v[170:173], v[218:221], v[8:11]
	v_mfma_f32_16x16x32_bf16 v[60:63], v[158:161], v[198:201], v[60:63]
	v_mfma_f32_16x16x32_bf16 v[56:59], v[174:177], v[198:201], v[56:59]
	v_mfma_f32_16x16x32_bf16 v[44:47], v[158:161], v[206:209], v[44:47]
	v_mfma_f32_16x16x32_bf16 v[40:43], v[174:177], v[206:209], v[40:43]
	v_mfma_f32_16x16x32_bf16 v[28:31], v[158:161], v[214:217], v[28:31]
	v_mfma_f32_16x16x32_bf16 v[24:27], v[174:177], v[214:217], v[24:27]
	v_mfma_f32_16x16x32_bf16 v[12:15], v[158:161], v[222:225], v[12:15]
	v_mfma_f32_16x16x32_bf16 v[8:11], v[174:177], v[222:225], v[8:11]
	s_setprio 0
	s_setprio 1
	v_mfma_f32_16x16x32_bf16 v[52:55], v[178:181], v[194:197], v[52:55]
	v_mfma_f32_16x16x32_bf16 v[48:51], v[186:189], v[194:197], v[48:51]
	v_mfma_f32_16x16x32_bf16 v[36:39], v[178:181], v[202:205], v[36:39]
	v_mfma_f32_16x16x32_bf16 v[32:35], v[186:189], v[202:205], v[32:35]
	v_mfma_f32_16x16x32_bf16 v[20:23], v[178:181], v[210:213], v[20:23]
	v_mfma_f32_16x16x32_bf16 v[16:19], v[186:189], v[210:213], v[16:19]
	v_mfma_f32_16x16x32_bf16 v[4:7], v[178:181], v[218:221], v[4:7]
	v_mfma_f32_16x16x32_bf16 v[0:3], v[186:189], v[218:221], v[0:3]
	v_mfma_f32_16x16x32_bf16 v[52:55], v[182:185], v[198:201], v[52:55]
	v_mfma_f32_16x16x32_bf16 v[48:51], v[190:193], v[198:201], v[48:51]
	v_mfma_f32_16x16x32_bf16 v[36:39], v[182:185], v[206:209], v[36:39]
	v_mfma_f32_16x16x32_bf16 v[32:35], v[190:193], v[206:209], v[32:35]
	v_mfma_f32_16x16x32_bf16 v[20:23], v[182:185], v[214:217], v[20:23]
	v_mfma_f32_16x16x32_bf16 v[16:19], v[190:193], v[214:217], v[16:19]
	v_mfma_f32_16x16x32_bf16 v[4:7], v[182:185], v[222:225], v[4:7]
	v_mfma_f32_16x16x32_bf16 v[0:3], v[190:193], v[222:225], v[0:3]
	s_setprio 0
	s_barrier
	s_add_i32 s55, s55, 2
	s_add_u32 s18, s18, 0x100
	s_addc_u32 s19, s19, 0
	s_add_u32 s53, s53, 0x100
	s_addc_u32 s54, s54, 0
	s_cmpk_gt_u32 s55, 0x55
	s_cbranch_scc1 .Lpeel_done_595
	.p2alignl 6, 3212836864
	s_nop 0
	s_nop 0

; #define PG8_STAGE(bufoff, gbase, voff) do { _Pragma("unroll") for (int _i = 0; _i < 2; ++_i) \
;         __builtin_amdgcn_global_load_lds((const unsigned*)((const char*)(gbase) + (voff)[_i]), (LAS unsigned*)(lds + (bufoff) + ldsw + _i * 8192), 16, 0, 0); } while (0)
; #define PG8_LDA(dst, b, h) do { _Pragma("unroll") for (int m = 0; m < 4; ++m) _Pragma("unroll") for (int k = 0; k < 2; ++k) dst[m][k] = *(const LAS bf16x8*)(lds + PG8_SA(b, h) + aoff + m * 2048 + k * 1024); } while (0)
; #define PG8_LDB(dst, b, h) do { _Pragma("unroll") for (int n = 0; n < 2; ++n) _Pragma("unroll") for (int k = 0; k < 2; ++k) dst[n][k] = *(const LAS bf16x8*)(lds + PG8_SB(b, h) + boff + n * 2048 + k * 1024); } while (0)
; #define PG8_WAIT_V(n) asm volatile("s_waitcnt vmcnt(" #n ")" ::: "memory")
; #define PG8_WAIT_L(n) asm volatile("s_waitcnt lgkmcnt(" #n ")" ::: "memory")
; template <class EpiT>
; __device__ __forceinline__ void gemm_phase(LAS unsigned char* lds, const Gemm g, const StaticOrder& S, const EpiT& E) {
;     ...
;         const char* nA = has_next ? (const char*)g.A + (size_t)nxt.pm * tstepA + (size_t)nxt.pn * g.a_koff * 2 : cA; const char* nB = has_next ? (const char*)g.Bt + (size_t)nxt.pn * tstepB : cB;
;         for (int t = 0; t < nt; t += 2) {
;             const bool last = (t == nt - 2);
;             const char* a1 = cA + (size_t)(t + 1) * kstep;
;             const char* a2 = last ? nA : cA + (size_t)(t + 2) * kstep; const char* b2 = last ? nB : cB + (size_t)(t + 2) * kstep;
;             const char* a3 = a2 + kstep; const char* b3 = b2 + kstep;
;             PG8_LDB(B0, 0, 0); PG8_LDB(B1, 0, 1); PG8_SCHED; PG8_LDA(At, 0, 0); PG8_STAGE(PG8_SA(1, 1), a1 + hstepA, voffA);
;             PG8_WAIT_V(8); PG8_WAIT_L(0); PG8_BAR; PG8_MMA(0, 0, At, B0); PG8_MMA(0, 1, At, B1); PG8_BAR; PG8_SCHED;
;             PG8_LDA(At, 0, 1); PG8_STAGE(PG8_SB(0, 0), b2, voffB); PG8_STAGE(PG8_SB(0, 1), b2 + hstepB, voffB); PG8_STAGE(PG8_SA(0, 0), a2, voffA);
;             PG8_WAIT_V(8); PG8_WAIT_L(0); PG8_BAR; PG8_MMA(1, 0, At, B0); PG8_MMA(1, 1, At, B1); PG8_BAR; PG8_SCHED;
;     ...
; #pragma unroll
;         for (int a = 0; a < 2; ++a)
; #pragma unroll
;             for (int b = 0; b < 2; ++b)
; #pragma unroll
;                 for (int m = 0; m < 4; ++m)
; #pragma unroll
;                     for (int n = 0; n < 2; ++n) acc[a][b][m][n] = (f32x4){0.f, 0.f, 0.f, 0.f};
.LBB0_760:
	s_add_u32 s20, s20, 0x84080
	s_addc_u32 s21, s21, 0
	s_add_u32 s8, s22, 0x100
	s_addc_u32 s39, s23, 0
	s_mov_b32 s56, -2
	s_waitcnt lgkmcnt(0)
	ds_read_b128 v[156:159], v160
	ds_read_b128 v[164:167], v160 offset:1024
	ds_read_b128 v[170:173], v160 offset:2048
	ds_read_b128 v[174:177], v160 offset:3072
	ds_read_b128 v[178:181], v161
	ds_read_b128 v[182:185], v161 offset:1024
	ds_read_b128 v[186:189], v161 offset:2048
	ds_read_b128 v[190:193], v161 offset:3072
	s_add_u32 s22, s20, 0xfff7c080
	s_addc_u32 s23, s21, -1
	s_cmp_eq_u32 s56, 28
	s_cselect_b32 s25, s5, s23
	s_cselect_b32 s24, s4, s22
	s_cselect_b32 s23, s19, s39
	s_cselect_b32 s22, s18, s8
	v_lshl_add_u64 v[226:227], s[20:21], 0, v[146:147]
	s_add_i32 m0, s40, 0xc000
	ds_read_b128 v[194:197], v162
	ds_read_b128 v[198:201], v162 offset:1024
	ds_read_b128 v[202:205], v162 offset:2048
	ds_read_b128 v[206:209], v162 offset:3072
	ds_read_b128 v[210:213], v162 offset:4096
	ds_read_b128 v[214:217], v162 offset:5120
	ds_read_b128 v[218:221], v162 offset:6144
	ds_read_b128 v[222:225], v162 offset:7168
	global_load_lds_dwordx4 v[226:227], off
	v_lshl_add_u64 v[226:227], s[20:21], 0, v[150:151]
	s_add_i32 m0, s40, 0xe000
	s_nop 0
	global_load_lds_dwordx4 v[226:227], off
	s_waitcnt vmcnt(8)
	s_waitcnt lgkmcnt(0)
	s_barrier
	s_setprio 1
	s_waitcnt lgkmcnt(0)
	v_mfma_f32_16x16x32_bf16 v[124:127], v[156:159], v[194:197], 0
	v_mfma_f32_16x16x32_bf16 v[120:123], v[170:173], v[194:197], 0
	v_mfma_f32_16x16x32_bf16 v[108:111], v[156:159], v[202:205], 0
	v_mfma_f32_16x16x32_bf16 v[104:107], v[170:173], v[202:205], 0
	v_mfma_f32_16x16x32_bf16 v[92:95], v[156:159], v[210:213], 0
	v_mfma_f32_16x16x32_bf16 v[88:91], v[170:173], v[210:213], 0
	v_mfma_f32_16x16x32_bf16 v[76:79], v[156:159], v[218:221], 0
	v_mfma_f32_16x16x32_bf16 v[72:75], v[170:173], v[218:221], 0
	v_mfma_f32_16x16x32_bf16 v[124:127], v[164:167], v[198:201], v[124:127]
	v_mfma_f32_16x16x32_bf16 v[120:123], v[174:177], v[198:201], v[120:123]
	v_mfma_f32_16x16x32_bf16 v[108:111], v[164:167], v[206:209], v[108:111]
	v_mfma_f32_16x16x32_bf16 v[104:107], v[174:177], v[206:209], v[104:107]
	v_mfma_f32_16x16x32_bf16 v[92:95], v[164:167], v[214:217], v[92:95]
	v_mfma_f32_16x16x32_bf16 v[88:91], v[174:177], v[214:217], v[88:91]
	v_mfma_f32_16x16x32_bf16 v[76:79], v[164:167], v[222:225], v[76:79]
	v_mfma_f32_16x16x32_bf16 v[72:75], v[174:177], v[222:225], v[72:75]
	s_setprio 0
	s_setprio 1
	v_mfma_f32_16x16x32_bf16 v[116:119], v[178:181], v[194:197], 0
	v_mfma_f32_16x16x32_bf16 v[112:115], v[186:189], v[194:197], 0
	v_mfma_f32_16x16x32_bf16 v[100:103], v[178:181], v[202:205], 0
	v_mfma_f32_16x16x32_bf16 v[96:99], v[186:189], v[202:205], 0
	v_mfma_f32_16x16x32_bf16 v[84:87], v[178:181], v[210:213], 0
	v_mfma_f32_16x16x32_bf16 v[80:83], v[186:189], v[210:213], 0
	v_mfma_f32_16x16x32_bf16 v[68:71], v[178:181], v[218:221], 0
	v_mfma_f32_16x16x32_bf16 v[64:67], v[186:189], v[218:221], 0
	v_mfma_f32_16x16x32_bf16 v[116:119], v[182:185], v[198:201], v[116:119]
	v_mfma_f32_16x16x32_bf16 v[112:115], v[190:193], v[198:201], v[112:115]
	v_mfma_f32_16x16x32_bf16 v[100:103], v[182:185], v[206:209], v[100:103]
	v_mfma_f32_16x16x32_bf16 v[96:99], v[190:193], v[206:209], v[96:99]
	v_mfma_f32_16x16x32_bf16 v[84:87], v[182:185], v[214:217], v[84:87]
	v_mfma_f32_16x16x32_bf16 v[80:83], v[190:193], v[214:217], v[80:83]
	v_mfma_f32_16x16x32_bf16 v[68:71], v[182:185], v[222:225], v[68:71]
	v_mfma_f32_16x16x32_bf16 v[64:67], v[190:193], v[222:225], v[64:67]
	s_setprio 0
	s_barrier
	s_add_i32 s57, s49, s37
	v_lshl_add_u64 v[226:227], s[22:23], 0, v[130:131]
	s_mov_b32 m0, s57
	ds_read_b128 v[194:197], v162 offset:16384
	ds_read_b128 v[198:201], v162 offset:17408
	ds_read_b128 v[202:205], v162 offset:18432
	ds_read_b128 v[206:209], v162 offset:19456
	ds_read_b128 v[210:213], v162 offset:20480
	ds_read_b128 v[214:217], v162 offset:21504
	ds_read_b128 v[218:221], v162 offset:22528
	ds_read_b128 v[222:225], v162 offset:23552
	global_load_lds_dwordx4 v[226:227], off
	s_add_i32 m0, s57, 0x2000
	s_add_u32 s58, s22, 0x84000
	v_lshl_add_u64 v[228:229], s[22:23], 0, v[134:135]
	s_addc_u32 s59, s23, 0
	s_add_i32 s57, s50, s37
	global_load_lds_dwordx4 v[228:229], off
	v_lshl_add_u64 v[230:231], s[58:59], 0, v[130:131]
	s_mov_b32 m0, s57
	v_lshl_add_u64 v[232:233], s[24:25], 0, v[132:133]
	global_load_lds_dwordx4 v[230:231], off
	v_lshl_add_u64 v[230:231], s[58:59], 0, v[134:135]
	s_add_i32 m0, s57, 0x2000
	s_nop 0
	global_load_lds_dwordx4 v[230:231], off
	v_lshl_add_u64 v[230:231], s[24:25], 0, v[128:129]
	s_mov_b32 m0, s40
	s_nop 0
	global_load_lds_dwordx4 v[230:231], off
	s_mov_b32 m0, s41
	s_nop 0
	global_load_lds_dwordx4 v[232:233], off
	s_waitcnt vmcnt(8)
	s_waitcnt lgkmcnt(0)
	s_barrier
; #define PG8_STAGE(bufoff, gbase, voff) do { _Pragma("unroll") for (int _i = 0; _i < 2; ++_i) \
;         __builtin_amdgcn_global_load_lds((const unsigned*)((const char*)(gbase) + (voff)[_i]), (LAS unsigned*)(lds + (bufoff) + ldsw + _i * 8192), 16, 0, 0); } while (0)
; #define PG8_LDA(dst, b, h) do { _Pragma("unroll") for (int m = 0; m < 4; ++m) _Pragma("unroll") for (int k = 0; k < 2; ++k) dst[m][k] = *(const LAS bf16x8*)(lds + PG8_SA(b, h) + aoff + m * 2048 + k * 1024); } while (0)
; #define PG8_LDB(dst, b, h) do { _Pragma("unroll") for (int n = 0; n < 2; ++n) _Pragma("unroll") for (int k = 0; k < 2; ++k) dst[n][k] = *(const LAS bf16x8*)(lds + PG8_SB(b, h) + boff + n * 2048 + k * 1024); } while (0)
; #define PG8_MMA(ai, bj, At, Bt) do { __builtin_amdgcn_s_setprio(1); _Pragma("unroll") for (int m = 0; m < 4; ++m) _Pragma("unroll") for (int n = 0; n < 2; ++n) _Pragma("unroll") for (int k = 0; k < 2; ++k) \
;         acc[ai][bj][m][n] = __builtin_amdgcn_mfma_f32_16x16x32_bf16(Bt[n][k], At[m][k], acc[ai][bj][m][n], 0, 0, 0); __builtin_amdgcn_s_setprio(0); } while (0)
; #define PG8_WAIT_V(n) asm volatile("s_waitcnt vmcnt(" #n ")" ::: "memory")
; #define PG8_WAIT_L(n) asm volatile("s_waitcnt lgkmcnt(" #n ")" ::: "memory")
; #define PG8_BAR __builtin_amdgcn_s_barrier()
; #define PG8_SCHED __builtin_amdgcn_sched_barrier(0)
; template <class EpiT>
; __device__ __forceinline__ void gemm_phase(LAS unsigned char* lds, const Gemm g, const StaticOrder& S, const EpiT& E) {
;     ...
;             PG8_WAIT_V(8); PG8_WAIT_L(0); PG8_BAR; PG8_MMA(1, 0, At, B0); PG8_MMA(1, 1, At, B1); PG8_BAR; PG8_SCHED;
;             PG8_LDB(B0, 1, 0); PG8_LDB(B1, 1, 1); PG8_SCHED; PG8_LDA(At, 1, 0); PG8_STAGE(PG8_SA(0, 1), a2 + hstepA, voffA);
;             PG8_WAIT_V(8); PG8_WAIT_L(0); PG8_BAR; PG8_MMA(0, 0, At, B0); PG8_MMA(0, 1, At, B1); PG8_BAR; PG8_SCHED;
	s_setprio 1
	s_waitcnt lgkmcnt(0)
	v_mfma_f32_16x16x32_bf16 v[60:63], v[156:159], v[194:197], 0
	v_mfma_f32_16x16x32_bf16 v[56:59], v[170:173], v[194:197], 0
	v_mfma_f32_16x16x32_bf16 v[44:47], v[156:159], v[202:205], 0
	v_mfma_f32_16x16x32_bf16 v[40:43], v[170:173], v[202:205], 0
	v_mfma_f32_16x16x32_bf16 v[28:31], v[156:159], v[210:213], 0
	v_mfma_f32_16x16x32_bf16 v[24:27], v[170:173], v[210:213], 0
	v_mfma_f32_16x16x32_bf16 v[12:15], v[156:159], v[218:221], 0
	v_mfma_f32_16x16x32_bf16 v[8:11], v[170:173], v[218:221], 0
	v_mfma_f32_16x16x32_bf16 v[60:63], v[164:167], v[198:201], v[60:63]
	v_mfma_f32_16x16x32_bf16 v[56:59], v[174:177], v[198:201], v[56:59]
	v_mfma_f32_16x16x32_bf16 v[44:47], v[164:167], v[206:209], v[44:47]
	v_mfma_f32_16x16x32_bf16 v[40:43], v[174:177], v[206:209], v[40:43]
	v_mfma_f32_16x16x32_bf16 v[28:31], v[164:167], v[214:217], v[28:31]
	v_mfma_f32_16x16x32_bf16 v[24:27], v[174:177], v[214:217], v[24:27]
	v_mfma_f32_16x16x32_bf16 v[12:15], v[164:167], v[222:225], v[12:15]
	v_mfma_f32_16x16x32_bf16 v[8:11], v[174:177], v[222:225], v[8:11]
	s_setprio 0
	s_setprio 1
	v_mfma_f32_16x16x32_bf16 v[52:55], v[178:181], v[194:197], 0
	v_mfma_f32_16x16x32_bf16 v[48:51], v[186:189], v[194:197], 0
	v_mfma_f32_16x16x32_bf16 v[36:39], v[178:181], v[202:205], 0
	v_mfma_f32_16x16x32_bf16 v[32:35], v[186:189], v[202:205], 0
	v_mfma_f32_16x16x32_bf16 v[20:23], v[178:181], v[210:213], 0
	v_mfma_f32_16x16x32_bf16 v[16:19], v[186:189], v[210:213], 0
	v_mfma_f32_16x16x32_bf16 v[4:7], v[178:181], v[218:221], 0
	v_mfma_f32_16x16x32_bf16 v[0:3], v[186:189], v[218:221], 0
	v_mfma_f32_16x16x32_bf16 v[52:55], v[182:185], v[198:201], v[52:55]
	v_mfma_f32_16x16x32_bf16 v[48:51], v[190:193], v[198:201], v[48:51]
	v_mfma_f32_16x16x32_bf16 v[36:39], v[182:185], v[206:209], v[36:39]
	v_mfma_f32_16x16x32_bf16 v[32:35], v[190:193], v[206:209], v[32:35]
	v_mfma_f32_16x16x32_bf16 v[20:23], v[182:185], v[214:217], v[20:23]
	v_mfma_f32_16x16x32_bf16 v[16:19], v[190:193], v[214:217], v[16:19]
	v_mfma_f32_16x16x32_bf16 v[4:7], v[182:185], v[222:225], v[4:7]
	v_mfma_f32_16x16x32_bf16 v[0:3], v[190:193], v[222:225], v[0:3]
	s_setprio 0
	s_barrier
	s_add_i32 s57, 0, 0x18000
	v_add_u32_e32 v136, s57, v149
	s_add_i32 s58, 0, 0x1c000
	ds_read_b128 v[156:159], v136
	ds_read_b128 v[164:167], v136 offset:1024
	ds_read_b128 v[170:173], v136 offset:2048
	ds_read_b128 v[174:177], v136 offset:3072
	v_add_u32_e32 v136, s58, v149
	ds_read_b128 v[178:181], v136
	ds_read_b128 v[182:185], v136 offset:1024
	ds_read_b128 v[186:189], v136 offset:2048
	ds_read_b128 v[190:193], v136 offset:3072
	s_add_u32 s24, s24, 0x84000
	s_addc_u32 s25, s25, 0
	s_mov_b32 m0, s42
	v_lshl_add_u64 v[234:235], s[24:25], 0, v[128:129]
	ds_read_b128 v[194:197], v162 offset:32768
	ds_read_b128 v[198:201], v162 offset:33792
	ds_read_b128 v[202:205], v162 offset:34816
	ds_read_b128 v[206:209], v162 offset:35840
	ds_read_b128 v[210:213], v162 offset:36864
	ds_read_b128 v[214:217], v162 offset:37888
	ds_read_b128 v[218:221], v162 offset:38912
	ds_read_b128 v[222:225], v162 offset:39936
	global_load_lds_dwordx4 v[234:235], off
	v_lshl_add_u64 v[234:235], s[24:25], 0, v[132:133]
	s_mov_b32 m0, s43
	s_nop 0
	global_load_lds_dwordx4 v[234:235], off
	s_waitcnt vmcnt(8)
	s_waitcnt lgkmcnt(0)
	s_barrier
	s_setprio 1
	s_waitcnt lgkmcnt(0)
	v_mfma_f32_16x16x32_bf16 v[124:127], v[156:159], v[194:197], v[124:127]
	v_mfma_f32_16x16x32_bf16 v[120:123], v[170:173], v[194:197], v[120:123]
	v_mfma_f32_16x16x32_bf16 v[108:111], v[156:159], v[202:205], v[108:111]
	v_mfma_f32_16x16x32_bf16 v[104:107], v[170:173], v[202:205], v[104:107]
	v_mfma_f32_16x16x32_bf16 v[92:95], v[156:159], v[210:213], v[92:95]
	v_mfma_f32_16x16x32_bf16 v[88:91], v[170:173], v[210:213], v[88:91]
	v_mfma_f32_16x16x32_bf16 v[76:79], v[156:159], v[218:221], v[76:79]
	v_mfma_f32_16x16x32_bf16 v[72:75], v[170:173], v[218:221], v[72:75]
	v_mfma_f32_16x16x32_bf16 v[124:127], v[164:167], v[198:201], v[124:127]
	v_mfma_f32_16x16x32_bf16 v[120:123], v[174:177], v[198:201], v[120:123]
	v_mfma_f32_16x16x32_bf16 v[108:111], v[164:167], v[206:209], v[108:111]
	v_mfma_f32_16x16x32_bf16 v[104:107], v[174:177], v[206:209], v[104:107]
	v_mfma_f32_16x16x32_bf16 v[92:95], v[164:167], v[214:217], v[92:95]
	v_mfma_f32_16x16x32_bf16 v[88:91], v[174:177], v[214:217], v[88:91]
	v_mfma_f32_16x16x32_bf16 v[76:79], v[164:167], v[222:225], v[76:79]
	v_mfma_f32_16x16x32_bf16 v[72:75], v[174:177], v[222:225], v[72:75]
	s_setprio 0
	s_setprio 1
	v_mfma_f32_16x16x32_bf16 v[116:119], v[178:181], v[194:197], v[116:119]
	v_mfma_f32_16x16x32_bf16 v[112:115], v[186:189], v[194:197], v[112:115]
	v_mfma_f32_16x16x32_bf16 v[100:103], v[178:181], v[202:205], v[100:103]
	v_mfma_f32_16x16x32_bf16 v[96:99], v[186:189], v[202:205], v[96:99]
	v_mfma_f32_16x16x32_bf16 v[84:87], v[178:181], v[210:213], v[84:87]
	v_mfma_f32_16x16x32_bf16 v[80:83], v[186:189], v[210:213], v[80:83]
	v_mfma_f32_16x16x32_bf16 v[68:71], v[178:181], v[218:221], v[68:71]
	v_mfma_f32_16x16x32_bf16 v[64:67], v[186:189], v[218:221], v[64:67]
	v_mfma_f32_16x16x32_bf16 v[116:119], v[182:185], v[198:201], v[116:119]
	v_mfma_f32_16x16x32_bf16 v[112:115], v[190:193], v[198:201], v[112:115]
	v_mfma_f32_16x16x32_bf16 v[100:103], v[182:185], v[206:209], v[100:103]
	v_mfma_f32_16x16x32_bf16 v[96:99], v[190:193], v[206:209], v[96:99]
	v_mfma_f32_16x16x32_bf16 v[84:87], v[182:185], v[214:217], v[84:87]
	v_mfma_f32_16x16x32_bf16 v[80:83], v[190:193], v[214:217], v[80:83]
	v_mfma_f32_16x16x32_bf16 v[68:71], v[182:185], v[222:225], v[68:71]
	v_mfma_f32_16x16x32_bf16 v[64:67], v[190:193], v[222:225], v[64:67]
	s_setprio 0
	s_barrier
; #define PG8_STAGE(bufoff, gbase, voff) do { _Pragma("unroll") for (int _i = 0; _i < 2; ++_i) \
;         __builtin_amdgcn_global_load_lds((const unsigned*)((const char*)(gbase) + (voff)[_i]), (LAS unsigned*)(lds + (bufoff) + ldsw + _i * 8192), 16, 0, 0); } while (0)
; #define PG8_LDA(dst, b, h) do { _Pragma("unroll") for (int m = 0; m < 4; ++m) _Pragma("unroll") for (int k = 0; k < 2; ++k) dst[m][k] = *(const LAS bf16x8*)(lds + PG8_SA(b, h) + aoff + m * 2048 + k * 1024); } while (0)
; #define PG8_MMA(ai, bj, At, Bt) do { __builtin_amdgcn_s_setprio(1); _Pragma("unroll") for (int m = 0; m < 4; ++m) _Pragma("unroll") for (int n = 0; n < 2; ++n) _Pragma("unroll") for (int k = 0; k < 2; ++k) \
;         acc[ai][bj][m][n] = __builtin_amdgcn_mfma_f32_16x16x32_bf16(Bt[n][k], At[m][k], acc[ai][bj][m][n], 0, 0, 0); __builtin_amdgcn_s_setprio(0); } while (0)
; #define PG8_WAIT_V(n) asm volatile("s_waitcnt vmcnt(" #n ")" ::: "memory")
; #define PG8_WAIT_L(n) asm volatile("s_waitcnt lgkmcnt(" #n ")" ::: "memory")
; #define PG8_BAR __builtin_amdgcn_s_barrier()
; #define PG8_SCHED __builtin_amdgcn_sched_barrier(0)
; template <class EpiT>
; __device__ __forceinline__ void gemm_phase(LAS unsigned char* lds, const Gemm g, const StaticOrder& S, const EpiT& E) {
;     ...
;         for (int t = 0; t < nt; t += 2) {
;             const bool last = (t == nt - 2);
;     ...
;             PG8_LDA(At, 1, 1); PG8_STAGE(PG8_SB(1, 0), b3, voffB); PG8_STAGE(PG8_SB(1, 1), b3 + hstepB, voffB); PG8_STAGE(PG8_SA(1, 0), a3, voffA);
;             PG8_WAIT_V(8); PG8_WAIT_L(0); PG8_BAR; PG8_MMA(1, 0, At, B0); PG8_MMA(1, 1, At, B1); PG8_BAR; PG8_SCHED;
	s_add_i32 s24, s57, s37
	v_lshl_add_u64 v[226:227], v[226:227], 0, s[14:15]
	s_mov_b32 m0, s24
	ds_read_b128 v[194:197], v162 offset:49152
	ds_read_b128 v[198:201], v162 offset:50176
	ds_read_b128 v[202:205], v162 offset:51200
	ds_read_b128 v[206:209], v162 offset:52224
	ds_read_b128 v[210:213], v162 offset:53248
	ds_read_b128 v[214:217], v162 offset:54272
	ds_read_b128 v[218:221], v162 offset:55296
	ds_read_b128 v[222:225], v162 offset:56320
	global_load_lds_dwordx4 v[226:227], off
	s_add_i32 m0, s24, 0x2000
	s_add_u32 s22, s22, 0x84080
	v_lshl_add_u64 v[226:227], v[228:229], 0, s[14:15]
	s_addc_u32 s23, s23, 0
	s_add_i32 s24, s58, s37
	global_load_lds_dwordx4 v[226:227], off
	v_lshl_add_u64 v[226:227], s[22:23], 0, v[130:131]
	s_mov_b32 m0, s24
	s_nop 0
	global_load_lds_dwordx4 v[226:227], off
	v_lshl_add_u64 v[226:227], s[22:23], 0, v[134:135]
	s_add_i32 m0, s24, 0x2000
	s_nop 0
	global_load_lds_dwordx4 v[226:227], off
	v_lshl_add_u64 v[226:227], v[230:231], 0, s[14:15]
	s_mov_b32 m0, s44
	s_nop 0
	global_load_lds_dwordx4 v[226:227], off
	v_lshl_add_u64 v[226:227], v[232:233], 0, s[14:15]
	s_mov_b32 m0, s45
	s_nop 0
	global_load_lds_dwordx4 v[226:227], off
	s_waitcnt vmcnt(8)
	s_waitcnt lgkmcnt(0)
	s_barrier
	s_setprio 1
	s_waitcnt lgkmcnt(0)
	v_mfma_f32_16x16x32_bf16 v[60:63], v[156:159], v[194:197], v[60:63]
	v_mfma_f32_16x16x32_bf16 v[56:59], v[170:173], v[194:197], v[56:59]
	v_mfma_f32_16x16x32_bf16 v[44:47], v[156:159], v[202:205], v[44:47]
	v_mfma_f32_16x16x32_bf16 v[40:43], v[170:173], v[202:205], v[40:43]
	v_mfma_f32_16x16x32_bf16 v[28:31], v[156:159], v[210:213], v[28:31]
	v_mfma_f32_16x16x32_bf16 v[24:27], v[170:173], v[210:213], v[24:27]
	v_mfma_f32_16x16x32_bf16 v[12:15], v[156:159], v[218:221], v[12:15]
	v_mfma_f32_16x16x32_bf16 v[8:11], v[170:173], v[218:221], v[8:11]
	v_mfma_f32_16x16x32_bf16 v[60:63], v[164:167], v[198:201], v[60:63]
	v_mfma_f32_16x16x32_bf16 v[56:59], v[174:177], v[198:201], v[56:59]
	v_mfma_f32_16x16x32_bf16 v[44:47], v[164:167], v[206:209], v[44:47]
	v_mfma_f32_16x16x32_bf16 v[40:43], v[174:177], v[206:209], v[40:43]
	v_mfma_f32_16x16x32_bf16 v[28:31], v[164:167], v[214:217], v[28:31]
	v_mfma_f32_16x16x32_bf16 v[24:27], v[174:177], v[214:217], v[24:27]
	v_mfma_f32_16x16x32_bf16 v[12:15], v[164:167], v[222:225], v[12:15]
	v_mfma_f32_16x16x32_bf16 v[8:11], v[174:177], v[222:225], v[8:11]
	s_setprio 0
	s_setprio 1
	v_mfma_f32_16x16x32_bf16 v[52:55], v[178:181], v[194:197], v[52:55]
	v_mfma_f32_16x16x32_bf16 v[48:51], v[186:189], v[194:197], v[48:51]
	v_mfma_f32_16x16x32_bf16 v[36:39], v[178:181], v[202:205], v[36:39]
	v_mfma_f32_16x16x32_bf16 v[32:35], v[186:189], v[202:205], v[32:35]
	v_mfma_f32_16x16x32_bf16 v[20:23], v[178:181], v[210:213], v[20:23]
	v_mfma_f32_16x16x32_bf16 v[16:19], v[186:189], v[210:213], v[16:19]
	v_mfma_f32_16x16x32_bf16 v[4:7], v[178:181], v[218:221], v[4:7]
	v_mfma_f32_16x16x32_bf16 v[0:3], v[186:189], v[218:221], v[0:3]
	v_mfma_f32_16x16x32_bf16 v[52:55], v[182:185], v[198:201], v[52:55]
	v_mfma_f32_16x16x32_bf16 v[48:51], v[190:193], v[198:201], v[48:51]
	v_mfma_f32_16x16x32_bf16 v[36:39], v[182:185], v[206:209], v[36:39]
	v_mfma_f32_16x16x32_bf16 v[32:35], v[190:193], v[206:209], v[32:35]
	v_mfma_f32_16x16x32_bf16 v[20:23], v[182:185], v[214:217], v[20:23]
	v_mfma_f32_16x16x32_bf16 v[16:19], v[190:193], v[214:217], v[16:19]
	v_mfma_f32_16x16x32_bf16 v[4:7], v[182:185], v[222:225], v[4:7]
	v_mfma_f32_16x16x32_bf16 v[0:3], v[190:193], v[222:225], v[0:3]
	s_setprio 0
	s_barrier
	s_add_i32 s56, s56, 2
	s_add_u32 s20, s20, 0x100
	s_addc_u32 s21, s21, 0
	s_add_u32 s8, s8, 0x100
	s_addc_u32 s39, s39, 0
	s_cmp_gt_u32 s56, 29
	s_cbranch_scc1 .Lpeel_done_761
	.p2alignl 6, 3212836864

; #define PG8_BAR __builtin_amdgcn_s_barrier()
; template <class EpiT>
; __device__ __forceinline__ void gemm_phase(LAS unsigned char* lds, const Gemm g, const StaticOrder& S, const EpiT& E) {
;     ...
;         if (wr == 0) PG8_BAR;
;         E(acc, cur, wr, wc, fr, fq);
.Lpeel_done_761:
	s_and_b64 vcc, exec, s[16:17]
	s_cbranch_vccz .LBB0_764
	s_barrier

; #define PG8_STAGE(bufoff, gbase, voff) do { _Pragma("unroll") for (int _i = 0; _i < 2; ++_i) \
;         __builtin_amdgcn_global_load_lds((const unsigned*)((const char*)(gbase) + (voff)[_i]), (LAS unsigned*)(lds + (bufoff) + ldsw + _i * 8192), 16, 0, 0); } while (0)
; #define PG8_LDA(dst, b, h) do { _Pragma("unroll") for (int m = 0; m < 4; ++m) _Pragma("unroll") for (int k = 0; k < 2; ++k) dst[m][k] = *(const LAS bf16x8*)(lds + PG8_SA(b, h) + aoff + m * 2048 + k * 1024); } while (0)
; #define PG8_LDB(dst, b, h) do { _Pragma("unroll") for (int n = 0; n < 2; ++n) _Pragma("unroll") for (int k = 0; k < 2; ++k) dst[n][k] = *(const LAS bf16x8*)(lds + PG8_SB(b, h) + boff + n * 2048 + k * 1024); } while (0)
; #define PG8_WAIT_V(n) asm volatile("s_waitcnt vmcnt(" #n ")" ::: "memory")
; #define PG8_WAIT_L(n) asm volatile("s_waitcnt lgkmcnt(" #n ")" ::: "memory")
; template <class EpiT>
; __device__ __forceinline__ void gemm_phase(LAS unsigned char* lds, const Gemm g, const StaticOrder& S, const EpiT& E) {
;     ...
;         const char* nA = has_next ? (const char*)g.A + (size_t)nxt.pm * tstepA + (size_t)nxt.pn * g.a_koff * 2 : cA; const char* nB = has_next ? (const char*)g.Bt + (size_t)nxt.pn * tstepB : cB;
;         for (int t = 0; t < nt; t += 2) {
;             const bool last = (t == nt - 2);
;             const char* a1 = cA + (size_t)(t + 1) * kstep;
;             const char* a2 = last ? nA : cA + (size_t)(t + 2) * kstep; const char* b2 = last ? nB : cB + (size_t)(t + 2) * kstep;
;             const char* a3 = a2 + kstep; const char* b3 = b2 + kstep;
;             PG8_LDB(B0, 0, 0); PG8_LDB(B1, 0, 1); PG8_SCHED; PG8_LDA(At, 0, 0); PG8_STAGE(PG8_SA(1, 1), a1 + hstepA, voffA);
;             PG8_WAIT_V(8); PG8_WAIT_L(0); PG8_BAR; PG8_MMA(0, 0, At, B0); PG8_MMA(0, 1, At, B1); PG8_BAR; PG8_SCHED;
;             PG8_LDA(At, 0, 1); PG8_STAGE(PG8_SB(0, 0), b2, voffB); PG8_STAGE(PG8_SB(0, 1), b2 + hstepB, voffB); PG8_STAGE(PG8_SA(0, 0), a2, voffA);
;             PG8_WAIT_V(8); PG8_WAIT_L(0); PG8_BAR; PG8_MMA(1, 0, At, B0); PG8_MMA(1, 1, At, B1); PG8_BAR; PG8_SCHED;
;     ...
; #pragma unroll
;         for (int a = 0; a < 2; ++a)
; #pragma unroll
;             for (int b = 0; b < 2; ++b)
; #pragma unroll
;                 for (int m = 0; m < 4; ++m)
; #pragma unroll
;                     for (int n = 0; n < 2; ++n) acc[a][b][m][n] = (f32x4){0.f, 0.f, 0.f, 0.f};
.LBB0_1031:
	s_add_u32 s18, s18, 0x84080
	s_addc_u32 s19, s19, 0
	s_add_u32 s53, s20, 0x100
	s_addc_u32 s54, s21, 0
	s_mov_b32 s55, -2
	ds_read_b128 v[154:157], v150
	ds_read_b128 v[158:161], v150 offset:1024
	ds_read_b128 v[162:165], v150 offset:2048
	ds_read_b128 v[170:173], v150 offset:3072
	ds_read_b128 v[174:177], v151
	ds_read_b128 v[178:181], v151 offset:1024
	ds_read_b128 v[182:185], v151 offset:2048
	ds_read_b128 v[186:189], v151 offset:3072
	s_add_u32 s20, s18, 0xfff7c080
	s_addc_u32 s21, s19, -1
	s_cmp_eq_u32 s55, 28
	s_cselect_b32 s23, s5, s21
	s_cselect_b32 s22, s4, s20
	s_cselect_b32 s21, s17, s54
	s_cselect_b32 s20, s16, s53
	v_lshl_add_u64 v[166:167], s[18:19], 0, v[138:139]
	s_add_i32 m0, s37, 0xc000
	ds_read_b128 v[190:193], v152
	ds_read_b128 v[194:197], v152 offset:1024
	ds_read_b128 v[198:201], v152 offset:2048
	ds_read_b128 v[202:205], v152 offset:3072
	ds_read_b128 v[206:209], v152 offset:4096
	ds_read_b128 v[210:213], v152 offset:5120
	ds_read_b128 v[214:217], v152 offset:6144
	ds_read_b128 v[218:221], v152 offset:7168
	global_load_lds_dwordx4 v[166:167], off
	v_lshl_add_u64 v[166:167], s[18:19], 0, v[140:141]
	s_add_i32 m0, s37, 0xe000
	s_nop 0
	global_load_lds_dwordx4 v[166:167], off
	s_waitcnt vmcnt(8)
	s_waitcnt lgkmcnt(0)
	s_barrier
	s_setprio 1
	s_waitcnt lgkmcnt(0)
	v_mfma_f32_16x16x32_bf16 v[124:127], v[154:157], v[190:193], 0
	v_mfma_f32_16x16x32_bf16 v[120:123], v[162:165], v[190:193], 0
	v_mfma_f32_16x16x32_bf16 v[108:111], v[154:157], v[198:201], 0
	v_mfma_f32_16x16x32_bf16 v[104:107], v[162:165], v[198:201], 0
	v_mfma_f32_16x16x32_bf16 v[92:95], v[154:157], v[206:209], 0
	v_mfma_f32_16x16x32_bf16 v[88:91], v[162:165], v[206:209], 0
	v_mfma_f32_16x16x32_bf16 v[76:79], v[154:157], v[214:217], 0
	v_mfma_f32_16x16x32_bf16 v[72:75], v[162:165], v[214:217], 0
	v_mfma_f32_16x16x32_bf16 v[124:127], v[158:161], v[194:197], v[124:127]
	v_mfma_f32_16x16x32_bf16 v[120:123], v[170:173], v[194:197], v[120:123]
	v_mfma_f32_16x16x32_bf16 v[108:111], v[158:161], v[202:205], v[108:111]
	v_mfma_f32_16x16x32_bf16 v[104:107], v[170:173], v[202:205], v[104:107]
	v_mfma_f32_16x16x32_bf16 v[92:95], v[158:161], v[210:213], v[92:95]
	v_mfma_f32_16x16x32_bf16 v[88:91], v[170:173], v[210:213], v[88:91]
	v_mfma_f32_16x16x32_bf16 v[76:79], v[158:161], v[218:221], v[76:79]
	v_mfma_f32_16x16x32_bf16 v[72:75], v[170:173], v[218:221], v[72:75]
	s_setprio 0
	s_setprio 1
	v_mfma_f32_16x16x32_bf16 v[116:119], v[174:177], v[190:193], 0
	v_mfma_f32_16x16x32_bf16 v[112:115], v[182:185], v[190:193], 0
	v_mfma_f32_16x16x32_bf16 v[100:103], v[174:177], v[198:201], 0
	v_mfma_f32_16x16x32_bf16 v[96:99], v[182:185], v[198:201], 0
	v_mfma_f32_16x16x32_bf16 v[84:87], v[174:177], v[206:209], 0
	v_mfma_f32_16x16x32_bf16 v[80:83], v[182:185], v[206:209], 0
	v_mfma_f32_16x16x32_bf16 v[68:71], v[174:177], v[214:217], 0
	v_mfma_f32_16x16x32_bf16 v[64:67], v[182:185], v[214:217], 0
	v_mfma_f32_16x16x32_bf16 v[116:119], v[178:181], v[194:197], v[116:119]
	v_mfma_f32_16x16x32_bf16 v[112:115], v[186:189], v[194:197], v[112:115]
	v_mfma_f32_16x16x32_bf16 v[100:103], v[178:181], v[202:205], v[100:103]
	v_mfma_f32_16x16x32_bf16 v[96:99], v[186:189], v[202:205], v[96:99]
	v_mfma_f32_16x16x32_bf16 v[84:87], v[178:181], v[210:213], v[84:87]
	v_mfma_f32_16x16x32_bf16 v[80:83], v[186:189], v[210:213], v[80:83]
	v_mfma_f32_16x16x32_bf16 v[68:71], v[178:181], v[218:221], v[68:71]
	v_mfma_f32_16x16x32_bf16 v[64:67], v[186:189], v[218:221], v[64:67]
	s_setprio 0
	s_barrier
	s_add_i32 s56, s46, s36
	v_lshl_add_u64 v[166:167], s[20:21], 0, v[130:131]
	s_mov_b32 m0, s56
	ds_read_b128 v[190:193], v152 offset:16384
	ds_read_b128 v[194:197], v152 offset:17408
	ds_read_b128 v[198:201], v152 offset:18432
	ds_read_b128 v[202:205], v152 offset:19456
	ds_read_b128 v[206:209], v152 offset:20480
	ds_read_b128 v[210:213], v152 offset:21504
	ds_read_b128 v[214:217], v152 offset:22528
	ds_read_b128 v[218:221], v152 offset:23552
	global_load_lds_dwordx4 v[166:167], off
	s_add_i32 m0, s56, 0x2000
	s_add_u32 s56, s20, 0x84000
	v_lshl_add_u64 v[222:223], s[20:21], 0, v[134:135]
	s_addc_u32 s57, s21, 0
	s_add_i32 s58, s47, s36
	global_load_lds_dwordx4 v[222:223], off
	v_lshl_add_u64 v[224:225], s[56:57], 0, v[130:131]
	s_mov_b32 m0, s58
	v_lshl_add_u64 v[226:227], s[22:23], 0, v[132:133]
	global_load_lds_dwordx4 v[224:225], off
	v_lshl_add_u64 v[224:225], s[56:57], 0, v[134:135]
	s_add_i32 m0, s58, 0x2000
	s_nop 0
	global_load_lds_dwordx4 v[224:225], off
	v_lshl_add_u64 v[224:225], s[22:23], 0, v[128:129]
	s_mov_b32 m0, s37
	s_nop 0
	global_load_lds_dwordx4 v[224:225], off
	s_mov_b32 m0, s38
	s_nop 0
	global_load_lds_dwordx4 v[226:227], off
	s_waitcnt vmcnt(8)
	s_waitcnt lgkmcnt(0)
	s_barrier
; #define PG8_STAGE(bufoff, gbase, voff) do { _Pragma("unroll") for (int _i = 0; _i < 2; ++_i) \
;         __builtin_amdgcn_global_load_lds((const unsigned*)((const char*)(gbase) + (voff)[_i]), (LAS unsigned*)(lds + (bufoff) + ldsw + _i * 8192), 16, 0, 0); } while (0)
; #define PG8_LDA(dst, b, h) do { _Pragma("unroll") for (int m = 0; m < 4; ++m) _Pragma("unroll") for (int k = 0; k < 2; ++k) dst[m][k] = *(const LAS bf16x8*)(lds + PG8_SA(b, h) + aoff + m * 2048 + k * 1024); } while (0)
; #define PG8_LDB(dst, b, h) do { _Pragma("unroll") for (int n = 0; n < 2; ++n) _Pragma("unroll") for (int k = 0; k < 2; ++k) dst[n][k] = *(const LAS bf16x8*)(lds + PG8_SB(b, h) + boff + n * 2048 + k * 1024); } while (0)
; #define PG8_MMA(ai, bj, At, Bt) do { __builtin_amdgcn_s_setprio(1); _Pragma("unroll") for (int m = 0; m < 4; ++m) _Pragma("unroll") for (int n = 0; n < 2; ++n) _Pragma("unroll") for (int k = 0; k < 2; ++k) \
;         acc[ai][bj][m][n] = __builtin_amdgcn_mfma_f32_16x16x32_bf16(Bt[n][k], At[m][k], acc[ai][bj][m][n], 0, 0, 0); __builtin_amdgcn_s_setprio(0); } while (0)
; #define PG8_WAIT_V(n) asm volatile("s_waitcnt vmcnt(" #n ")" ::: "memory")
; #define PG8_WAIT_L(n) asm volatile("s_waitcnt lgkmcnt(" #n ")" ::: "memory")
; #define PG8_BAR __builtin_amdgcn_s_barrier()
; #define PG8_SCHED __builtin_amdgcn_sched_barrier(0)
; template <class EpiT>
; __device__ __forceinline__ void gemm_phase(LAS unsigned char* lds, const Gemm g, const StaticOrder& S, const EpiT& E) {
;     ...
;             PG8_WAIT_V(8); PG8_WAIT_L(0); PG8_BAR; PG8_MMA(1, 0, At, B0); PG8_MMA(1, 1, At, B1); PG8_BAR; PG8_SCHED;
;             PG8_LDB(B0, 1, 0); PG8_LDB(B1, 1, 1); PG8_SCHED; PG8_LDA(At, 1, 0); PG8_STAGE(PG8_SA(0, 1), a2 + hstepA, voffA);
;             PG8_WAIT_V(8); PG8_WAIT_L(0); PG8_BAR; PG8_MMA(0, 0, At, B0); PG8_MMA(0, 1, At, B1); PG8_BAR; PG8_SCHED;
	s_setprio 1
	s_waitcnt lgkmcnt(0)
	v_mfma_f32_16x16x32_bf16 v[60:63], v[154:157], v[190:193], 0
	v_mfma_f32_16x16x32_bf16 v[56:59], v[162:165], v[190:193], 0
	v_mfma_f32_16x16x32_bf16 v[44:47], v[154:157], v[198:201], 0
	v_mfma_f32_16x16x32_bf16 v[40:43], v[162:165], v[198:201], 0
	v_mfma_f32_16x16x32_bf16 v[28:31], v[154:157], v[206:209], 0
	v_mfma_f32_16x16x32_bf16 v[24:27], v[162:165], v[206:209], 0
	v_mfma_f32_16x16x32_bf16 v[12:15], v[154:157], v[214:217], 0
	v_mfma_f32_16x16x32_bf16 v[8:11], v[162:165], v[214:217], 0
	v_mfma_f32_16x16x32_bf16 v[60:63], v[158:161], v[194:197], v[60:63]
	v_mfma_f32_16x16x32_bf16 v[56:59], v[170:173], v[194:197], v[56:59]
	v_mfma_f32_16x16x32_bf16 v[44:47], v[158:161], v[202:205], v[44:47]
	v_mfma_f32_16x16x32_bf16 v[40:43], v[170:173], v[202:205], v[40:43]
	v_mfma_f32_16x16x32_bf16 v[28:31], v[158:161], v[210:213], v[28:31]
	v_mfma_f32_16x16x32_bf16 v[24:27], v[170:173], v[210:213], v[24:27]
	v_mfma_f32_16x16x32_bf16 v[12:15], v[158:161], v[218:221], v[12:15]
	v_mfma_f32_16x16x32_bf16 v[8:11], v[170:173], v[218:221], v[8:11]
	s_setprio 0
	s_setprio 1
	v_mfma_f32_16x16x32_bf16 v[52:55], v[174:177], v[190:193], 0
	v_mfma_f32_16x16x32_bf16 v[48:51], v[182:185], v[190:193], 0
	v_mfma_f32_16x16x32_bf16 v[36:39], v[174:177], v[198:201], 0
	v_mfma_f32_16x16x32_bf16 v[32:35], v[182:185], v[198:201], 0
	v_mfma_f32_16x16x32_bf16 v[20:23], v[174:177], v[206:209], 0
	v_mfma_f32_16x16x32_bf16 v[16:19], v[182:185], v[206:209], 0
	v_mfma_f32_16x16x32_bf16 v[4:7], v[174:177], v[214:217], 0
	v_mfma_f32_16x16x32_bf16 v[0:3], v[182:185], v[214:217], 0
	v_mfma_f32_16x16x32_bf16 v[52:55], v[178:181], v[194:197], v[52:55]
	v_mfma_f32_16x16x32_bf16 v[48:51], v[186:189], v[194:197], v[48:51]
	v_mfma_f32_16x16x32_bf16 v[36:39], v[178:181], v[202:205], v[36:39]
	v_mfma_f32_16x16x32_bf16 v[32:35], v[186:189], v[202:205], v[32:35]
	v_mfma_f32_16x16x32_bf16 v[20:23], v[178:181], v[210:213], v[20:23]
	v_mfma_f32_16x16x32_bf16 v[16:19], v[186:189], v[210:213], v[16:19]
	v_mfma_f32_16x16x32_bf16 v[4:7], v[178:181], v[218:221], v[4:7]
	v_mfma_f32_16x16x32_bf16 v[0:3], v[186:189], v[218:221], v[0:3]
	s_setprio 0
	s_barrier
	s_add_i32 s56, 0, 0x18000
	s_add_i32 s57, 0, 0x1c000
	v_add_u32_e32 v170, s56, v146
	v_add_u32_e32 v186, s57, v146
	ds_read_b128 v[154:157], v170
	ds_read_b128 v[158:161], v170 offset:1024
	ds_read_b128 v[162:165], v170 offset:2048
	ds_read_b128 v[170:173], v170 offset:3072
	ds_read_b128 v[174:177], v186
	ds_read_b128 v[178:181], v186 offset:1024
	ds_read_b128 v[182:185], v186 offset:2048
	ds_read_b128 v[186:189], v186 offset:3072
	s_add_u32 s22, s22, 0x84000
	s_addc_u32 s23, s23, 0
	s_mov_b32 m0, s39
	v_lshl_add_u64 v[228:229], s[22:23], 0, v[128:129]
	ds_read_b128 v[190:193], v152 offset:32768
	ds_read_b128 v[194:197], v152 offset:33792
	ds_read_b128 v[198:201], v152 offset:34816
	ds_read_b128 v[202:205], v152 offset:35840
	ds_read_b128 v[206:209], v152 offset:36864
	ds_read_b128 v[210:213], v152 offset:37888
	ds_read_b128 v[214:217], v152 offset:38912
	ds_read_b128 v[218:221], v152 offset:39936
	global_load_lds_dwordx4 v[228:229], off
	v_lshl_add_u64 v[228:229], s[22:23], 0, v[132:133]
	s_mov_b32 m0, s40
	s_nop 0
	global_load_lds_dwordx4 v[228:229], off
	s_waitcnt vmcnt(8)
	s_waitcnt lgkmcnt(0)
	s_barrier
	s_setprio 1
	s_waitcnt lgkmcnt(0)
	v_mfma_f32_16x16x32_bf16 v[124:127], v[154:157], v[190:193], v[124:127]
	v_mfma_f32_16x16x32_bf16 v[120:123], v[162:165], v[190:193], v[120:123]
	v_mfma_f32_16x16x32_bf16 v[108:111], v[154:157], v[198:201], v[108:111]
	v_mfma_f32_16x16x32_bf16 v[104:107], v[162:165], v[198:201], v[104:107]
	v_mfma_f32_16x16x32_bf16 v[92:95], v[154:157], v[206:209], v[92:95]
	v_mfma_f32_16x16x32_bf16 v[88:91], v[162:165], v[206:209], v[88:91]
	v_mfma_f32_16x16x32_bf16 v[76:79], v[154:157], v[214:217], v[76:79]
	v_mfma_f32_16x16x32_bf16 v[72:75], v[162:165], v[214:217], v[72:75]
	v_mfma_f32_16x16x32_bf16 v[124:127], v[158:161], v[194:197], v[124:127]
	v_mfma_f32_16x16x32_bf16 v[120:123], v[170:173], v[194:197], v[120:123]
	v_mfma_f32_16x16x32_bf16 v[108:111], v[158:161], v[202:205], v[108:111]
	v_mfma_f32_16x16x32_bf16 v[104:107], v[170:173], v[202:205], v[104:107]
	v_mfma_f32_16x16x32_bf16 v[92:95], v[158:161], v[210:213], v[92:95]
	v_mfma_f32_16x16x32_bf16 v[88:91], v[170:173], v[210:213], v[88:91]
	v_mfma_f32_16x16x32_bf16 v[76:79], v[158:161], v[218:221], v[76:79]
	v_mfma_f32_16x16x32_bf16 v[72:75], v[170:173], v[218:221], v[72:75]
	s_setprio 0
	s_setprio 1
	v_mfma_f32_16x16x32_bf16 v[116:119], v[174:177], v[190:193], v[116:119]
	v_mfma_f32_16x16x32_bf16 v[112:115], v[182:185], v[190:193], v[112:115]
	v_mfma_f32_16x16x32_bf16 v[100:103], v[174:177], v[198:201], v[100:103]
	v_mfma_f32_16x16x32_bf16 v[96:99], v[182:185], v[198:201], v[96:99]
	v_mfma_f32_16x16x32_bf16 v[84:87], v[174:177], v[206:209], v[84:87]
	v_mfma_f32_16x16x32_bf16 v[80:83], v[182:185], v[206:209], v[80:83]
	v_mfma_f32_16x16x32_bf16 v[68:71], v[174:177], v[214:217], v[68:71]
	v_mfma_f32_16x16x32_bf16 v[64:67], v[182:185], v[214:217], v[64:67]
	v_mfma_f32_16x16x32_bf16 v[116:119], v[178:181], v[194:197], v[116:119]
	v_mfma_f32_16x16x32_bf16 v[112:115], v[186:189], v[194:197], v[112:115]
	v_mfma_f32_16x16x32_bf16 v[100:103], v[178:181], v[202:205], v[100:103]
	v_mfma_f32_16x16x32_bf16 v[96:99], v[186:189], v[202:205], v[96:99]
	v_mfma_f32_16x16x32_bf16 v[84:87], v[178:181], v[210:213], v[84:87]
	v_mfma_f32_16x16x32_bf16 v[80:83], v[186:189], v[210:213], v[80:83]
	v_mfma_f32_16x16x32_bf16 v[68:71], v[178:181], v[218:221], v[68:71]
	v_mfma_f32_16x16x32_bf16 v[64:67], v[186:189], v[218:221], v[64:67]
	s_setprio 0
	s_barrier
; #define PG8_STAGE(bufoff, gbase, voff) do { _Pragma("unroll") for (int _i = 0; _i < 2; ++_i) \
;         __builtin_amdgcn_global_load_lds((const unsigned*)((const char*)(gbase) + (voff)[_i]), (LAS unsigned*)(lds + (bufoff) + ldsw + _i * 8192), 16, 0, 0); } while (0)
; #define PG8_LDA(dst, b, h) do { _Pragma("unroll") for (int m = 0; m < 4; ++m) _Pragma("unroll") for (int k = 0; k < 2; ++k) dst[m][k] = *(const LAS bf16x8*)(lds + PG8_SA(b, h) + aoff + m * 2048 + k * 1024); } while (0)
; #define PG8_MMA(ai, bj, At, Bt) do { __builtin_amdgcn_s_setprio(1); _Pragma("unroll") for (int m = 0; m < 4; ++m) _Pragma("unroll") for (int n = 0; n < 2; ++n) _Pragma("unroll") for (int k = 0; k < 2; ++k) \
;         acc[ai][bj][m][n] = __builtin_amdgcn_mfma_f32_16x16x32_bf16(Bt[n][k], At[m][k], acc[ai][bj][m][n], 0, 0, 0); __builtin_amdgcn_s_setprio(0); } while (0)
; #define PG8_WAIT_V(n) asm volatile("s_waitcnt vmcnt(" #n ")" ::: "memory")
; #define PG8_WAIT_L(n) asm volatile("s_waitcnt lgkmcnt(" #n ")" ::: "memory")
; #define PG8_BAR __builtin_amdgcn_s_barrier()
; #define PG8_SCHED __builtin_amdgcn_sched_barrier(0)
; template <class EpiT>
; __device__ __forceinline__ void gemm_phase(LAS unsigned char* lds, const Gemm g, const StaticOrder& S, const EpiT& E) {
;     ...
;         for (int t = 0; t < nt; t += 2) {
;             const bool last = (t == nt - 2);
;     ...
;             PG8_LDA(At, 1, 1); PG8_STAGE(PG8_SB(1, 0), b3, voffB); PG8_STAGE(PG8_SB(1, 1), b3 + hstepB, voffB); PG8_STAGE(PG8_SA(1, 0), a3, voffA);
;             PG8_WAIT_V(8); PG8_WAIT_L(0); PG8_BAR; PG8_MMA(1, 0, At, B0); PG8_MMA(1, 1, At, B1); PG8_BAR; PG8_SCHED;
	s_add_i32 s22, s56, s36
	v_lshl_add_u64 v[166:167], v[166:167], 0, s[12:13]
	s_mov_b32 m0, s22
	ds_read_b128 v[190:193], v152 offset:49152
	ds_read_b128 v[194:197], v152 offset:50176
	ds_read_b128 v[198:201], v152 offset:51200
	ds_read_b128 v[202:205], v152 offset:52224
	ds_read_b128 v[206:209], v152 offset:53248
	ds_read_b128 v[210:213], v152 offset:54272
	ds_read_b128 v[214:217], v152 offset:55296
	ds_read_b128 v[218:221], v152 offset:56320
	global_load_lds_dwordx4 v[166:167], off
	s_add_i32 m0, s22, 0x2000
	s_add_u32 s20, s20, 0x84080
	v_lshl_add_u64 v[166:167], v[222:223], 0, s[12:13]
	s_addc_u32 s21, s21, 0
	s_add_i32 s22, s57, s36
	global_load_lds_dwordx4 v[166:167], off
	v_lshl_add_u64 v[166:167], s[20:21], 0, v[130:131]
	s_mov_b32 m0, s22
	s_nop 0
	global_load_lds_dwordx4 v[166:167], off
	v_lshl_add_u64 v[166:167], s[20:21], 0, v[134:135]
	s_add_i32 m0, s22, 0x2000
	s_nop 0
	global_load_lds_dwordx4 v[166:167], off
	v_lshl_add_u64 v[166:167], v[224:225], 0, s[12:13]
	s_mov_b32 m0, s42
	s_nop 0
	global_load_lds_dwordx4 v[166:167], off
	v_lshl_add_u64 v[166:167], v[226:227], 0, s[12:13]
	s_mov_b32 m0, s43
	s_nop 0
	global_load_lds_dwordx4 v[166:167], off
	s_waitcnt vmcnt(8)
	s_waitcnt lgkmcnt(0)
	s_barrier
	s_setprio 1
	s_waitcnt lgkmcnt(0)
	v_mfma_f32_16x16x32_bf16 v[60:63], v[154:157], v[190:193], v[60:63]
	v_mfma_f32_16x16x32_bf16 v[56:59], v[162:165], v[190:193], v[56:59]
	v_mfma_f32_16x16x32_bf16 v[44:47], v[154:157], v[198:201], v[44:47]
	v_mfma_f32_16x16x32_bf16 v[40:43], v[162:165], v[198:201], v[40:43]
	v_mfma_f32_16x16x32_bf16 v[28:31], v[154:157], v[206:209], v[28:31]
	v_mfma_f32_16x16x32_bf16 v[24:27], v[162:165], v[206:209], v[24:27]
	v_mfma_f32_16x16x32_bf16 v[12:15], v[154:157], v[214:217], v[12:15]
	v_mfma_f32_16x16x32_bf16 v[8:11], v[162:165], v[214:217], v[8:11]
	v_mfma_f32_16x16x32_bf16 v[60:63], v[158:161], v[194:197], v[60:63]
	v_mfma_f32_16x16x32_bf16 v[56:59], v[170:173], v[194:197], v[56:59]
	v_mfma_f32_16x16x32_bf16 v[44:47], v[158:161], v[202:205], v[44:47]
	v_mfma_f32_16x16x32_bf16 v[40:43], v[170:173], v[202:205], v[40:43]
	v_mfma_f32_16x16x32_bf16 v[28:31], v[158:161], v[210:213], v[28:31]
	v_mfma_f32_16x16x32_bf16 v[24:27], v[170:173], v[210:213], v[24:27]
	v_mfma_f32_16x16x32_bf16 v[12:15], v[158:161], v[218:221], v[12:15]
	v_mfma_f32_16x16x32_bf16 v[8:11], v[170:173], v[218:221], v[8:11]
	s_setprio 0
	s_setprio 1
	v_mfma_f32_16x16x32_bf16 v[52:55], v[174:177], v[190:193], v[52:55]
	v_mfma_f32_16x16x32_bf16 v[48:51], v[182:185], v[190:193], v[48:51]
	v_mfma_f32_16x16x32_bf16 v[36:39], v[174:177], v[198:201], v[36:39]
	v_mfma_f32_16x16x32_bf16 v[32:35], v[182:185], v[198:201], v[32:35]
	v_mfma_f32_16x16x32_bf16 v[20:23], v[174:177], v[206:209], v[20:23]
	v_mfma_f32_16x16x32_bf16 v[16:19], v[182:185], v[206:209], v[16:19]
	v_mfma_f32_16x16x32_bf16 v[4:7], v[174:177], v[214:217], v[4:7]
	v_mfma_f32_16x16x32_bf16 v[0:3], v[182:185], v[214:217], v[0:3]
	v_mfma_f32_16x16x32_bf16 v[52:55], v[178:181], v[194:197], v[52:55]
	v_mfma_f32_16x16x32_bf16 v[48:51], v[186:189], v[194:197], v[48:51]
	v_mfma_f32_16x16x32_bf16 v[36:39], v[178:181], v[202:205], v[36:39]
	v_mfma_f32_16x16x32_bf16 v[32:35], v[186:189], v[202:205], v[32:35]
	v_mfma_f32_16x16x32_bf16 v[20:23], v[178:181], v[210:213], v[20:23]
	v_mfma_f32_16x16x32_bf16 v[16:19], v[186:189], v[210:213], v[16:19]
	v_mfma_f32_16x16x32_bf16 v[4:7], v[178:181], v[218:221], v[4:7]
	v_mfma_f32_16x16x32_bf16 v[0:3], v[186:189], v[218:221], v[0:3]
	s_setprio 0
	s_barrier
	s_add_i32 s55, s55, 2
	s_add_u32 s18, s18, 0x100
	s_addc_u32 s19, s19, 0
	s_add_u32 s53, s53, 0x100
	s_addc_u32 s54, s54, 0
	s_cmp_gt_u32 s55, 29
	s_cbranch_scc1 .Lpeel_done_1032
	.p2alignl 6, 3212836864
	s_nop 0
	s_nop 0
	s_nop 0
	s_nop 0
	s_nop 0
	s_nop 0
	s_nop 0
	s_nop 0
	s_nop 0
	s_nop 0

; #define PG8_STAGE(bufoff, gbase, voff) do { _Pragma("unroll") for (int _i = 0; _i < 2; ++_i) \
;         __builtin_amdgcn_global_load_lds((const unsigned*)((const char*)(gbase) + (voff)[_i]), (LAS unsigned*)(lds + (bufoff) + ldsw + _i * 8192), 16, 0, 0); } while (0)
; #define PG8_LDA(dst, b, h) do { _Pragma("unroll") for (int m = 0; m < 4; ++m) _Pragma("unroll") for (int k = 0; k < 2; ++k) dst[m][k] = *(const LAS bf16x8*)(lds + PG8_SA(b, h) + aoff + m * 2048 + k * 1024); } while (0)
; #define PG8_LDB(dst, b, h) do { _Pragma("unroll") for (int n = 0; n < 2; ++n) _Pragma("unroll") for (int k = 0; k < 2; ++k) dst[n][k] = *(const LAS bf16x8*)(lds + PG8_SB(b, h) + boff + n * 2048 + k * 1024); } while (0)
; #define PG8_WAIT_V(n) asm volatile("s_waitcnt vmcnt(" #n ")" ::: "memory")
; #define PG8_WAIT_L(n) asm volatile("s_waitcnt lgkmcnt(" #n ")" ::: "memory")
; template <class EpiT>
; __device__ __forceinline__ void gemm_phase(LAS unsigned char* lds, const Gemm g, const StaticOrder& S, const EpiT& E) {
;     ...
;         const char* nA = has_next ? (const char*)g.A + (size_t)nxt.pm * tstepA + (size_t)nxt.pn * g.a_koff * 2 : cA; const char* nB = has_next ? (const char*)g.Bt + (size_t)nxt.pn * tstepB : cB;
;         for (int t = 0; t < nt; t += 2) {
;             const bool last = (t == nt - 2);
;             const char* a1 = cA + (size_t)(t + 1) * kstep;
;             const char* a2 = last ? nA : cA + (size_t)(t + 2) * kstep; const char* b2 = last ? nB : cB + (size_t)(t + 2) * kstep;
;             const char* a3 = a2 + kstep; const char* b3 = b2 + kstep;
;             PG8_LDB(B0, 0, 0); PG8_LDB(B1, 0, 1); PG8_SCHED; PG8_LDA(At, 0, 0); PG8_STAGE(PG8_SA(1, 1), a1 + hstepA, voffA);
;             PG8_WAIT_V(8); PG8_WAIT_L(0); PG8_BAR; PG8_MMA(0, 0, At, B0); PG8_MMA(0, 1, At, B1); PG8_BAR; PG8_SCHED;
;             PG8_LDA(At, 0, 1); PG8_STAGE(PG8_SB(0, 0), b2, voffB); PG8_STAGE(PG8_SB(0, 1), b2 + hstepB, voffB); PG8_STAGE(PG8_SA(0, 0), a2, voffA);
;             PG8_WAIT_V(8); PG8_WAIT_L(0); PG8_BAR; PG8_MMA(1, 0, At, B0); PG8_MMA(1, 1, At, B1); PG8_BAR; PG8_SCHED;
;     ...
; #pragma unroll
;         for (int a = 0; a < 2; ++a)
; #pragma unroll
;             for (int b = 0; b < 2; ++b)
; #pragma unroll
;                 for (int m = 0; m < 4; ++m)
; #pragma unroll
;                     for (int n = 0; n < 2; ++n) acc[a][b][m][n] = (f32x4){0.f, 0.f, 0.f, 0.f};
.LBB0_1155:
	s_add_u32 s16, s16, 0x84080
	s_addc_u32 s17, s17, 0
	s_add_u32 s51, s18, 0x100
	s_addc_u32 s52, s19, 0
	s_mov_b32 s53, -2
	ds_read_b128 v[154:157], v150
	ds_read_b128 v[158:161], v150 offset:1024
	ds_read_b128 v[162:165], v150 offset:2048
	ds_read_b128 v[170:173], v150 offset:3072
	ds_read_b128 v[174:177], v151
	ds_read_b128 v[178:181], v151 offset:1024
	ds_read_b128 v[182:185], v151 offset:2048
	ds_read_b128 v[186:189], v151 offset:3072
	s_add_u32 s18, s16, 0xfff7c080
	s_addc_u32 s19, s17, -1
	s_cmp_eq_u32 s53, 28
	s_cselect_b32 s21, s3, s19
	s_cselect_b32 s20, s2, s18
	s_cselect_b32 s19, s15, s52
	s_cselect_b32 s18, s14, s51
	v_lshl_add_u64 v[144:145], s[16:17], 0, v[136:137]
	s_add_i32 m0, s36, 0xc000
	ds_read_b128 v[190:193], v152
	ds_read_b128 v[194:197], v152 offset:1024
	ds_read_b128 v[198:201], v152 offset:2048
	ds_read_b128 v[202:205], v152 offset:3072
	ds_read_b128 v[206:209], v152 offset:4096
	ds_read_b128 v[210:213], v152 offset:5120
	ds_read_b128 v[214:217], v152 offset:6144
	ds_read_b128 v[218:221], v152 offset:7168
	global_load_lds_dwordx4 v[144:145], off
	v_lshl_add_u64 v[144:145], s[16:17], 0, v[138:139]
	s_add_i32 m0, s36, 0xe000
	s_nop 0
	global_load_lds_dwordx4 v[144:145], off
	s_waitcnt vmcnt(8)
	s_waitcnt lgkmcnt(0)
	s_barrier
	s_setprio 1
	s_waitcnt lgkmcnt(0)
	v_mfma_f32_16x16x32_bf16 v[124:127], v[154:157], v[190:193], 0
	v_mfma_f32_16x16x32_bf16 v[120:123], v[162:165], v[190:193], 0
	v_mfma_f32_16x16x32_bf16 v[108:111], v[154:157], v[198:201], 0
	v_mfma_f32_16x16x32_bf16 v[104:107], v[162:165], v[198:201], 0
	v_mfma_f32_16x16x32_bf16 v[92:95], v[154:157], v[206:209], 0
	v_mfma_f32_16x16x32_bf16 v[88:91], v[162:165], v[206:209], 0
	v_mfma_f32_16x16x32_bf16 v[76:79], v[154:157], v[214:217], 0
	v_mfma_f32_16x16x32_bf16 v[72:75], v[162:165], v[214:217], 0
	v_mfma_f32_16x16x32_bf16 v[124:127], v[158:161], v[194:197], v[124:127]
	v_mfma_f32_16x16x32_bf16 v[120:123], v[170:173], v[194:197], v[120:123]
	v_mfma_f32_16x16x32_bf16 v[108:111], v[158:161], v[202:205], v[108:111]
	v_mfma_f32_16x16x32_bf16 v[104:107], v[170:173], v[202:205], v[104:107]
	v_mfma_f32_16x16x32_bf16 v[92:95], v[158:161], v[210:213], v[92:95]
	v_mfma_f32_16x16x32_bf16 v[88:91], v[170:173], v[210:213], v[88:91]
	v_mfma_f32_16x16x32_bf16 v[76:79], v[158:161], v[218:221], v[76:79]
	v_mfma_f32_16x16x32_bf16 v[72:75], v[170:173], v[218:221], v[72:75]
	s_setprio 0
	s_setprio 1
	v_mfma_f32_16x16x32_bf16 v[116:119], v[174:177], v[190:193], 0
	v_mfma_f32_16x16x32_bf16 v[112:115], v[182:185], v[190:193], 0
	v_mfma_f32_16x16x32_bf16 v[100:103], v[174:177], v[198:201], 0
	v_mfma_f32_16x16x32_bf16 v[96:99], v[182:185], v[198:201], 0
	v_mfma_f32_16x16x32_bf16 v[84:87], v[174:177], v[206:209], 0
	v_mfma_f32_16x16x32_bf16 v[80:83], v[182:185], v[206:209], 0
	v_mfma_f32_16x16x32_bf16 v[68:71], v[174:177], v[214:217], 0
	v_mfma_f32_16x16x32_bf16 v[64:67], v[182:185], v[214:217], 0
	v_mfma_f32_16x16x32_bf16 v[116:119], v[178:181], v[194:197], v[116:119]
	v_mfma_f32_16x16x32_bf16 v[112:115], v[186:189], v[194:197], v[112:115]
	v_mfma_f32_16x16x32_bf16 v[100:103], v[178:181], v[202:205], v[100:103]
	v_mfma_f32_16x16x32_bf16 v[96:99], v[186:189], v[202:205], v[96:99]
	v_mfma_f32_16x16x32_bf16 v[84:87], v[178:181], v[210:213], v[84:87]
	v_mfma_f32_16x16x32_bf16 v[80:83], v[186:189], v[210:213], v[80:83]
	v_mfma_f32_16x16x32_bf16 v[68:71], v[178:181], v[218:221], v[68:71]
	v_mfma_f32_16x16x32_bf16 v[64:67], v[186:189], v[218:221], v[64:67]
	s_setprio 0
	s_barrier
	s_add_i32 s54, s44, s27
	v_lshl_add_u64 v[144:145], s[18:19], 0, v[132:133]
	s_mov_b32 m0, s54
	ds_read_b128 v[190:193], v152 offset:16384
	ds_read_b128 v[194:197], v152 offset:17408
	ds_read_b128 v[198:201], v152 offset:18432
	ds_read_b128 v[202:205], v152 offset:19456
	ds_read_b128 v[206:209], v152 offset:20480
	ds_read_b128 v[210:213], v152 offset:21504
	ds_read_b128 v[214:217], v152 offset:22528
	ds_read_b128 v[218:221], v152 offset:23552
	global_load_lds_dwordx4 v[144:145], off
	s_add_i32 m0, s54, 0x2000
	s_add_u32 s54, s18, 0x84000
	v_lshl_add_u64 v[166:167], s[18:19], 0, v[128:129]
	s_addc_u32 s55, s19, 0
	s_add_i32 s56, s45, s27
	global_load_lds_dwordx4 v[166:167], off
	v_lshl_add_u64 v[222:223], s[54:55], 0, v[132:133]
	s_mov_b32 m0, s56
	v_lshl_add_u64 v[224:225], s[20:21], 0, v[130:131]
	global_load_lds_dwordx4 v[222:223], off
	v_lshl_add_u64 v[222:223], s[54:55], 0, v[128:129]
	s_add_i32 m0, s56, 0x2000
	s_nop 0
	global_load_lds_dwordx4 v[222:223], off
	v_lshl_add_u64 v[222:223], s[20:21], 0, v[134:135]
	s_mov_b32 m0, s36
	s_nop 0
	global_load_lds_dwordx4 v[222:223], off
	s_mov_b32 m0, s37
	s_nop 0
	global_load_lds_dwordx4 v[224:225], off
	s_waitcnt vmcnt(8)
	s_waitcnt lgkmcnt(0)
	s_barrier
; #define PG8_STAGE(bufoff, gbase, voff) do { _Pragma("unroll") for (int _i = 0; _i < 2; ++_i) \
;         __builtin_amdgcn_global_load_lds((const unsigned*)((const char*)(gbase) + (voff)[_i]), (LAS unsigned*)(lds + (bufoff) + ldsw + _i * 8192), 16, 0, 0); } while (0)
; #define PG8_LDA(dst, b, h) do { _Pragma("unroll") for (int m = 0; m < 4; ++m) _Pragma("unroll") for (int k = 0; k < 2; ++k) dst[m][k] = *(const LAS bf16x8*)(lds + PG8_SA(b, h) + aoff + m * 2048 + k * 1024); } while (0)
; #define PG8_LDB(dst, b, h) do { _Pragma("unroll") for (int n = 0; n < 2; ++n) _Pragma("unroll") for (int k = 0; k < 2; ++k) dst[n][k] = *(const LAS bf16x8*)(lds + PG8_SB(b, h) + boff + n * 2048 + k * 1024); } while (0)
; #define PG8_MMA(ai, bj, At, Bt) do { __builtin_amdgcn_s_setprio(1); _Pragma("unroll") for (int m = 0; m < 4; ++m) _Pragma("unroll") for (int n = 0; n < 2; ++n) _Pragma("unroll") for (int k = 0; k < 2; ++k) \
;         acc[ai][bj][m][n] = __builtin_amdgcn_mfma_f32_16x16x32_bf16(Bt[n][k], At[m][k], acc[ai][bj][m][n], 0, 0, 0); __builtin_amdgcn_s_setprio(0); } while (0)
; #define PG8_WAIT_V(n) asm volatile("s_waitcnt vmcnt(" #n ")" ::: "memory")
; #define PG8_WAIT_L(n) asm volatile("s_waitcnt lgkmcnt(" #n ")" ::: "memory")
; #define PG8_BAR __builtin_amdgcn_s_barrier()
; #define PG8_SCHED __builtin_amdgcn_sched_barrier(0)
; template <class EpiT>
; __device__ __forceinline__ void gemm_phase(LAS unsigned char* lds, const Gemm g, const StaticOrder& S, const EpiT& E) {
;     ...
;             PG8_WAIT_V(8); PG8_WAIT_L(0); PG8_BAR; PG8_MMA(1, 0, At, B0); PG8_MMA(1, 1, At, B1); PG8_BAR; PG8_SCHED;
;             PG8_LDB(B0, 1, 0); PG8_LDB(B1, 1, 1); PG8_SCHED; PG8_LDA(At, 1, 0); PG8_STAGE(PG8_SA(0, 1), a2 + hstepA, voffA);
;             PG8_WAIT_V(8); PG8_WAIT_L(0); PG8_BAR; PG8_MMA(0, 0, At, B0); PG8_MMA(0, 1, At, B1); PG8_BAR; PG8_SCHED;
	s_setprio 1
	s_waitcnt lgkmcnt(0)
	v_mfma_f32_16x16x32_bf16 v[60:63], v[154:157], v[190:193], 0
	v_mfma_f32_16x16x32_bf16 v[56:59], v[162:165], v[190:193], 0
	v_mfma_f32_16x16x32_bf16 v[44:47], v[154:157], v[198:201], 0
	v_mfma_f32_16x16x32_bf16 v[40:43], v[162:165], v[198:201], 0
	v_mfma_f32_16x16x32_bf16 v[28:31], v[154:157], v[206:209], 0
	v_mfma_f32_16x16x32_bf16 v[24:27], v[162:165], v[206:209], 0
	v_mfma_f32_16x16x32_bf16 v[12:15], v[154:157], v[214:217], 0
	v_mfma_f32_16x16x32_bf16 v[8:11], v[162:165], v[214:217], 0
	v_mfma_f32_16x16x32_bf16 v[60:63], v[158:161], v[194:197], v[60:63]
	v_mfma_f32_16x16x32_bf16 v[56:59], v[170:173], v[194:197], v[56:59]
	v_mfma_f32_16x16x32_bf16 v[44:47], v[158:161], v[202:205], v[44:47]
	v_mfma_f32_16x16x32_bf16 v[40:43], v[170:173], v[202:205], v[40:43]
	v_mfma_f32_16x16x32_bf16 v[28:31], v[158:161], v[210:213], v[28:31]
	v_mfma_f32_16x16x32_bf16 v[24:27], v[170:173], v[210:213], v[24:27]
	v_mfma_f32_16x16x32_bf16 v[12:15], v[158:161], v[218:221], v[12:15]
	v_mfma_f32_16x16x32_bf16 v[8:11], v[170:173], v[218:221], v[8:11]
	s_setprio 0
	s_setprio 1
	v_mfma_f32_16x16x32_bf16 v[52:55], v[174:177], v[190:193], 0
	v_mfma_f32_16x16x32_bf16 v[48:51], v[182:185], v[190:193], 0
	v_mfma_f32_16x16x32_bf16 v[36:39], v[174:177], v[198:201], 0
	v_mfma_f32_16x16x32_bf16 v[32:35], v[182:185], v[198:201], 0
	v_mfma_f32_16x16x32_bf16 v[20:23], v[174:177], v[206:209], 0
	v_mfma_f32_16x16x32_bf16 v[16:19], v[182:185], v[206:209], 0
	v_mfma_f32_16x16x32_bf16 v[4:7], v[174:177], v[214:217], 0
	v_mfma_f32_16x16x32_bf16 v[0:3], v[182:185], v[214:217], 0
	v_mfma_f32_16x16x32_bf16 v[52:55], v[178:181], v[194:197], v[52:55]
	v_mfma_f32_16x16x32_bf16 v[48:51], v[186:189], v[194:197], v[48:51]
	v_mfma_f32_16x16x32_bf16 v[36:39], v[178:181], v[202:205], v[36:39]
	v_mfma_f32_16x16x32_bf16 v[32:35], v[186:189], v[202:205], v[32:35]
	v_mfma_f32_16x16x32_bf16 v[20:23], v[178:181], v[210:213], v[20:23]
	v_mfma_f32_16x16x32_bf16 v[16:19], v[186:189], v[210:213], v[16:19]
	v_mfma_f32_16x16x32_bf16 v[4:7], v[178:181], v[218:221], v[4:7]
	v_mfma_f32_16x16x32_bf16 v[0:3], v[186:189], v[218:221], v[0:3]
	s_setprio 0
	s_barrier
	s_add_i32 s54, 0, 0x18000
	v_add_u32_e32 v153, s54, v147
	s_add_i32 s55, 0, 0x1c000
	ds_read_b128 v[154:157], v153
	ds_read_b128 v[158:161], v153 offset:1024
	ds_read_b128 v[162:165], v153 offset:2048
	ds_read_b128 v[170:173], v153 offset:3072
	v_add_u32_e32 v153, s55, v147
	ds_read_b128 v[174:177], v153
	ds_read_b128 v[178:181], v153 offset:1024
	ds_read_b128 v[182:185], v153 offset:2048
	ds_read_b128 v[186:189], v153 offset:3072
	s_add_u32 s20, s20, 0x84000
	s_addc_u32 s21, s21, 0
	s_mov_b32 m0, s38
	v_lshl_add_u64 v[226:227], s[20:21], 0, v[134:135]
	ds_read_b128 v[190:193], v152 offset:32768
	ds_read_b128 v[194:197], v152 offset:33792
	ds_read_b128 v[198:201], v152 offset:34816
	ds_read_b128 v[202:205], v152 offset:35840
	ds_read_b128 v[206:209], v152 offset:36864
	ds_read_b128 v[210:213], v152 offset:37888
	ds_read_b128 v[214:217], v152 offset:38912
	ds_read_b128 v[218:221], v152 offset:39936
	global_load_lds_dwordx4 v[226:227], off
	v_lshl_add_u64 v[226:227], s[20:21], 0, v[130:131]
	s_mov_b32 m0, s39
	s_nop 0
	global_load_lds_dwordx4 v[226:227], off
	s_waitcnt vmcnt(8)
	s_waitcnt lgkmcnt(0)
	s_barrier
	s_setprio 1
	s_waitcnt lgkmcnt(0)
	v_mfma_f32_16x16x32_bf16 v[124:127], v[154:157], v[190:193], v[124:127]
	v_mfma_f32_16x16x32_bf16 v[120:123], v[162:165], v[190:193], v[120:123]
	v_mfma_f32_16x16x32_bf16 v[108:111], v[154:157], v[198:201], v[108:111]
	v_mfma_f32_16x16x32_bf16 v[104:107], v[162:165], v[198:201], v[104:107]
	v_mfma_f32_16x16x32_bf16 v[92:95], v[154:157], v[206:209], v[92:95]
	v_mfma_f32_16x16x32_bf16 v[88:91], v[162:165], v[206:209], v[88:91]
	v_mfma_f32_16x16x32_bf16 v[76:79], v[154:157], v[214:217], v[76:79]
	v_mfma_f32_16x16x32_bf16 v[72:75], v[162:165], v[214:217], v[72:75]
	v_mfma_f32_16x16x32_bf16 v[124:127], v[158:161], v[194:197], v[124:127]
	v_mfma_f32_16x16x32_bf16 v[120:123], v[170:173], v[194:197], v[120:123]
	v_mfma_f32_16x16x32_bf16 v[108:111], v[158:161], v[202:205], v[108:111]
	v_mfma_f32_16x16x32_bf16 v[104:107], v[170:173], v[202:205], v[104:107]
	v_mfma_f32_16x16x32_bf16 v[92:95], v[158:161], v[210:213], v[92:95]
	v_mfma_f32_16x16x32_bf16 v[88:91], v[170:173], v[210:213], v[88:91]
	v_mfma_f32_16x16x32_bf16 v[76:79], v[158:161], v[218:221], v[76:79]
	v_mfma_f32_16x16x32_bf16 v[72:75], v[170:173], v[218:221], v[72:75]
	s_setprio 0
	s_setprio 1
	v_mfma_f32_16x16x32_bf16 v[116:119], v[174:177], v[190:193], v[116:119]
	v_mfma_f32_16x16x32_bf16 v[112:115], v[182:185], v[190:193], v[112:115]
	v_mfma_f32_16x16x32_bf16 v[100:103], v[174:177], v[198:201], v[100:103]
	v_mfma_f32_16x16x32_bf16 v[96:99], v[182:185], v[198:201], v[96:99]
	v_mfma_f32_16x16x32_bf16 v[84:87], v[174:177], v[206:209], v[84:87]
	v_mfma_f32_16x16x32_bf16 v[80:83], v[182:185], v[206:209], v[80:83]
	v_mfma_f32_16x16x32_bf16 v[68:71], v[174:177], v[214:217], v[68:71]
	v_mfma_f32_16x16x32_bf16 v[64:67], v[182:185], v[214:217], v[64:67]
	v_mfma_f32_16x16x32_bf16 v[116:119], v[178:181], v[194:197], v[116:119]
	v_mfma_f32_16x16x32_bf16 v[112:115], v[186:189], v[194:197], v[112:115]
	v_mfma_f32_16x16x32_bf16 v[100:103], v[178:181], v[202:205], v[100:103]
	v_mfma_f32_16x16x32_bf16 v[96:99], v[186:189], v[202:205], v[96:99]
	v_mfma_f32_16x16x32_bf16 v[84:87], v[178:181], v[210:213], v[84:87]
	v_mfma_f32_16x16x32_bf16 v[80:83], v[186:189], v[210:213], v[80:83]
	v_mfma_f32_16x16x32_bf16 v[68:71], v[178:181], v[218:221], v[68:71]
	v_mfma_f32_16x16x32_bf16 v[64:67], v[186:189], v[218:221], v[64:67]
	s_setprio 0
	s_barrier
; #define PG8_STAGE(bufoff, gbase, voff) do { _Pragma("unroll") for (int _i = 0; _i < 2; ++_i) \
;         __builtin_amdgcn_global_load_lds((const unsigned*)((const char*)(gbase) + (voff)[_i]), (LAS unsigned*)(lds + (bufoff) + ldsw + _i * 8192), 16, 0, 0); } while (0)
; #define PG8_LDA(dst, b, h) do { _Pragma("unroll") for (int m = 0; m < 4; ++m) _Pragma("unroll") for (int k = 0; k < 2; ++k) dst[m][k] = *(const LAS bf16x8*)(lds + PG8_SA(b, h) + aoff + m * 2048 + k * 1024); } while (0)
; #define PG8_MMA(ai, bj, At, Bt) do { __builtin_amdgcn_s_setprio(1); _Pragma("unroll") for (int m = 0; m < 4; ++m) _Pragma("unroll") for (int n = 0; n < 2; ++n) _Pragma("unroll") for (int k = 0; k < 2; ++k) \
;         acc[ai][bj][m][n] = __builtin_amdgcn_mfma_f32_16x16x32_bf16(Bt[n][k], At[m][k], acc[ai][bj][m][n], 0, 0, 0); __builtin_amdgcn_s_setprio(0); } while (0)
; #define PG8_WAIT_V(n) asm volatile("s_waitcnt vmcnt(" #n ")" ::: "memory")
; #define PG8_WAIT_L(n) asm volatile("s_waitcnt lgkmcnt(" #n ")" ::: "memory")
; #define PG8_BAR __builtin_amdgcn_s_barrier()
; #define PG8_SCHED __builtin_amdgcn_sched_barrier(0)
; template <class EpiT>
; __device__ __forceinline__ void gemm_phase(LAS unsigned char* lds, const Gemm g, const StaticOrder& S, const EpiT& E) {
;     ...
;         for (int t = 0; t < nt; t += 2) {
;             const bool last = (t == nt - 2);
;     ...
;             PG8_LDA(At, 1, 1); PG8_STAGE(PG8_SB(1, 0), b3, voffB); PG8_STAGE(PG8_SB(1, 1), b3 + hstepB, voffB); PG8_STAGE(PG8_SA(1, 0), a3, voffA);
;             PG8_WAIT_V(8); PG8_WAIT_L(0); PG8_BAR; PG8_MMA(1, 0, At, B0); PG8_MMA(1, 1, At, B1); PG8_BAR; PG8_SCHED;
	s_add_i32 s20, s54, s27
	v_lshl_add_u64 v[144:145], v[144:145], 0, s[10:11]
	s_mov_b32 m0, s20
	ds_read_b128 v[190:193], v152 offset:49152
	ds_read_b128 v[194:197], v152 offset:50176
	ds_read_b128 v[198:201], v152 offset:51200
	ds_read_b128 v[202:205], v152 offset:52224
	ds_read_b128 v[206:209], v152 offset:53248
	ds_read_b128 v[210:213], v152 offset:54272
	ds_read_b128 v[214:217], v152 offset:55296
	ds_read_b128 v[218:221], v152 offset:56320
	global_load_lds_dwordx4 v[144:145], off
	s_add_i32 m0, s20, 0x2000
	s_add_u32 s18, s18, 0x84080
	v_lshl_add_u64 v[144:145], v[166:167], 0, s[10:11]
	s_addc_u32 s19, s19, 0
	s_add_i32 s20, s55, s27
	global_load_lds_dwordx4 v[144:145], off
	v_lshl_add_u64 v[144:145], s[18:19], 0, v[132:133]
	s_mov_b32 m0, s20
	s_nop 0
	global_load_lds_dwordx4 v[144:145], off
	v_lshl_add_u64 v[144:145], s[18:19], 0, v[128:129]
	s_add_i32 m0, s20, 0x2000
	s_nop 0
	global_load_lds_dwordx4 v[144:145], off
	v_lshl_add_u64 v[144:145], v[222:223], 0, s[10:11]
	s_mov_b32 m0, s41
	s_nop 0
	global_load_lds_dwordx4 v[144:145], off
	v_lshl_add_u64 v[144:145], v[224:225], 0, s[10:11]
	s_mov_b32 m0, s42
	s_nop 0
	global_load_lds_dwordx4 v[144:145], off
	s_waitcnt vmcnt(8)
	s_waitcnt lgkmcnt(0)
	s_barrier
	s_setprio 1
	s_waitcnt lgkmcnt(0)
	v_mfma_f32_16x16x32_bf16 v[60:63], v[154:157], v[190:193], v[60:63]
	v_mfma_f32_16x16x32_bf16 v[56:59], v[162:165], v[190:193], v[56:59]
	v_mfma_f32_16x16x32_bf16 v[44:47], v[154:157], v[198:201], v[44:47]
	v_mfma_f32_16x16x32_bf16 v[40:43], v[162:165], v[198:201], v[40:43]
	v_mfma_f32_16x16x32_bf16 v[28:31], v[154:157], v[206:209], v[28:31]
	v_mfma_f32_16x16x32_bf16 v[24:27], v[162:165], v[206:209], v[24:27]
	v_mfma_f32_16x16x32_bf16 v[12:15], v[154:157], v[214:217], v[12:15]
	v_mfma_f32_16x16x32_bf16 v[8:11], v[162:165], v[214:217], v[8:11]
	v_mfma_f32_16x16x32_bf16 v[60:63], v[158:161], v[194:197], v[60:63]
	v_mfma_f32_16x16x32_bf16 v[56:59], v[170:173], v[194:197], v[56:59]
	v_mfma_f32_16x16x32_bf16 v[44:47], v[158:161], v[202:205], v[44:47]
	v_mfma_f32_16x16x32_bf16 v[40:43], v[170:173], v[202:205], v[40:43]
	v_mfma_f32_16x16x32_bf16 v[28:31], v[158:161], v[210:213], v[28:31]
	v_mfma_f32_16x16x32_bf16 v[24:27], v[170:173], v[210:213], v[24:27]
	v_mfma_f32_16x16x32_bf16 v[12:15], v[158:161], v[218:221], v[12:15]
	v_mfma_f32_16x16x32_bf16 v[8:11], v[170:173], v[218:221], v[8:11]
	s_setprio 0
	s_setprio 1
	v_mfma_f32_16x16x32_bf16 v[52:55], v[174:177], v[190:193], v[52:55]
	v_mfma_f32_16x16x32_bf16 v[48:51], v[182:185], v[190:193], v[48:51]
	v_mfma_f32_16x16x32_bf16 v[36:39], v[174:177], v[198:201], v[36:39]
	v_mfma_f32_16x16x32_bf16 v[32:35], v[182:185], v[198:201], v[32:35]
	v_mfma_f32_16x16x32_bf16 v[20:23], v[174:177], v[206:209], v[20:23]
	v_mfma_f32_16x16x32_bf16 v[16:19], v[182:185], v[206:209], v[16:19]
	v_mfma_f32_16x16x32_bf16 v[4:7], v[174:177], v[214:217], v[4:7]
	v_mfma_f32_16x16x32_bf16 v[0:3], v[182:185], v[214:217], v[0:3]
	v_mfma_f32_16x16x32_bf16 v[52:55], v[178:181], v[194:197], v[52:55]
	v_mfma_f32_16x16x32_bf16 v[48:51], v[186:189], v[194:197], v[48:51]
	v_mfma_f32_16x16x32_bf16 v[36:39], v[178:181], v[202:205], v[36:39]
	v_mfma_f32_16x16x32_bf16 v[32:35], v[186:189], v[202:205], v[32:35]
	v_mfma_f32_16x16x32_bf16 v[20:23], v[178:181], v[210:213], v[20:23]
	v_mfma_f32_16x16x32_bf16 v[16:19], v[186:189], v[210:213], v[16:19]
	v_mfma_f32_16x16x32_bf16 v[4:7], v[178:181], v[218:221], v[4:7]
	v_mfma_f32_16x16x32_bf16 v[0:3], v[186:189], v[218:221], v[0:3]
	s_setprio 0
	s_barrier
	s_add_i32 s53, s53, 2
	s_add_u32 s16, s16, 0x100
	s_addc_u32 s17, s17, 0
	s_add_u32 s51, s51, 0x100
	s_addc_u32 s52, s52, 0
	s_cmp_gt_u32 s53, 29
	s_cbranch_scc1 .Lpeel_done_1156
	.p2alignl 6, 3212836864
	s_nop 0
	s_nop 0
	s_nop 0

; #define PG8_STAGE(bufoff, gbase, voff) do { _Pragma("unroll") for (int _i = 0; _i < 2; ++_i) \
;         __builtin_amdgcn_global_load_lds((const unsigned*)((const char*)(gbase) + (voff)[_i]), (LAS unsigned*)(lds + (bufoff) + ldsw + _i * 8192), 16, 0, 0); } while (0)
; #define PG8_LDA(dst, b, h) do { _Pragma("unroll") for (int m = 0; m < 4; ++m) _Pragma("unroll") for (int k = 0; k < 2; ++k) dst[m][k] = *(const LAS bf16x8*)(lds + PG8_SA(b, h) + aoff + m * 2048 + k * 1024); } while (0)
; #define PG8_LDB(dst, b, h) do { _Pragma("unroll") for (int n = 0; n < 2; ++n) _Pragma("unroll") for (int k = 0; k < 2; ++k) dst[n][k] = *(const LAS bf16x8*)(lds + PG8_SB(b, h) + boff + n * 2048 + k * 1024); } while (0)
; #define PG8_WAIT_V(n) asm volatile("s_waitcnt vmcnt(" #n ")" ::: "memory")
; #define PG8_WAIT_L(n) asm volatile("s_waitcnt lgkmcnt(" #n ")" ::: "memory")
; template <class EpiT>
; __device__ __forceinline__ void gemm_phase(LAS unsigned char* lds, const Gemm g, const StaticOrder& S, const EpiT& E) {
;     ...
;         const char* nA = has_next ? (const char*)g.A + (size_t)nxt.pm * tstepA + (size_t)nxt.pn * g.a_koff * 2 : cA; const char* nB = has_next ? (const char*)g.Bt + (size_t)nxt.pn * tstepB : cB;
;         for (int t = 0; t < nt; t += 2) {
;             const bool last = (t == nt - 2);
;             const char* a1 = cA + (size_t)(t + 1) * kstep;
;             const char* a2 = last ? nA : cA + (size_t)(t + 2) * kstep; const char* b2 = last ? nB : cB + (size_t)(t + 2) * kstep;
;             const char* a3 = a2 + kstep; const char* b3 = b2 + kstep;
;             PG8_LDB(B0, 0, 0); PG8_LDB(B1, 0, 1); PG8_SCHED; PG8_LDA(At, 0, 0); PG8_STAGE(PG8_SA(1, 1), a1 + hstepA, voffA);
;             PG8_WAIT_V(8); PG8_WAIT_L(0); PG8_BAR; PG8_MMA(0, 0, At, B0); PG8_MMA(0, 1, At, B1); PG8_BAR; PG8_SCHED;
;             PG8_LDA(At, 0, 1); PG8_STAGE(PG8_SB(0, 0), b2, voffB); PG8_STAGE(PG8_SB(0, 1), b2 + hstepB, voffB); PG8_STAGE(PG8_SA(0, 0), a2, voffA);
;             PG8_WAIT_V(8); PG8_WAIT_L(0); PG8_BAR; PG8_MMA(1, 0, At, B0); PG8_MMA(1, 1, At, B1); PG8_BAR; PG8_SCHED;
;     ...
; #pragma unroll
;         for (int a = 0; a < 2; ++a)
; #pragma unroll
;             for (int b = 0; b < 2; ++b)
; #pragma unroll
;                 for (int m = 0; m < 4; ++m)
; #pragma unroll
;                     for (int n = 0; n < 2; ++n) acc[a][b][m][n] = (f32x4){0.f, 0.f, 0.f, 0.f};
.LBB0_1234:
	s_add_u32 s18, s18, 0x164080
	s_addc_u32 s19, s19, 0
	s_add_u32 s53, s20, 0x100
	s_addc_u32 s54, s21, 0
	s_mov_b32 s55, -2
	ds_read_b128 v[154:157], v150
	ds_read_b128 v[158:161], v150 offset:1024
	ds_read_b128 v[162:165], v150 offset:2048
	ds_read_b128 v[170:173], v150 offset:3072
	ds_read_b128 v[174:177], v151
	ds_read_b128 v[178:181], v151 offset:1024
	ds_read_b128 v[182:185], v151 offset:2048
	ds_read_b128 v[186:189], v151 offset:3072
	s_add_u32 s20, s18, 0xffe9c080
	s_addc_u32 s21, s19, -1
	s_cmpk_eq_i32 s55, 0x54
	s_cselect_b32 s23, s5, s21
	s_cselect_b32 s22, s4, s20
	s_cselect_b32 s21, s17, s54
	s_cselect_b32 s20, s16, s53
	v_lshl_add_u64 v[166:167], s[18:19], 0, v[138:139]
	s_add_i32 m0, s37, 0xc000
	ds_read_b128 v[190:193], v152
	ds_read_b128 v[194:197], v152 offset:1024
	ds_read_b128 v[198:201], v152 offset:2048
	ds_read_b128 v[202:205], v152 offset:3072
	ds_read_b128 v[206:209], v152 offset:4096
	ds_read_b128 v[210:213], v152 offset:5120
	ds_read_b128 v[214:217], v152 offset:6144
	ds_read_b128 v[218:221], v152 offset:7168
	global_load_lds_dwordx4 v[166:167], off
	v_lshl_add_u64 v[166:167], s[18:19], 0, v[140:141]
	s_add_i32 m0, s37, 0xe000
	s_nop 0
	global_load_lds_dwordx4 v[166:167], off
	s_waitcnt vmcnt(8)
	s_waitcnt lgkmcnt(0)
	s_barrier
	s_setprio 1
	s_waitcnt lgkmcnt(0)
	v_mfma_f32_16x16x32_bf16 v[124:127], v[154:157], v[190:193], 0
	v_mfma_f32_16x16x32_bf16 v[120:123], v[162:165], v[190:193], 0
	v_mfma_f32_16x16x32_bf16 v[108:111], v[154:157], v[198:201], 0
	v_mfma_f32_16x16x32_bf16 v[104:107], v[162:165], v[198:201], 0
	v_mfma_f32_16x16x32_bf16 v[92:95], v[154:157], v[206:209], 0
	v_mfma_f32_16x16x32_bf16 v[88:91], v[162:165], v[206:209], 0
	v_mfma_f32_16x16x32_bf16 v[76:79], v[154:157], v[214:217], 0
	v_mfma_f32_16x16x32_bf16 v[72:75], v[162:165], v[214:217], 0
	v_mfma_f32_16x16x32_bf16 v[124:127], v[158:161], v[194:197], v[124:127]
	v_mfma_f32_16x16x32_bf16 v[120:123], v[170:173], v[194:197], v[120:123]
	v_mfma_f32_16x16x32_bf16 v[108:111], v[158:161], v[202:205], v[108:111]
	v_mfma_f32_16x16x32_bf16 v[104:107], v[170:173], v[202:205], v[104:107]
	v_mfma_f32_16x16x32_bf16 v[92:95], v[158:161], v[210:213], v[92:95]
	v_mfma_f32_16x16x32_bf16 v[88:91], v[170:173], v[210:213], v[88:91]
	v_mfma_f32_16x16x32_bf16 v[76:79], v[158:161], v[218:221], v[76:79]
	v_mfma_f32_16x16x32_bf16 v[72:75], v[170:173], v[218:221], v[72:75]
	s_setprio 0
	s_setprio 1
	v_mfma_f32_16x16x32_bf16 v[116:119], v[174:177], v[190:193], 0
	v_mfma_f32_16x16x32_bf16 v[112:115], v[182:185], v[190:193], 0
	v_mfma_f32_16x16x32_bf16 v[100:103], v[174:177], v[198:201], 0
	v_mfma_f32_16x16x32_bf16 v[96:99], v[182:185], v[198:201], 0
	v_mfma_f32_16x16x32_bf16 v[84:87], v[174:177], v[206:209], 0
	v_mfma_f32_16x16x32_bf16 v[80:83], v[182:185], v[206:209], 0
	v_mfma_f32_16x16x32_bf16 v[68:71], v[174:177], v[214:217], 0
	v_mfma_f32_16x16x32_bf16 v[64:67], v[182:185], v[214:217], 0
	v_mfma_f32_16x16x32_bf16 v[116:119], v[178:181], v[194:197], v[116:119]
	v_mfma_f32_16x16x32_bf16 v[112:115], v[186:189], v[194:197], v[112:115]
	v_mfma_f32_16x16x32_bf16 v[100:103], v[178:181], v[202:205], v[100:103]
	v_mfma_f32_16x16x32_bf16 v[96:99], v[186:189], v[202:205], v[96:99]
	v_mfma_f32_16x16x32_bf16 v[84:87], v[178:181], v[210:213], v[84:87]
	v_mfma_f32_16x16x32_bf16 v[80:83], v[186:189], v[210:213], v[80:83]
	v_mfma_f32_16x16x32_bf16 v[68:71], v[178:181], v[218:221], v[68:71]
	v_mfma_f32_16x16x32_bf16 v[64:67], v[186:189], v[218:221], v[64:67]
	s_setprio 0
	s_barrier
	s_add_i32 s56, s46, s36
	v_lshl_add_u64 v[166:167], s[20:21], 0, v[130:131]
	s_mov_b32 m0, s56
	ds_read_b128 v[190:193], v152 offset:16384
	ds_read_b128 v[194:197], v152 offset:17408
	ds_read_b128 v[198:201], v152 offset:18432
	ds_read_b128 v[202:205], v152 offset:19456
	ds_read_b128 v[206:209], v152 offset:20480
	ds_read_b128 v[210:213], v152 offset:21504
	ds_read_b128 v[214:217], v152 offset:22528
	ds_read_b128 v[218:221], v152 offset:23552
	global_load_lds_dwordx4 v[166:167], off
	s_add_i32 m0, s56, 0x2000
	s_add_u32 s56, s20, 0x164000
	v_lshl_add_u64 v[222:223], s[20:21], 0, v[134:135]
	s_addc_u32 s57, s21, 0
	s_add_i32 s58, s47, s36
	global_load_lds_dwordx4 v[222:223], off
	v_lshl_add_u64 v[224:225], s[56:57], 0, v[130:131]
	s_mov_b32 m0, s58
	v_lshl_add_u64 v[226:227], s[22:23], 0, v[132:133]
	global_load_lds_dwordx4 v[224:225], off
	v_lshl_add_u64 v[224:225], s[56:57], 0, v[134:135]
	s_add_i32 m0, s58, 0x2000
	s_nop 0
	global_load_lds_dwordx4 v[224:225], off
	v_lshl_add_u64 v[224:225], s[22:23], 0, v[128:129]
	s_mov_b32 m0, s37
	s_nop 0
	global_load_lds_dwordx4 v[224:225], off
	s_mov_b32 m0, s38
	s_nop 0
	global_load_lds_dwordx4 v[226:227], off
	s_waitcnt vmcnt(8)
	s_waitcnt lgkmcnt(0)
	s_barrier
; #define PG8_STAGE(bufoff, gbase, voff) do { _Pragma("unroll") for (int _i = 0; _i < 2; ++_i) \
;         __builtin_amdgcn_global_load_lds((const unsigned*)((const char*)(gbase) + (voff)[_i]), (LAS unsigned*)(lds + (bufoff) + ldsw + _i * 8192), 16, 0, 0); } while (0)
; #define PG8_LDA(dst, b, h) do { _Pragma("unroll") for (int m = 0; m < 4; ++m) _Pragma("unroll") for (int k = 0; k < 2; ++k) dst[m][k] = *(const LAS bf16x8*)(lds + PG8_SA(b, h) + aoff + m * 2048 + k * 1024); } while (0)
; #define PG8_LDB(dst, b, h) do { _Pragma("unroll") for (int n = 0; n < 2; ++n) _Pragma("unroll") for (int k = 0; k < 2; ++k) dst[n][k] = *(const LAS bf16x8*)(lds + PG8_SB(b, h) + boff + n * 2048 + k * 1024); } while (0)
; #define PG8_MMA(ai, bj, At, Bt) do { __builtin_amdgcn_s_setprio(1); _Pragma("unroll") for (int m = 0; m < 4; ++m) _Pragma("unroll") for (int n = 0; n < 2; ++n) _Pragma("unroll") for (int k = 0; k < 2; ++k) \
;         acc[ai][bj][m][n] = __builtin_amdgcn_mfma_f32_16x16x32_bf16(Bt[n][k], At[m][k], acc[ai][bj][m][n], 0, 0, 0); __builtin_amdgcn_s_setprio(0); } while (0)
; #define PG8_WAIT_V(n) asm volatile("s_waitcnt vmcnt(" #n ")" ::: "memory")
; #define PG8_WAIT_L(n) asm volatile("s_waitcnt lgkmcnt(" #n ")" ::: "memory")
; #define PG8_BAR __builtin_amdgcn_s_barrier()
; #define PG8_SCHED __builtin_amdgcn_sched_barrier(0)
; template <class EpiT>
; __device__ __forceinline__ void gemm_phase(LAS unsigned char* lds, const Gemm g, const StaticOrder& S, const EpiT& E) {
;     ...
;             PG8_WAIT_V(8); PG8_WAIT_L(0); PG8_BAR; PG8_MMA(1, 0, At, B0); PG8_MMA(1, 1, At, B1); PG8_BAR; PG8_SCHED;
;             PG8_LDB(B0, 1, 0); PG8_LDB(B1, 1, 1); PG8_SCHED; PG8_LDA(At, 1, 0); PG8_STAGE(PG8_SA(0, 1), a2 + hstepA, voffA);
;             PG8_WAIT_V(8); PG8_WAIT_L(0); PG8_BAR; PG8_MMA(0, 0, At, B0); PG8_MMA(0, 1, At, B1); PG8_BAR; PG8_SCHED;
	s_setprio 1
	s_waitcnt lgkmcnt(0)
	v_mfma_f32_16x16x32_bf16 v[60:63], v[154:157], v[190:193], 0
	v_mfma_f32_16x16x32_bf16 v[56:59], v[162:165], v[190:193], 0
	v_mfma_f32_16x16x32_bf16 v[44:47], v[154:157], v[198:201], 0
	v_mfma_f32_16x16x32_bf16 v[40:43], v[162:165], v[198:201], 0
	v_mfma_f32_16x16x32_bf16 v[28:31], v[154:157], v[206:209], 0
	v_mfma_f32_16x16x32_bf16 v[24:27], v[162:165], v[206:209], 0
	v_mfma_f32_16x16x32_bf16 v[12:15], v[154:157], v[214:217], 0
	v_mfma_f32_16x16x32_bf16 v[8:11], v[162:165], v[214:217], 0
	v_mfma_f32_16x16x32_bf16 v[60:63], v[158:161], v[194:197], v[60:63]
	v_mfma_f32_16x16x32_bf16 v[56:59], v[170:173], v[194:197], v[56:59]
	v_mfma_f32_16x16x32_bf16 v[44:47], v[158:161], v[202:205], v[44:47]
	v_mfma_f32_16x16x32_bf16 v[40:43], v[170:173], v[202:205], v[40:43]
	v_mfma_f32_16x16x32_bf16 v[28:31], v[158:161], v[210:213], v[28:31]
	v_mfma_f32_16x16x32_bf16 v[24:27], v[170:173], v[210:213], v[24:27]
	v_mfma_f32_16x16x32_bf16 v[12:15], v[158:161], v[218:221], v[12:15]
	v_mfma_f32_16x16x32_bf16 v[8:11], v[170:173], v[218:221], v[8:11]
	s_setprio 0
	s_setprio 1
	v_mfma_f32_16x16x32_bf16 v[52:55], v[174:177], v[190:193], 0
	v_mfma_f32_16x16x32_bf16 v[48:51], v[182:185], v[190:193], 0
	v_mfma_f32_16x16x32_bf16 v[36:39], v[174:177], v[198:201], 0
	v_mfma_f32_16x16x32_bf16 v[32:35], v[182:185], v[198:201], 0
	v_mfma_f32_16x16x32_bf16 v[20:23], v[174:177], v[206:209], 0
	v_mfma_f32_16x16x32_bf16 v[16:19], v[182:185], v[206:209], 0
	v_mfma_f32_16x16x32_bf16 v[4:7], v[174:177], v[214:217], 0
	v_mfma_f32_16x16x32_bf16 v[0:3], v[182:185], v[214:217], 0
	v_mfma_f32_16x16x32_bf16 v[52:55], v[178:181], v[194:197], v[52:55]
	v_mfma_f32_16x16x32_bf16 v[48:51], v[186:189], v[194:197], v[48:51]
	v_mfma_f32_16x16x32_bf16 v[36:39], v[178:181], v[202:205], v[36:39]
	v_mfma_f32_16x16x32_bf16 v[32:35], v[186:189], v[202:205], v[32:35]
	v_mfma_f32_16x16x32_bf16 v[20:23], v[178:181], v[210:213], v[20:23]
	v_mfma_f32_16x16x32_bf16 v[16:19], v[186:189], v[210:213], v[16:19]
	v_mfma_f32_16x16x32_bf16 v[4:7], v[178:181], v[218:221], v[4:7]
	v_mfma_f32_16x16x32_bf16 v[0:3], v[186:189], v[218:221], v[0:3]
	s_setprio 0
	s_barrier
	s_add_i32 s56, 0, 0x18000
	s_add_i32 s57, 0, 0x1c000
	v_add_u32_e32 v170, s56, v146
	v_add_u32_e32 v186, s57, v146
	ds_read_b128 v[154:157], v170
	ds_read_b128 v[158:161], v170 offset:1024
	ds_read_b128 v[162:165], v170 offset:2048
	ds_read_b128 v[170:173], v170 offset:3072
	ds_read_b128 v[174:177], v186
	ds_read_b128 v[178:181], v186 offset:1024
	ds_read_b128 v[182:185], v186 offset:2048
	ds_read_b128 v[186:189], v186 offset:3072
	s_add_u32 s22, s22, 0x164000
	s_addc_u32 s23, s23, 0
	s_mov_b32 m0, s39
	v_lshl_add_u64 v[228:229], s[22:23], 0, v[128:129]
	ds_read_b128 v[190:193], v152 offset:32768
	ds_read_b128 v[194:197], v152 offset:33792
	ds_read_b128 v[198:201], v152 offset:34816
	ds_read_b128 v[202:205], v152 offset:35840
	ds_read_b128 v[206:209], v152 offset:36864
	ds_read_b128 v[210:213], v152 offset:37888
	ds_read_b128 v[214:217], v152 offset:38912
	ds_read_b128 v[218:221], v152 offset:39936
	global_load_lds_dwordx4 v[228:229], off
	v_lshl_add_u64 v[228:229], s[22:23], 0, v[132:133]
	s_mov_b32 m0, s40
	s_nop 0
	global_load_lds_dwordx4 v[228:229], off
	s_waitcnt vmcnt(8)
	s_waitcnt lgkmcnt(0)
	s_barrier
	s_setprio 1
	s_waitcnt lgkmcnt(0)
	v_mfma_f32_16x16x32_bf16 v[124:127], v[154:157], v[190:193], v[124:127]
	v_mfma_f32_16x16x32_bf16 v[120:123], v[162:165], v[190:193], v[120:123]
	v_mfma_f32_16x16x32_bf16 v[108:111], v[154:157], v[198:201], v[108:111]
	v_mfma_f32_16x16x32_bf16 v[104:107], v[162:165], v[198:201], v[104:107]
	v_mfma_f32_16x16x32_bf16 v[92:95], v[154:157], v[206:209], v[92:95]
	v_mfma_f32_16x16x32_bf16 v[88:91], v[162:165], v[206:209], v[88:91]
	v_mfma_f32_16x16x32_bf16 v[76:79], v[154:157], v[214:217], v[76:79]
	v_mfma_f32_16x16x32_bf16 v[72:75], v[162:165], v[214:217], v[72:75]
	v_mfma_f32_16x16x32_bf16 v[124:127], v[158:161], v[194:197], v[124:127]
	v_mfma_f32_16x16x32_bf16 v[120:123], v[170:173], v[194:197], v[120:123]
	v_mfma_f32_16x16x32_bf16 v[108:111], v[158:161], v[202:205], v[108:111]
	v_mfma_f32_16x16x32_bf16 v[104:107], v[170:173], v[202:205], v[104:107]
	v_mfma_f32_16x16x32_bf16 v[92:95], v[158:161], v[210:213], v[92:95]
	v_mfma_f32_16x16x32_bf16 v[88:91], v[170:173], v[210:213], v[88:91]
	v_mfma_f32_16x16x32_bf16 v[76:79], v[158:161], v[218:221], v[76:79]
	v_mfma_f32_16x16x32_bf16 v[72:75], v[170:173], v[218:221], v[72:75]
	s_setprio 0
	s_setprio 1
	v_mfma_f32_16x16x32_bf16 v[116:119], v[174:177], v[190:193], v[116:119]
	v_mfma_f32_16x16x32_bf16 v[112:115], v[182:185], v[190:193], v[112:115]
	v_mfma_f32_16x16x32_bf16 v[100:103], v[174:177], v[198:201], v[100:103]
	v_mfma_f32_16x16x32_bf16 v[96:99], v[182:185], v[198:201], v[96:99]
	v_mfma_f32_16x16x32_bf16 v[84:87], v[174:177], v[206:209], v[84:87]
	v_mfma_f32_16x16x32_bf16 v[80:83], v[182:185], v[206:209], v[80:83]
	v_mfma_f32_16x16x32_bf16 v[68:71], v[174:177], v[214:217], v[68:71]
	v_mfma_f32_16x16x32_bf16 v[64:67], v[182:185], v[214:217], v[64:67]
	v_mfma_f32_16x16x32_bf16 v[116:119], v[178:181], v[194:197], v[116:119]
	v_mfma_f32_16x16x32_bf16 v[112:115], v[186:189], v[194:197], v[112:115]
	v_mfma_f32_16x16x32_bf16 v[100:103], v[178:181], v[202:205], v[100:103]
	v_mfma_f32_16x16x32_bf16 v[96:99], v[186:189], v[202:205], v[96:99]
	v_mfma_f32_16x16x32_bf16 v[84:87], v[178:181], v[210:213], v[84:87]
	v_mfma_f32_16x16x32_bf16 v[80:83], v[186:189], v[210:213], v[80:83]
	v_mfma_f32_16x16x32_bf16 v[68:71], v[178:181], v[218:221], v[68:71]
	v_mfma_f32_16x16x32_bf16 v[64:67], v[186:189], v[218:221], v[64:67]
	s_setprio 0
	s_barrier
; #define PG8_STAGE(bufoff, gbase, voff) do { _Pragma("unroll") for (int _i = 0; _i < 2; ++_i) \
;         __builtin_amdgcn_global_load_lds((const unsigned*)((const char*)(gbase) + (voff)[_i]), (LAS unsigned*)(lds + (bufoff) + ldsw + _i * 8192), 16, 0, 0); } while (0)
; #define PG8_LDA(dst, b, h) do { _Pragma("unroll") for (int m = 0; m < 4; ++m) _Pragma("unroll") for (int k = 0; k < 2; ++k) dst[m][k] = *(const LAS bf16x8*)(lds + PG8_SA(b, h) + aoff + m * 2048 + k * 1024); } while (0)
; #define PG8_MMA(ai, bj, At, Bt) do { __builtin_amdgcn_s_setprio(1); _Pragma("unroll") for (int m = 0; m < 4; ++m) _Pragma("unroll") for (int n = 0; n < 2; ++n) _Pragma("unroll") for (int k = 0; k < 2; ++k) \
;         acc[ai][bj][m][n] = __builtin_amdgcn_mfma_f32_16x16x32_bf16(Bt[n][k], At[m][k], acc[ai][bj][m][n], 0, 0, 0); __builtin_amdgcn_s_setprio(0); } while (0)
; #define PG8_WAIT_V(n) asm volatile("s_waitcnt vmcnt(" #n ")" ::: "memory")
; #define PG8_WAIT_L(n) asm volatile("s_waitcnt lgkmcnt(" #n ")" ::: "memory")
; #define PG8_BAR __builtin_amdgcn_s_barrier()
; #define PG8_SCHED __builtin_amdgcn_sched_barrier(0)
; template <class EpiT>
; __device__ __forceinline__ void gemm_phase(LAS unsigned char* lds, const Gemm g, const StaticOrder& S, const EpiT& E) {
;     ...
;         for (int t = 0; t < nt; t += 2) {
;             const bool last = (t == nt - 2);
;     ...
;             PG8_LDA(At, 1, 1); PG8_STAGE(PG8_SB(1, 0), b3, voffB); PG8_STAGE(PG8_SB(1, 1), b3 + hstepB, voffB); PG8_STAGE(PG8_SA(1, 0), a3, voffA);
;             PG8_WAIT_V(8); PG8_WAIT_L(0); PG8_BAR; PG8_MMA(1, 0, At, B0); PG8_MMA(1, 1, At, B1); PG8_BAR; PG8_SCHED;
	s_add_i32 s22, s56, s36
	v_lshl_add_u64 v[166:167], v[166:167], 0, s[12:13]
	s_mov_b32 m0, s22
	ds_read_b128 v[190:193], v152 offset:49152
	ds_read_b128 v[194:197], v152 offset:50176
	ds_read_b128 v[198:201], v152 offset:51200
	ds_read_b128 v[202:205], v152 offset:52224
	ds_read_b128 v[206:209], v152 offset:53248
	ds_read_b128 v[210:213], v152 offset:54272
	ds_read_b128 v[214:217], v152 offset:55296
	ds_read_b128 v[218:221], v152 offset:56320
	global_load_lds_dwordx4 v[166:167], off
	s_add_i32 m0, s22, 0x2000
	s_add_u32 s20, s20, 0x164080
	v_lshl_add_u64 v[166:167], v[222:223], 0, s[12:13]
	s_addc_u32 s21, s21, 0
	s_add_i32 s22, s57, s36
	global_load_lds_dwordx4 v[166:167], off
	v_lshl_add_u64 v[166:167], s[20:21], 0, v[130:131]
	s_mov_b32 m0, s22
	s_nop 0
	global_load_lds_dwordx4 v[166:167], off
	v_lshl_add_u64 v[166:167], s[20:21], 0, v[134:135]
	s_add_i32 m0, s22, 0x2000
	s_nop 0
	global_load_lds_dwordx4 v[166:167], off
	v_lshl_add_u64 v[166:167], v[224:225], 0, s[12:13]
	s_mov_b32 m0, s42
	s_nop 0
	global_load_lds_dwordx4 v[166:167], off
	v_lshl_add_u64 v[166:167], v[226:227], 0, s[12:13]
	s_mov_b32 m0, s43
	s_nop 0
	global_load_lds_dwordx4 v[166:167], off
	s_waitcnt vmcnt(8)
	s_waitcnt lgkmcnt(0)
	s_barrier
	s_setprio 1
	s_waitcnt lgkmcnt(0)
	v_mfma_f32_16x16x32_bf16 v[60:63], v[154:157], v[190:193], v[60:63]
	v_mfma_f32_16x16x32_bf16 v[56:59], v[162:165], v[190:193], v[56:59]
	v_mfma_f32_16x16x32_bf16 v[44:47], v[154:157], v[198:201], v[44:47]
	v_mfma_f32_16x16x32_bf16 v[40:43], v[162:165], v[198:201], v[40:43]
	v_mfma_f32_16x16x32_bf16 v[28:31], v[154:157], v[206:209], v[28:31]
	v_mfma_f32_16x16x32_bf16 v[24:27], v[162:165], v[206:209], v[24:27]
	v_mfma_f32_16x16x32_bf16 v[12:15], v[154:157], v[214:217], v[12:15]
	v_mfma_f32_16x16x32_bf16 v[8:11], v[162:165], v[214:217], v[8:11]
	v_mfma_f32_16x16x32_bf16 v[60:63], v[158:161], v[194:197], v[60:63]
	v_mfma_f32_16x16x32_bf16 v[56:59], v[170:173], v[194:197], v[56:59]
	v_mfma_f32_16x16x32_bf16 v[44:47], v[158:161], v[202:205], v[44:47]
	v_mfma_f32_16x16x32_bf16 v[40:43], v[170:173], v[202:205], v[40:43]
	v_mfma_f32_16x16x32_bf16 v[28:31], v[158:161], v[210:213], v[28:31]
	v_mfma_f32_16x16x32_bf16 v[24:27], v[170:173], v[210:213], v[24:27]
	v_mfma_f32_16x16x32_bf16 v[12:15], v[158:161], v[218:221], v[12:15]
	v_mfma_f32_16x16x32_bf16 v[8:11], v[170:173], v[218:221], v[8:11]
	s_setprio 0
	s_setprio 1
	v_mfma_f32_16x16x32_bf16 v[52:55], v[174:177], v[190:193], v[52:55]
	v_mfma_f32_16x16x32_bf16 v[48:51], v[182:185], v[190:193], v[48:51]
	v_mfma_f32_16x16x32_bf16 v[36:39], v[174:177], v[198:201], v[36:39]
	v_mfma_f32_16x16x32_bf16 v[32:35], v[182:185], v[198:201], v[32:35]
	v_mfma_f32_16x16x32_bf16 v[20:23], v[174:177], v[206:209], v[20:23]
	v_mfma_f32_16x16x32_bf16 v[16:19], v[182:185], v[206:209], v[16:19]
	v_mfma_f32_16x16x32_bf16 v[4:7], v[174:177], v[214:217], v[4:7]
	v_mfma_f32_16x16x32_bf16 v[0:3], v[182:185], v[214:217], v[0:3]
	v_mfma_f32_16x16x32_bf16 v[52:55], v[178:181], v[194:197], v[52:55]
	v_mfma_f32_16x16x32_bf16 v[48:51], v[186:189], v[194:197], v[48:51]
	v_mfma_f32_16x16x32_bf16 v[36:39], v[178:181], v[202:205], v[36:39]
	v_mfma_f32_16x16x32_bf16 v[32:35], v[186:189], v[202:205], v[32:35]
	v_mfma_f32_16x16x32_bf16 v[20:23], v[178:181], v[210:213], v[20:23]
	v_mfma_f32_16x16x32_bf16 v[16:19], v[186:189], v[210:213], v[16:19]
	v_mfma_f32_16x16x32_bf16 v[4:7], v[178:181], v[218:221], v[4:7]
	v_mfma_f32_16x16x32_bf16 v[0:3], v[186:189], v[218:221], v[0:3]
	s_setprio 0
	s_barrier
	s_add_i32 s55, s55, 2
	s_add_u32 s18, s18, 0x100
	s_addc_u32 s19, s19, 0
	s_add_u32 s53, s53, 0x100
	s_addc_u32 s54, s54, 0
	s_cmpk_gt_u32 s55, 0x55
	s_cbranch_scc1 .Lpeel_done_1235
	.p2alignl 6, 3212836864
	s_nop 0
	s_nop 0
	s_nop 0
	s_nop 0
	s_nop 0
	s_nop 0
	s_nop 0
	s_nop 0
	s_nop 0
	s_nop 0
	s_nop 0
	s_nop 0
	s_nop 0
	s_nop 0
